# GEMM K-loops: LDS-DMA loads take SGPR base + 32-bit lane offset (saddr) instead of a VALU 64-bit add per load
# speedup vs baseline: 1.0030x; 1.0030x over previous
; #define PG8_STAGE(bufoff, gbase, voff) do { _Pragma("unroll") for (int _i = 0; _i < 2; ++_i) \
;         __builtin_amdgcn_global_load_lds((const unsigned*)((const char*)(gbase) + (voff)[_i]), (PG8_LAS unsigned*)(lds + (bufoff) + ldsw + _i * 8192), 16, 0, 0); } while (0)
; #define PG8_LDA(dst, b, h) do { _Pragma("unroll") for (int m = 0; m < 4; ++m) _Pragma("unroll") for (int k = 0; k < 2; ++k) dst[m][k] = *(const PG8_LAS bf16x8*)(lds + PG8_SA(b, h) + aoff + m * 2048 + k * 1024); } while (0)
; #define PG8_LDB(dst, b, h) do { _Pragma("unroll") for (int n = 0; n < 2; ++n) _Pragma("unroll") for (int k = 0; k < 2; ++k) dst[n][k] = *(const PG8_LAS bf16x8*)(lds + PG8_SB(b, h) + boff + n * 2048 + k * 1024); } while (0)
; #define PG8_MMA(ai, bj, At, Bt) do { __builtin_amdgcn_s_setprio(1); _Pragma("unroll") for (int m = 0; m < 4; ++m) _Pragma("unroll") for (int n = 0; n < 2; ++n) _Pragma("unroll") for (int k = 0; k < 2; ++k) \
;         acc[ai][bj][m][n] = __builtin_amdgcn_mfma_f32_16x16x32_bf16(Bt[n][k], At[m][k], acc[ai][bj][m][n], 0, 0, 0); __builtin_amdgcn_s_setprio(0); } while (0)
; #define PG8_BAR __builtin_amdgcn_s_barrier()
; template <class Epi, class Sched, bool ALIGN_EPI = false, bool SP2 = false>
; __device__ __forceinline__ void gemm_phase(PG8_LAS unsigned char* lds, const Gemm g, const Sched& S, const Epi& E) {
;     ...
;         const bool has_next = S.next(ui + 1, nxt);
;         const char* nA = has_next ? (const char*)g.A + (size_t)nxt.pm * tstep : cA; const char* nB = has_next ? (const char*)g.Bt + (size_t)nxt.pn * tstep : cB;
;         for (int t = 0; t < nt; t += 2) {
;             const bool last = (t == nt - 2);
;             const char* a1 = cA + (size_t)(t + 1) * kstep;
;             const char* a2 = last ? nA : cA + (size_t)(t + 2) * kstep; const char* b2 = last ? nB : cB + (size_t)(t + 2) * kstep;
;             const char* a3 = a2 + kstep; const char* b3 = b2 + kstep;
;             if (last && has_next) S.a_ready(nxt);
;             if constexpr (SP2) {
;             PG8_LDB(B0, 0, 0); PG8_LDB(B1, 0, 1); PG8_SCHED; PG8_LDA(At, 0, 0); PG8_STAGE(PG8_SA(1, 1), a1 + hstep, voffA);
;             PG8_WAIT_V(8); PG8_WAIT_L(0); PG8_BAR; PG8_MMA(0, 0, At, B0); PG8_MMA(0, 1, At, B1); PG8_BAR; PG8_SCHED;
;             PG8_LDA(At, 0, 1); PG8_STAGE(PG8_SB(0, 0), b2, voffB); PG8_STAGE(PG8_SB(0, 1), b2 + hstep, voffB); PG8_STAGE(PG8_SA(0, 0), a2, voffA);
.LBB0_232:
	s_ashr_i32 s29, s28, 31
	s_lshl_b64 s[30:31], s[28:29], 19
	s_add_u32 s30, s80, s30
	s_addc_u32 s31, s81, s31
	s_and_b64 s[34:35], s[6:7], exec
	s_cselect_b32 s29, s31, s39
	s_cselect_b32 s59, s30, s38
	s_ashr_i32 s27, s26, 31
	s_lshl_b64 s[34:35], s[26:27], 19
	s_add_u32 s34, s10, s34
	s_addc_u32 s35, s11, s35
	s_and_b64 s[44:45], s[6:7], exec
	s_cselect_b32 s27, s35, s41
	s_cselect_b32 s60, s34, s40
	s_add_u32 s38, s38, 0x40080
	s_addc_u32 s39, s39, 0
	s_add_u32 s61, s40, 0x100
	s_addc_u32 s62, s41, 0
	s_mov_b32 s63, -2
	ds_read_b128 v[144:147], v154
	ds_read_b128 v[158:161], v154 offset:1024
	ds_read_b128 v[162:165], v154 offset:2048
	ds_read_b128 v[166:169], v154 offset:3072
	ds_read_b128 v[170:173], v155
	ds_read_b128 v[174:177], v155 offset:1024
	ds_read_b128 v[180:183], v155 offset:2048
	ds_read_b128 v[184:187], v155 offset:3072
	s_add_u32 s40, s38, 0xfffc0080
	s_addc_u32 s41, s39, -1
	s_cmp_eq_u32 s63, 12
	s_cselect_b32 s45, s29, s41
	s_cselect_b32 s44, s59, s40
	s_cselect_b32 s41, s27, s62
	s_cselect_b32 s40, s60, s61
	s_add_i32 m0, s37, 0xc000
	ds_read_b128 v[188:191], v156
	ds_read_b128 v[192:195], v156 offset:1024
	ds_read_b128 v[196:199], v156 offset:2048
	ds_read_b128 v[200:203], v156 offset:3072
	ds_read_b128 v[204:207], v156 offset:4096
	ds_read_b128 v[208:211], v156 offset:5120
	ds_read_b128 v[212:215], v156 offset:6144
	ds_read_b128 v[216:219], v156 offset:7168
	global_load_lds_dwordx4 v136, s[38:39]
	s_add_i32 m0, s37, 0xe000
	s_nop 0
	global_load_lds_dwordx4 v138, s[38:39]
	s_waitcnt vmcnt(8)
	s_waitcnt lgkmcnt(0)
	s_barrier
	s_setprio 1
	s_waitcnt lgkmcnt(0)
	v_mfma_f32_16x16x32_bf16 v[124:127], v[144:147], v[188:191], 0
	v_mfma_f32_16x16x32_bf16 v[116:119], v[162:165], v[188:191], 0
	v_mfma_f32_16x16x32_bf16 v[108:111], v[144:147], v[196:199], 0
	v_mfma_f32_16x16x32_bf16 v[100:103], v[162:165], v[196:199], 0
	v_mfma_f32_16x16x32_bf16 v[92:95], v[144:147], v[204:207], 0
	v_mfma_f32_16x16x32_bf16 v[84:87], v[162:165], v[204:207], 0
	v_mfma_f32_16x16x32_bf16 v[76:79], v[144:147], v[212:215], 0
	v_mfma_f32_16x16x32_bf16 v[68:71], v[162:165], v[212:215], 0
	v_mfma_f32_16x16x32_bf16 v[124:127], v[158:161], v[192:195], v[124:127]
	v_mfma_f32_16x16x32_bf16 v[116:119], v[166:169], v[192:195], v[116:119]
	v_mfma_f32_16x16x32_bf16 v[108:111], v[158:161], v[200:203], v[108:111]
	v_mfma_f32_16x16x32_bf16 v[100:103], v[166:169], v[200:203], v[100:103]
	v_mfma_f32_16x16x32_bf16 v[92:95], v[158:161], v[208:211], v[92:95]
	v_mfma_f32_16x16x32_bf16 v[84:87], v[166:169], v[208:211], v[84:87]
	v_mfma_f32_16x16x32_bf16 v[76:79], v[158:161], v[216:219], v[76:79]
	v_mfma_f32_16x16x32_bf16 v[68:71], v[166:169], v[216:219], v[68:71]
	s_setprio 0
	s_setprio 1
	v_mfma_f32_16x16x32_bf16 v[120:123], v[170:173], v[188:191], 0
	v_mfma_f32_16x16x32_bf16 v[112:115], v[180:183], v[188:191], 0
	v_mfma_f32_16x16x32_bf16 v[104:107], v[170:173], v[196:199], 0
	v_mfma_f32_16x16x32_bf16 v[96:99], v[180:183], v[196:199], 0
	v_mfma_f32_16x16x32_bf16 v[88:91], v[170:173], v[204:207], 0
	v_mfma_f32_16x16x32_bf16 v[80:83], v[180:183], v[204:207], 0
	v_mfma_f32_16x16x32_bf16 v[72:75], v[170:173], v[212:215], 0
	v_mfma_f32_16x16x32_bf16 v[64:67], v[180:183], v[212:215], 0
	v_mfma_f32_16x16x32_bf16 v[120:123], v[174:177], v[192:195], v[120:123]
	v_mfma_f32_16x16x32_bf16 v[112:115], v[184:187], v[192:195], v[112:115]
	v_mfma_f32_16x16x32_bf16 v[104:107], v[174:177], v[200:203], v[104:107]
	v_mfma_f32_16x16x32_bf16 v[96:99], v[184:187], v[200:203], v[96:99]
	v_mfma_f32_16x16x32_bf16 v[88:91], v[174:177], v[208:211], v[88:91]
	v_mfma_f32_16x16x32_bf16 v[80:83], v[184:187], v[208:211], v[80:83]
	v_mfma_f32_16x16x32_bf16 v[72:75], v[174:177], v[216:219], v[72:75]
	v_mfma_f32_16x16x32_bf16 v[64:67], v[184:187], v[216:219], v[64:67]
	s_setprio 0
	s_barrier
	s_add_i32 s64, s53, s33
	v_lshl_add_u64 v[148:149], s[40:41], 0, v[130:131]
	s_mov_b32 m0, s64
	ds_read_b128 v[188:191], v156 offset:16384
	ds_read_b128 v[192:195], v156 offset:17408
	ds_read_b128 v[196:199], v156 offset:18432
	ds_read_b128 v[200:203], v156 offset:19456
	ds_read_b128 v[204:207], v156 offset:20480
	ds_read_b128 v[208:211], v156 offset:21504
	ds_read_b128 v[212:215], v156 offset:22528
	ds_read_b128 v[216:219], v156 offset:23552
	global_load_lds_dwordx4 v[148:149], off
	s_add_i32 m0, s64, 0x2000
	s_add_u32 s64, s40, 0x40000
	v_lshl_add_u64 v[220:221], s[40:41], 0, v[134:135]
	s_addc_u32 s65, s41, 0
	s_add_i32 s66, s54, s33
	global_load_lds_dwordx4 v[220:221], off
	s_mov_b32 m0, s66
	v_lshl_add_u64 v[224:225], s[44:45], 0, v[132:133]
	global_load_lds_dwordx4 v130, s[64:65]
	s_add_i32 m0, s66, 0x2000
	s_nop 0
	global_load_lds_dwordx4 v134, s[64:65]
	v_lshl_add_u64 v[222:223], s[44:45], 0, v[128:129]
	s_mov_b32 m0, s37
	s_nop 0
	global_load_lds_dwordx4 v[222:223], off
	s_mov_b32 m0, s46
	s_nop 0
	global_load_lds_dwordx4 v[224:225], off
	s_waitcnt vmcnt(8)
	s_waitcnt lgkmcnt(0)
	s_barrier
; #define PG8_STAGE(bufoff, gbase, voff) do { _Pragma("unroll") for (int _i = 0; _i < 2; ++_i) \
;         __builtin_amdgcn_global_load_lds((const unsigned*)((const char*)(gbase) + (voff)[_i]), (PG8_LAS unsigned*)(lds + (bufoff) + ldsw + _i * 8192), 16, 0, 0); } while (0)
; #define PG8_LDA(dst, b, h) do { _Pragma("unroll") for (int m = 0; m < 4; ++m) _Pragma("unroll") for (int k = 0; k < 2; ++k) dst[m][k] = *(const PG8_LAS bf16x8*)(lds + PG8_SA(b, h) + aoff + m * 2048 + k * 1024); } while (0)
; #define PG8_LDB(dst, b, h) do { _Pragma("unroll") for (int n = 0; n < 2; ++n) _Pragma("unroll") for (int k = 0; k < 2; ++k) dst[n][k] = *(const PG8_LAS bf16x8*)(lds + PG8_SB(b, h) + boff + n * 2048 + k * 1024); } while (0)
; #define PG8_MMA(ai, bj, At, Bt) do { __builtin_amdgcn_s_setprio(1); _Pragma("unroll") for (int m = 0; m < 4; ++m) _Pragma("unroll") for (int n = 0; n < 2; ++n) _Pragma("unroll") for (int k = 0; k < 2; ++k) \
;         acc[ai][bj][m][n] = __builtin_amdgcn_mfma_f32_16x16x32_bf16(Bt[n][k], At[m][k], acc[ai][bj][m][n], 0, 0, 0); __builtin_amdgcn_s_setprio(0); } while (0)
; #define PG8_WAIT_V(n) asm volatile("s_waitcnt vmcnt(" #n ")" ::: "memory")
; #define PG8_WAIT_L(n) asm volatile("s_waitcnt lgkmcnt(" #n ")" ::: "memory")
; #define PG8_BAR __builtin_amdgcn_s_barrier()
; #define PG8_SCHED __builtin_amdgcn_sched_barrier(0)
; template <class Epi, class Sched, bool ALIGN_EPI = false, bool SP2 = false>
; __device__ __forceinline__ void gemm_phase(PG8_LAS unsigned char* lds, const Gemm g, const Sched& S, const Epi& E) {
;     ...
;             PG8_WAIT_V(8); PG8_WAIT_L(0); PG8_BAR; PG8_MMA(0, 0, At, B0); PG8_MMA(0, 1, At, B1); PG8_BAR; PG8_SCHED;
;             PG8_LDA(At, 0, 1); PG8_STAGE(PG8_SB(0, 0), b2, voffB); PG8_STAGE(PG8_SB(0, 1), b2 + hstep, voffB); PG8_STAGE(PG8_SA(0, 0), a2, voffA);
;             PG8_WAIT_V(8); PG8_WAIT_L(0); PG8_BAR; PG8_MMA(1, 0, At, B0); PG8_MMA(1, 1, At, B1); PG8_BAR; PG8_SCHED;
;             PG8_LDB(B0, 1, 0); PG8_LDB(B1, 1, 1); PG8_SCHED; PG8_LDA(At, 1, 0); PG8_STAGE(PG8_SA(0, 1), a2 + hstep, voffA);
	s_setprio 1
	s_waitcnt lgkmcnt(0)
	v_mfma_f32_16x16x32_bf16 v[60:63], v[144:147], v[188:191], 0
	v_mfma_f32_16x16x32_bf16 v[52:55], v[162:165], v[188:191], 0
	v_mfma_f32_16x16x32_bf16 v[44:47], v[144:147], v[196:199], 0
	v_mfma_f32_16x16x32_bf16 v[36:39], v[162:165], v[196:199], 0
	v_mfma_f32_16x16x32_bf16 v[28:31], v[144:147], v[204:207], 0
	v_mfma_f32_16x16x32_bf16 v[20:23], v[162:165], v[204:207], 0
	v_mfma_f32_16x16x32_bf16 v[12:15], v[144:147], v[212:215], 0
	v_mfma_f32_16x16x32_bf16 v[4:7], v[162:165], v[212:215], 0
	v_mfma_f32_16x16x32_bf16 v[60:63], v[158:161], v[192:195], v[60:63]
	v_mfma_f32_16x16x32_bf16 v[52:55], v[166:169], v[192:195], v[52:55]
	v_mfma_f32_16x16x32_bf16 v[44:47], v[158:161], v[200:203], v[44:47]
	v_mfma_f32_16x16x32_bf16 v[36:39], v[166:169], v[200:203], v[36:39]
	v_mfma_f32_16x16x32_bf16 v[28:31], v[158:161], v[208:211], v[28:31]
	v_mfma_f32_16x16x32_bf16 v[20:23], v[166:169], v[208:211], v[20:23]
	v_mfma_f32_16x16x32_bf16 v[12:15], v[158:161], v[216:219], v[12:15]
	v_mfma_f32_16x16x32_bf16 v[4:7], v[166:169], v[216:219], v[4:7]
	s_setprio 0
	s_setprio 1
	v_mfma_f32_16x16x32_bf16 v[56:59], v[170:173], v[188:191], 0
	v_mfma_f32_16x16x32_bf16 v[48:51], v[180:183], v[188:191], 0
	v_mfma_f32_16x16x32_bf16 v[40:43], v[170:173], v[196:199], 0
	v_mfma_f32_16x16x32_bf16 v[32:35], v[180:183], v[196:199], 0
	v_mfma_f32_16x16x32_bf16 v[24:27], v[170:173], v[204:207], 0
	v_mfma_f32_16x16x32_bf16 v[16:19], v[180:183], v[204:207], 0
	v_mfma_f32_16x16x32_bf16 v[8:11], v[170:173], v[212:215], 0
	v_mfma_f32_16x16x32_bf16 v[0:3], v[180:183], v[212:215], 0
	v_mfma_f32_16x16x32_bf16 v[56:59], v[174:177], v[192:195], v[56:59]
	v_mfma_f32_16x16x32_bf16 v[48:51], v[184:187], v[192:195], v[48:51]
	v_mfma_f32_16x16x32_bf16 v[40:43], v[174:177], v[200:203], v[40:43]
	v_mfma_f32_16x16x32_bf16 v[32:35], v[184:187], v[200:203], v[32:35]
	v_mfma_f32_16x16x32_bf16 v[24:27], v[174:177], v[208:211], v[24:27]
	v_mfma_f32_16x16x32_bf16 v[16:19], v[184:187], v[208:211], v[16:19]
	v_mfma_f32_16x16x32_bf16 v[8:11], v[174:177], v[216:219], v[8:11]
	v_mfma_f32_16x16x32_bf16 v[0:3], v[184:187], v[216:219], v[0:3]
	s_setprio 0
	s_barrier
	s_add_i32 s64, 0, 0x18000
	v_add_u32_e32 v157, s64, v151
	s_add_i32 s65, 0, 0x1c000
	ds_read_b128 v[144:147], v157
	ds_read_b128 v[158:161], v157 offset:1024
	ds_read_b128 v[162:165], v157 offset:2048
	ds_read_b128 v[166:169], v157 offset:3072
	v_add_u32_e32 v157, s65, v151
	ds_read_b128 v[170:173], v157
	ds_read_b128 v[174:177], v157 offset:1024
	ds_read_b128 v[180:183], v157 offset:2048
	ds_read_b128 v[184:187], v157 offset:3072
	s_add_u32 s44, s44, 0x40000
	s_addc_u32 s45, s45, 0
	s_mov_b32 m0, s47
	ds_read_b128 v[188:191], v156 offset:32768
	ds_read_b128 v[192:195], v156 offset:33792
	ds_read_b128 v[196:199], v156 offset:34816
	ds_read_b128 v[200:203], v156 offset:35840
	ds_read_b128 v[204:207], v156 offset:36864
	ds_read_b128 v[208:211], v156 offset:37888
	ds_read_b128 v[212:215], v156 offset:38912
	ds_read_b128 v[216:219], v156 offset:39936
	global_load_lds_dwordx4 v128, s[44:45]
	v_lshl_add_u64 v[226:227], s[44:45], 0, v[132:133]
	s_mov_b32 m0, s48
	s_nop 0
	global_load_lds_dwordx4 v[226:227], off
	s_waitcnt vmcnt(8)
	s_waitcnt lgkmcnt(0)
	s_barrier
	s_setprio 1
	s_waitcnt lgkmcnt(0)
	v_mfma_f32_16x16x32_bf16 v[124:127], v[144:147], v[188:191], v[124:127]
	v_mfma_f32_16x16x32_bf16 v[116:119], v[162:165], v[188:191], v[116:119]
	v_mfma_f32_16x16x32_bf16 v[108:111], v[144:147], v[196:199], v[108:111]
	v_mfma_f32_16x16x32_bf16 v[100:103], v[162:165], v[196:199], v[100:103]
	v_mfma_f32_16x16x32_bf16 v[92:95], v[144:147], v[204:207], v[92:95]
	v_mfma_f32_16x16x32_bf16 v[84:87], v[162:165], v[204:207], v[84:87]
	v_mfma_f32_16x16x32_bf16 v[76:79], v[144:147], v[212:215], v[76:79]
	v_mfma_f32_16x16x32_bf16 v[68:71], v[162:165], v[212:215], v[68:71]
	v_mfma_f32_16x16x32_bf16 v[124:127], v[158:161], v[192:195], v[124:127]
	v_mfma_f32_16x16x32_bf16 v[116:119], v[166:169], v[192:195], v[116:119]
	v_mfma_f32_16x16x32_bf16 v[108:111], v[158:161], v[200:203], v[108:111]
	v_mfma_f32_16x16x32_bf16 v[100:103], v[166:169], v[200:203], v[100:103]
	v_mfma_f32_16x16x32_bf16 v[92:95], v[158:161], v[208:211], v[92:95]
	v_mfma_f32_16x16x32_bf16 v[84:87], v[166:169], v[208:211], v[84:87]
	v_mfma_f32_16x16x32_bf16 v[76:79], v[158:161], v[216:219], v[76:79]
	v_mfma_f32_16x16x32_bf16 v[68:71], v[166:169], v[216:219], v[68:71]
	s_setprio 0
	s_setprio 1
	v_mfma_f32_16x16x32_bf16 v[120:123], v[170:173], v[188:191], v[120:123]
	v_mfma_f32_16x16x32_bf16 v[112:115], v[180:183], v[188:191], v[112:115]
	v_mfma_f32_16x16x32_bf16 v[104:107], v[170:173], v[196:199], v[104:107]
	v_mfma_f32_16x16x32_bf16 v[96:99], v[180:183], v[196:199], v[96:99]
	v_mfma_f32_16x16x32_bf16 v[88:91], v[170:173], v[204:207], v[88:91]
	v_mfma_f32_16x16x32_bf16 v[80:83], v[180:183], v[204:207], v[80:83]
	v_mfma_f32_16x16x32_bf16 v[72:75], v[170:173], v[212:215], v[72:75]
	v_mfma_f32_16x16x32_bf16 v[64:67], v[180:183], v[212:215], v[64:67]
	v_mfma_f32_16x16x32_bf16 v[120:123], v[174:177], v[192:195], v[120:123]
	v_mfma_f32_16x16x32_bf16 v[112:115], v[184:187], v[192:195], v[112:115]
	v_mfma_f32_16x16x32_bf16 v[104:107], v[174:177], v[200:203], v[104:107]
	v_mfma_f32_16x16x32_bf16 v[96:99], v[184:187], v[200:203], v[96:99]
	v_mfma_f32_16x16x32_bf16 v[88:91], v[174:177], v[208:211], v[88:91]
	v_mfma_f32_16x16x32_bf16 v[80:83], v[184:187], v[208:211], v[80:83]
	v_mfma_f32_16x16x32_bf16 v[72:75], v[174:177], v[216:219], v[72:75]
	v_mfma_f32_16x16x32_bf16 v[64:67], v[184:187], v[216:219], v[64:67]
	s_setprio 0
	s_barrier
; #define PG8_STAGE(bufoff, gbase, voff) do { _Pragma("unroll") for (int _i = 0; _i < 2; ++_i) \
;         __builtin_amdgcn_global_load_lds((const unsigned*)((const char*)(gbase) + (voff)[_i]), (PG8_LAS unsigned*)(lds + (bufoff) + ldsw + _i * 8192), 16, 0, 0); } while (0)
; #define PG8_LDA(dst, b, h) do { _Pragma("unroll") for (int m = 0; m < 4; ++m) _Pragma("unroll") for (int k = 0; k < 2; ++k) dst[m][k] = *(const PG8_LAS bf16x8*)(lds + PG8_SA(b, h) + aoff + m * 2048 + k * 1024); } while (0)
; #define PG8_LDB(dst, b, h) do { _Pragma("unroll") for (int n = 0; n < 2; ++n) _Pragma("unroll") for (int k = 0; k < 2; ++k) dst[n][k] = *(const PG8_LAS bf16x8*)(lds + PG8_SB(b, h) + boff + n * 2048 + k * 1024); } while (0)
; #define PG8_MMA(ai, bj, At, Bt) do { __builtin_amdgcn_s_setprio(1); _Pragma("unroll") for (int m = 0; m < 4; ++m) _Pragma("unroll") for (int n = 0; n < 2; ++n) _Pragma("unroll") for (int k = 0; k < 2; ++k) \
;         acc[ai][bj][m][n] = __builtin_amdgcn_mfma_f32_16x16x32_bf16(Bt[n][k], At[m][k], acc[ai][bj][m][n], 0, 0, 0); __builtin_amdgcn_s_setprio(0); } while (0)
; #define PG8_WAIT_V(n) asm volatile("s_waitcnt vmcnt(" #n ")" ::: "memory")
; #define PG8_WAIT_L(n) asm volatile("s_waitcnt lgkmcnt(" #n ")" ::: "memory")
; #define PG8_BAR __builtin_amdgcn_s_barrier()
; #define PG8_SCHED __builtin_amdgcn_sched_barrier(0)
; template <class Epi, class Sched, bool ALIGN_EPI = false, bool SP2 = false>
; __device__ __forceinline__ void gemm_phase(PG8_LAS unsigned char* lds, const Gemm g, const Sched& S, const Epi& E) {
;     ...
;         for (int t = 0; t < nt; t += 2) {
;     ...
;             PG8_LDB(B0, 1, 0); PG8_LDB(B1, 1, 1); PG8_SCHED; PG8_LDA(At, 1, 0); PG8_STAGE(PG8_SA(0, 1), a2 + hstep, voffA);
;             PG8_WAIT_V(8); PG8_WAIT_L(0); PG8_BAR; PG8_MMA(0, 0, At, B0); PG8_MMA(0, 1, At, B1); PG8_BAR; PG8_SCHED;
;             PG8_LDA(At, 1, 1); PG8_STAGE(PG8_SB(1, 0), b3, voffB); PG8_STAGE(PG8_SB(1, 1), b3 + hstep, voffB); PG8_STAGE(PG8_SA(1, 0), a3, voffA);
;             PG8_WAIT_V(8); PG8_WAIT_L(0); PG8_BAR; PG8_MMA(1, 0, At, B0); PG8_MMA(1, 1, At, B1); PG8_BAR; PG8_SCHED;
	s_add_i32 s44, s64, s33
	v_lshl_add_u64 v[148:149], v[148:149], 0, s[16:17]
	s_mov_b32 m0, s44
	ds_read_b128 v[188:191], v156 offset:49152
	ds_read_b128 v[192:195], v156 offset:50176
	ds_read_b128 v[196:199], v156 offset:51200
	ds_read_b128 v[200:203], v156 offset:52224
	ds_read_b128 v[204:207], v156 offset:53248
	ds_read_b128 v[208:211], v156 offset:54272
	ds_read_b128 v[212:215], v156 offset:55296
	ds_read_b128 v[216:219], v156 offset:56320
	global_load_lds_dwordx4 v[148:149], off
	s_add_i32 m0, s44, 0x2000
	s_add_u32 s40, s40, 0x40080
	v_lshl_add_u64 v[148:149], v[220:221], 0, s[16:17]
	s_addc_u32 s41, s41, 0
	s_add_i32 s44, s65, s33
	global_load_lds_dwordx4 v[148:149], off
	s_mov_b32 m0, s44
	s_nop 0
	global_load_lds_dwordx4 v130, s[40:41]
	s_add_i32 m0, s44, 0x2000
	s_nop 0
	global_load_lds_dwordx4 v134, s[40:41]
	v_lshl_add_u64 v[148:149], v[222:223], 0, s[16:17]
	s_mov_b32 m0, s51
	s_nop 0
	global_load_lds_dwordx4 v[148:149], off
	v_lshl_add_u64 v[148:149], v[224:225], 0, s[16:17]
	s_mov_b32 m0, s52
	s_nop 0
	global_load_lds_dwordx4 v[148:149], off
	s_waitcnt vmcnt(8)
	s_waitcnt lgkmcnt(0)
	s_barrier
	s_setprio 1
	s_waitcnt lgkmcnt(0)
	v_mfma_f32_16x16x32_bf16 v[60:63], v[144:147], v[188:191], v[60:63]
	v_mfma_f32_16x16x32_bf16 v[52:55], v[162:165], v[188:191], v[52:55]
	v_mfma_f32_16x16x32_bf16 v[44:47], v[144:147], v[196:199], v[44:47]
	v_mfma_f32_16x16x32_bf16 v[36:39], v[162:165], v[196:199], v[36:39]
	v_mfma_f32_16x16x32_bf16 v[28:31], v[144:147], v[204:207], v[28:31]
	v_mfma_f32_16x16x32_bf16 v[20:23], v[162:165], v[204:207], v[20:23]
	v_mfma_f32_16x16x32_bf16 v[12:15], v[144:147], v[212:215], v[12:15]
	v_mfma_f32_16x16x32_bf16 v[4:7], v[162:165], v[212:215], v[4:7]
	v_mfma_f32_16x16x32_bf16 v[60:63], v[158:161], v[192:195], v[60:63]
	v_mfma_f32_16x16x32_bf16 v[52:55], v[166:169], v[192:195], v[52:55]
	v_mfma_f32_16x16x32_bf16 v[44:47], v[158:161], v[200:203], v[44:47]
	v_mfma_f32_16x16x32_bf16 v[36:39], v[166:169], v[200:203], v[36:39]
	v_mfma_f32_16x16x32_bf16 v[28:31], v[158:161], v[208:211], v[28:31]
	v_mfma_f32_16x16x32_bf16 v[20:23], v[166:169], v[208:211], v[20:23]
	v_mfma_f32_16x16x32_bf16 v[12:15], v[158:161], v[216:219], v[12:15]
	v_mfma_f32_16x16x32_bf16 v[4:7], v[166:169], v[216:219], v[4:7]
	s_setprio 0
	s_setprio 1
	v_mfma_f32_16x16x32_bf16 v[56:59], v[170:173], v[188:191], v[56:59]
	v_mfma_f32_16x16x32_bf16 v[48:51], v[180:183], v[188:191], v[48:51]
	v_mfma_f32_16x16x32_bf16 v[40:43], v[170:173], v[196:199], v[40:43]
	v_mfma_f32_16x16x32_bf16 v[32:35], v[180:183], v[196:199], v[32:35]
	v_mfma_f32_16x16x32_bf16 v[24:27], v[170:173], v[204:207], v[24:27]
	v_mfma_f32_16x16x32_bf16 v[16:19], v[180:183], v[204:207], v[16:19]
	v_mfma_f32_16x16x32_bf16 v[8:11], v[170:173], v[212:215], v[8:11]
	v_mfma_f32_16x16x32_bf16 v[0:3], v[180:183], v[212:215], v[0:3]
	v_mfma_f32_16x16x32_bf16 v[56:59], v[174:177], v[192:195], v[56:59]
	v_mfma_f32_16x16x32_bf16 v[48:51], v[184:187], v[192:195], v[48:51]
	v_mfma_f32_16x16x32_bf16 v[40:43], v[174:177], v[200:203], v[40:43]
	v_mfma_f32_16x16x32_bf16 v[32:35], v[184:187], v[200:203], v[32:35]
	v_mfma_f32_16x16x32_bf16 v[24:27], v[174:177], v[208:211], v[24:27]
	v_mfma_f32_16x16x32_bf16 v[16:19], v[184:187], v[208:211], v[16:19]
	v_mfma_f32_16x16x32_bf16 v[8:11], v[174:177], v[216:219], v[8:11]
	v_mfma_f32_16x16x32_bf16 v[0:3], v[184:187], v[216:219], v[0:3]
	s_setprio 0
	s_barrier
	s_add_i32 s63, s63, 2
	s_add_u32 s38, s38, 0x100
	s_addc_u32 s39, s39, 0
	s_add_u32 s61, s61, 0x100
	s_addc_u32 s62, s62, 0
	s_cmp_gt_u32 s63, 13
	s_cbranch_scc0 .LBB0_233
.LBB0_233:
	ds_read_b128 v[144:147], v154
	ds_read_b128 v[158:161], v154 offset:1024
	ds_read_b128 v[162:165], v154 offset:2048
	ds_read_b128 v[166:169], v154 offset:3072
	ds_read_b128 v[170:173], v155
	ds_read_b128 v[174:177], v155 offset:1024
	ds_read_b128 v[180:183], v155 offset:2048
	ds_read_b128 v[184:187], v155 offset:3072
	s_add_u32 s40, s38, 0xfffc0080
	s_addc_u32 s41, s39, -1
	s_cmp_eq_u32 s63, 12
	s_cselect_b32 s45, s29, s41
	s_cselect_b32 s44, s59, s40
	s_cselect_b32 s41, s27, s62
	s_cselect_b32 s40, s60, s61
	s_add_i32 m0, s37, 0xc000
	ds_read_b128 v[188:191], v156
	ds_read_b128 v[192:195], v156 offset:1024
	ds_read_b128 v[196:199], v156 offset:2048
	ds_read_b128 v[200:203], v156 offset:3072
	ds_read_b128 v[204:207], v156 offset:4096
	ds_read_b128 v[208:211], v156 offset:5120
	ds_read_b128 v[212:215], v156 offset:6144
	ds_read_b128 v[216:219], v156 offset:7168
	global_load_lds_dwordx4 v136, s[38:39]
	s_add_i32 m0, s37, 0xe000
	s_nop 0
	global_load_lds_dwordx4 v138, s[38:39]
	s_waitcnt vmcnt(8)
	s_waitcnt lgkmcnt(0)
	s_barrier
; #define PG8_STAGE(bufoff, gbase, voff) do { _Pragma("unroll") for (int _i = 0; _i < 2; ++_i) \
;         __builtin_amdgcn_global_load_lds((const unsigned*)((const char*)(gbase) + (voff)[_i]), (PG8_LAS unsigned*)(lds + (bufoff) + ldsw + _i * 8192), 16, 0, 0); } while (0)
; #define PG8_LDA(dst, b, h) do { _Pragma("unroll") for (int m = 0; m < 4; ++m) _Pragma("unroll") for (int k = 0; k < 2; ++k) dst[m][k] = *(const PG8_LAS bf16x8*)(lds + PG8_SA(b, h) + aoff + m * 2048 + k * 1024); } while (0)
; #define PG8_LDB(dst, b, h) do { _Pragma("unroll") for (int n = 0; n < 2; ++n) _Pragma("unroll") for (int k = 0; k < 2; ++k) dst[n][k] = *(const PG8_LAS bf16x8*)(lds + PG8_SB(b, h) + boff + n * 2048 + k * 1024); } while (0)
; #define PG8_MMA(ai, bj, At, Bt) do { __builtin_amdgcn_s_setprio(1); _Pragma("unroll") for (int m = 0; m < 4; ++m) _Pragma("unroll") for (int n = 0; n < 2; ++n) _Pragma("unroll") for (int k = 0; k < 2; ++k) \
;         acc[ai][bj][m][n] = __builtin_amdgcn_mfma_f32_16x16x32_bf16(Bt[n][k], At[m][k], acc[ai][bj][m][n], 0, 0, 0); __builtin_amdgcn_s_setprio(0); } while (0)
; #define PG8_WAIT_V(n) asm volatile("s_waitcnt vmcnt(" #n ")" ::: "memory")
; #define PG8_WAIT_L(n) asm volatile("s_waitcnt lgkmcnt(" #n ")" ::: "memory")
; #define PG8_BAR __builtin_amdgcn_s_barrier()
; #define PG8_SCHED __builtin_amdgcn_sched_barrier(0)
; template <class Epi, class Sched, bool ALIGN_EPI = false, bool SP2 = false>
; __device__ __forceinline__ void gemm_phase(PG8_LAS unsigned char* lds, const Gemm g, const Sched& S, const Epi& E) {
;     ...
;             PG8_LDB(B0, 0, 0); PG8_LDB(B1, 0, 1); PG8_SCHED; PG8_LDA(At, 0, 0); PG8_STAGE(PG8_SA(1, 1), a1 + hstep, voffA);
;             PG8_WAIT_V(8); PG8_WAIT_L(0); PG8_BAR; PG8_MMA(0, 0, At, B0); PG8_MMA(0, 1, At, B1); PG8_BAR; PG8_SCHED;
;             PG8_LDA(At, 0, 1); PG8_STAGE(PG8_SB(0, 0), b2, voffB); PG8_STAGE(PG8_SB(0, 1), b2 + hstep, voffB); PG8_STAGE(PG8_SA(0, 0), a2, voffA);
;             PG8_WAIT_V(8); PG8_WAIT_L(0); PG8_BAR; PG8_MMA(1, 0, At, B0); PG8_MMA(1, 1, At, B1); PG8_BAR; PG8_SCHED;
	s_setprio 1
	s_waitcnt lgkmcnt(0)
	v_mfma_f32_16x16x32_bf16 v[124:127], v[144:147], v[188:191], v[124:127]
	v_mfma_f32_16x16x32_bf16 v[116:119], v[162:165], v[188:191], v[116:119]
	v_mfma_f32_16x16x32_bf16 v[108:111], v[144:147], v[196:199], v[108:111]
	v_mfma_f32_16x16x32_bf16 v[100:103], v[162:165], v[196:199], v[100:103]
	v_mfma_f32_16x16x32_bf16 v[92:95], v[144:147], v[204:207], v[92:95]
	v_mfma_f32_16x16x32_bf16 v[84:87], v[162:165], v[204:207], v[84:87]
	v_mfma_f32_16x16x32_bf16 v[76:79], v[144:147], v[212:215], v[76:79]
	v_mfma_f32_16x16x32_bf16 v[68:71], v[162:165], v[212:215], v[68:71]
	v_mfma_f32_16x16x32_bf16 v[124:127], v[158:161], v[192:195], v[124:127]
	v_mfma_f32_16x16x32_bf16 v[116:119], v[166:169], v[192:195], v[116:119]
	v_mfma_f32_16x16x32_bf16 v[108:111], v[158:161], v[200:203], v[108:111]
	v_mfma_f32_16x16x32_bf16 v[100:103], v[166:169], v[200:203], v[100:103]
	v_mfma_f32_16x16x32_bf16 v[92:95], v[158:161], v[208:211], v[92:95]
	v_mfma_f32_16x16x32_bf16 v[84:87], v[166:169], v[208:211], v[84:87]
	v_mfma_f32_16x16x32_bf16 v[76:79], v[158:161], v[216:219], v[76:79]
	v_mfma_f32_16x16x32_bf16 v[68:71], v[166:169], v[216:219], v[68:71]
	s_setprio 0
	s_setprio 1
	v_mfma_f32_16x16x32_bf16 v[120:123], v[170:173], v[188:191], v[120:123]
	v_mfma_f32_16x16x32_bf16 v[112:115], v[180:183], v[188:191], v[112:115]
	v_mfma_f32_16x16x32_bf16 v[104:107], v[170:173], v[196:199], v[104:107]
	v_mfma_f32_16x16x32_bf16 v[96:99], v[180:183], v[196:199], v[96:99]
	v_mfma_f32_16x16x32_bf16 v[88:91], v[170:173], v[204:207], v[88:91]
	v_mfma_f32_16x16x32_bf16 v[80:83], v[180:183], v[204:207], v[80:83]
	v_mfma_f32_16x16x32_bf16 v[72:75], v[170:173], v[212:215], v[72:75]
	v_mfma_f32_16x16x32_bf16 v[64:67], v[180:183], v[212:215], v[64:67]
	v_mfma_f32_16x16x32_bf16 v[120:123], v[174:177], v[192:195], v[120:123]
	v_mfma_f32_16x16x32_bf16 v[112:115], v[184:187], v[192:195], v[112:115]
	v_mfma_f32_16x16x32_bf16 v[104:107], v[174:177], v[200:203], v[104:107]
	v_mfma_f32_16x16x32_bf16 v[96:99], v[184:187], v[200:203], v[96:99]
	v_mfma_f32_16x16x32_bf16 v[88:91], v[174:177], v[208:211], v[88:91]
	v_mfma_f32_16x16x32_bf16 v[80:83], v[184:187], v[208:211], v[80:83]
	v_mfma_f32_16x16x32_bf16 v[72:75], v[174:177], v[216:219], v[72:75]
	v_mfma_f32_16x16x32_bf16 v[64:67], v[184:187], v[216:219], v[64:67]
	s_setprio 0
	s_barrier
	s_add_i32 s64, s53, s33
	v_lshl_add_u64 v[148:149], s[40:41], 0, v[130:131]
	s_mov_b32 m0, s64
	ds_read_b128 v[188:191], v156 offset:16384
	ds_read_b128 v[192:195], v156 offset:17408
	ds_read_b128 v[196:199], v156 offset:18432
	ds_read_b128 v[200:203], v156 offset:19456
	ds_read_b128 v[204:207], v156 offset:20480
	ds_read_b128 v[208:211], v156 offset:21504
	ds_read_b128 v[212:215], v156 offset:22528
	ds_read_b128 v[216:219], v156 offset:23552
	global_load_lds_dwordx4 v[148:149], off
	s_add_i32 m0, s64, 0x2000
	s_add_u32 s64, s40, 0x40000
	v_lshl_add_u64 v[220:221], s[40:41], 0, v[134:135]
	s_addc_u32 s65, s41, 0
	s_add_i32 s66, s54, s33
	global_load_lds_dwordx4 v[220:221], off
	s_mov_b32 m0, s66
	v_lshl_add_u64 v[224:225], s[44:45], 0, v[132:133]
	global_load_lds_dwordx4 v130, s[64:65]
	s_add_i32 m0, s66, 0x2000
	s_nop 0
	global_load_lds_dwordx4 v134, s[64:65]
	v_lshl_add_u64 v[222:223], s[44:45], 0, v[128:129]
	s_mov_b32 m0, s37
	s_nop 0
	global_load_lds_dwordx4 v[222:223], off
	s_mov_b32 m0, s46
	s_nop 0
	global_load_lds_dwordx4 v[224:225], off
	s_waitcnt vmcnt(8)
	s_waitcnt lgkmcnt(0)
	s_barrier
	s_setprio 1
	s_waitcnt lgkmcnt(0)
	v_mfma_f32_16x16x32_bf16 v[60:63], v[144:147], v[188:191], v[60:63]
	v_mfma_f32_16x16x32_bf16 v[52:55], v[162:165], v[188:191], v[52:55]
	v_mfma_f32_16x16x32_bf16 v[44:47], v[144:147], v[196:199], v[44:47]
	v_mfma_f32_16x16x32_bf16 v[36:39], v[162:165], v[196:199], v[36:39]
	v_mfma_f32_16x16x32_bf16 v[28:31], v[144:147], v[204:207], v[28:31]
	v_mfma_f32_16x16x32_bf16 v[20:23], v[162:165], v[204:207], v[20:23]
	v_mfma_f32_16x16x32_bf16 v[12:15], v[144:147], v[212:215], v[12:15]
	v_mfma_f32_16x16x32_bf16 v[4:7], v[162:165], v[212:215], v[4:7]
	v_mfma_f32_16x16x32_bf16 v[60:63], v[158:161], v[192:195], v[60:63]
	v_mfma_f32_16x16x32_bf16 v[52:55], v[166:169], v[192:195], v[52:55]
	v_mfma_f32_16x16x32_bf16 v[44:47], v[158:161], v[200:203], v[44:47]
	v_mfma_f32_16x16x32_bf16 v[36:39], v[166:169], v[200:203], v[36:39]
	v_mfma_f32_16x16x32_bf16 v[28:31], v[158:161], v[208:211], v[28:31]
	v_mfma_f32_16x16x32_bf16 v[20:23], v[166:169], v[208:211], v[20:23]
	v_mfma_f32_16x16x32_bf16 v[12:15], v[158:161], v[216:219], v[12:15]
	v_mfma_f32_16x16x32_bf16 v[4:7], v[166:169], v[216:219], v[4:7]
	s_setprio 0
	s_setprio 1
	v_mfma_f32_16x16x32_bf16 v[56:59], v[170:173], v[188:191], v[56:59]
	v_mfma_f32_16x16x32_bf16 v[48:51], v[180:183], v[188:191], v[48:51]
	v_mfma_f32_16x16x32_bf16 v[40:43], v[170:173], v[196:199], v[40:43]
	v_mfma_f32_16x16x32_bf16 v[32:35], v[180:183], v[196:199], v[32:35]
	v_mfma_f32_16x16x32_bf16 v[24:27], v[170:173], v[204:207], v[24:27]
	v_mfma_f32_16x16x32_bf16 v[16:19], v[180:183], v[204:207], v[16:19]
	v_mfma_f32_16x16x32_bf16 v[8:11], v[170:173], v[212:215], v[8:11]
	v_mfma_f32_16x16x32_bf16 v[0:3], v[180:183], v[212:215], v[0:3]
	v_mfma_f32_16x16x32_bf16 v[56:59], v[174:177], v[192:195], v[56:59]
	v_mfma_f32_16x16x32_bf16 v[48:51], v[184:187], v[192:195], v[48:51]
	v_mfma_f32_16x16x32_bf16 v[40:43], v[174:177], v[200:203], v[40:43]
	v_mfma_f32_16x16x32_bf16 v[32:35], v[184:187], v[200:203], v[32:35]
	v_mfma_f32_16x16x32_bf16 v[24:27], v[174:177], v[208:211], v[24:27]
	v_mfma_f32_16x16x32_bf16 v[16:19], v[184:187], v[208:211], v[16:19]
	v_mfma_f32_16x16x32_bf16 v[8:11], v[174:177], v[216:219], v[8:11]
	v_mfma_f32_16x16x32_bf16 v[0:3], v[184:187], v[216:219], v[0:3]
	s_setprio 0
	s_barrier
; #define PG8_STAGE(bufoff, gbase, voff) do { _Pragma("unroll") for (int _i = 0; _i < 2; ++_i) \
;         __builtin_amdgcn_global_load_lds((const unsigned*)((const char*)(gbase) + (voff)[_i]), (PG8_LAS unsigned*)(lds + (bufoff) + ldsw + _i * 8192), 16, 0, 0); } while (0)
; #define PG8_LDA(dst, b, h) do { _Pragma("unroll") for (int m = 0; m < 4; ++m) _Pragma("unroll") for (int k = 0; k < 2; ++k) dst[m][k] = *(const PG8_LAS bf16x8*)(lds + PG8_SA(b, h) + aoff + m * 2048 + k * 1024); } while (0)
; #define PG8_LDB(dst, b, h) do { _Pragma("unroll") for (int n = 0; n < 2; ++n) _Pragma("unroll") for (int k = 0; k < 2; ++k) dst[n][k] = *(const PG8_LAS bf16x8*)(lds + PG8_SB(b, h) + boff + n * 2048 + k * 1024); } while (0)
; #define PG8_MMA(ai, bj, At, Bt) do { __builtin_amdgcn_s_setprio(1); _Pragma("unroll") for (int m = 0; m < 4; ++m) _Pragma("unroll") for (int n = 0; n < 2; ++n) _Pragma("unroll") for (int k = 0; k < 2; ++k) \
;         acc[ai][bj][m][n] = __builtin_amdgcn_mfma_f32_16x16x32_bf16(Bt[n][k], At[m][k], acc[ai][bj][m][n], 0, 0, 0); __builtin_amdgcn_s_setprio(0); } while (0)
; #define PG8_WAIT_V(n) asm volatile("s_waitcnt vmcnt(" #n ")" ::: "memory")
; #define PG8_WAIT_L(n) asm volatile("s_waitcnt lgkmcnt(" #n ")" ::: "memory")
; #define PG8_BAR __builtin_amdgcn_s_barrier()
; #define PG8_SCHED __builtin_amdgcn_sched_barrier(0)
; template <class Epi, class Sched, bool ALIGN_EPI = false, bool SP2 = false>
; __device__ __forceinline__ void gemm_phase(PG8_LAS unsigned char* lds, const Gemm g, const Sched& S, const Epi& E) {
;     ...
;             PG8_WAIT_V(8); PG8_WAIT_L(0); PG8_BAR; PG8_MMA(1, 0, At, B0); PG8_MMA(1, 1, At, B1); PG8_BAR; PG8_SCHED;
;             PG8_LDB(B0, 1, 0); PG8_LDB(B1, 1, 1); PG8_SCHED; PG8_LDA(At, 1, 0); PG8_STAGE(PG8_SA(0, 1), a2 + hstep, voffA);
;             PG8_WAIT_V(8); PG8_WAIT_L(0); PG8_BAR; PG8_MMA(0, 0, At, B0); PG8_MMA(0, 1, At, B1); PG8_BAR; PG8_SCHED;
	s_add_i32 s64, 0, 0x18000
	v_add_u32_e32 v157, s64, v151
	s_add_i32 s65, 0, 0x1c000
	ds_read_b128 v[144:147], v157
	ds_read_b128 v[158:161], v157 offset:1024
	ds_read_b128 v[162:165], v157 offset:2048
	ds_read_b128 v[166:169], v157 offset:3072
	v_add_u32_e32 v157, s65, v151
	ds_read_b128 v[170:173], v157
	ds_read_b128 v[174:177], v157 offset:1024
	ds_read_b128 v[180:183], v157 offset:2048
	ds_read_b128 v[184:187], v157 offset:3072
	s_add_u32 s44, s44, 0x40000
	s_addc_u32 s45, s45, 0
	s_mov_b32 m0, s47
	ds_read_b128 v[188:191], v156 offset:32768
	ds_read_b128 v[192:195], v156 offset:33792
	ds_read_b128 v[196:199], v156 offset:34816
	ds_read_b128 v[200:203], v156 offset:35840
	ds_read_b128 v[204:207], v156 offset:36864
	ds_read_b128 v[208:211], v156 offset:37888
	ds_read_b128 v[212:215], v156 offset:38912
	ds_read_b128 v[216:219], v156 offset:39936
	global_load_lds_dwordx4 v128, s[44:45]
	v_lshl_add_u64 v[226:227], s[44:45], 0, v[132:133]
	s_mov_b32 m0, s48
	s_nop 0
	global_load_lds_dwordx4 v[226:227], off
	s_waitcnt vmcnt(8)
	s_waitcnt lgkmcnt(0)
	s_barrier
	s_setprio 1
	s_waitcnt lgkmcnt(0)
	v_mfma_f32_16x16x32_bf16 v[124:127], v[144:147], v[188:191], v[124:127]
	v_mfma_f32_16x16x32_bf16 v[116:119], v[162:165], v[188:191], v[116:119]
	v_mfma_f32_16x16x32_bf16 v[108:111], v[144:147], v[196:199], v[108:111]
	v_mfma_f32_16x16x32_bf16 v[100:103], v[162:165], v[196:199], v[100:103]
	v_mfma_f32_16x16x32_bf16 v[92:95], v[144:147], v[204:207], v[92:95]
	v_mfma_f32_16x16x32_bf16 v[84:87], v[162:165], v[204:207], v[84:87]
	v_mfma_f32_16x16x32_bf16 v[76:79], v[144:147], v[212:215], v[76:79]
	v_mfma_f32_16x16x32_bf16 v[68:71], v[162:165], v[212:215], v[68:71]
	v_mfma_f32_16x16x32_bf16 v[124:127], v[158:161], v[192:195], v[124:127]
	v_mfma_f32_16x16x32_bf16 v[116:119], v[166:169], v[192:195], v[116:119]
	v_mfma_f32_16x16x32_bf16 v[108:111], v[158:161], v[200:203], v[108:111]
	v_mfma_f32_16x16x32_bf16 v[100:103], v[166:169], v[200:203], v[100:103]
	v_mfma_f32_16x16x32_bf16 v[92:95], v[158:161], v[208:211], v[92:95]
	v_mfma_f32_16x16x32_bf16 v[84:87], v[166:169], v[208:211], v[84:87]
	v_mfma_f32_16x16x32_bf16 v[76:79], v[158:161], v[216:219], v[76:79]
	v_mfma_f32_16x16x32_bf16 v[68:71], v[166:169], v[216:219], v[68:71]
	s_setprio 0
	s_setprio 1
	v_mfma_f32_16x16x32_bf16 v[120:123], v[170:173], v[188:191], v[120:123]
	v_mfma_f32_16x16x32_bf16 v[112:115], v[180:183], v[188:191], v[112:115]
	v_mfma_f32_16x16x32_bf16 v[104:107], v[170:173], v[196:199], v[104:107]
	v_mfma_f32_16x16x32_bf16 v[96:99], v[180:183], v[196:199], v[96:99]
	v_mfma_f32_16x16x32_bf16 v[88:91], v[170:173], v[204:207], v[88:91]
	v_mfma_f32_16x16x32_bf16 v[80:83], v[180:183], v[204:207], v[80:83]
	v_mfma_f32_16x16x32_bf16 v[72:75], v[170:173], v[212:215], v[72:75]
	v_mfma_f32_16x16x32_bf16 v[64:67], v[180:183], v[212:215], v[64:67]
	v_mfma_f32_16x16x32_bf16 v[120:123], v[174:177], v[192:195], v[120:123]
	v_mfma_f32_16x16x32_bf16 v[112:115], v[184:187], v[192:195], v[112:115]
	v_mfma_f32_16x16x32_bf16 v[104:107], v[174:177], v[200:203], v[104:107]
	v_mfma_f32_16x16x32_bf16 v[96:99], v[184:187], v[200:203], v[96:99]
	v_mfma_f32_16x16x32_bf16 v[88:91], v[174:177], v[208:211], v[88:91]
	v_mfma_f32_16x16x32_bf16 v[80:83], v[184:187], v[208:211], v[80:83]
	v_mfma_f32_16x16x32_bf16 v[72:75], v[174:177], v[216:219], v[72:75]
	v_mfma_f32_16x16x32_bf16 v[64:67], v[184:187], v[216:219], v[64:67]
	s_setprio 0
	s_barrier
; #define PG8_STAGE(bufoff, gbase, voff) do { _Pragma("unroll") for (int _i = 0; _i < 2; ++_i) \
;         __builtin_amdgcn_global_load_lds((const unsigned*)((const char*)(gbase) + (voff)[_i]), (PG8_LAS unsigned*)(lds + (bufoff) + ldsw + _i * 8192), 16, 0, 0); } while (0)
; #define PG8_LDA(dst, b, h) do { _Pragma("unroll") for (int m = 0; m < 4; ++m) _Pragma("unroll") for (int k = 0; k < 2; ++k) dst[m][k] = *(const PG8_LAS bf16x8*)(lds + PG8_SA(b, h) + aoff + m * 2048 + k * 1024); } while (0)
; #define PG8_MMA(ai, bj, At, Bt) do { __builtin_amdgcn_s_setprio(1); _Pragma("unroll") for (int m = 0; m < 4; ++m) _Pragma("unroll") for (int n = 0; n < 2; ++n) _Pragma("unroll") for (int k = 0; k < 2; ++k) \
;         acc[ai][bj][m][n] = __builtin_amdgcn_mfma_f32_16x16x32_bf16(Bt[n][k], At[m][k], acc[ai][bj][m][n], 0, 0, 0); __builtin_amdgcn_s_setprio(0); } while (0)
; #define PG8_WAIT_V(n) asm volatile("s_waitcnt vmcnt(" #n ")" ::: "memory")
; #define PG8_WAIT_L(n) asm volatile("s_waitcnt lgkmcnt(" #n ")" ::: "memory")
; #define PG8_BAR __builtin_amdgcn_s_barrier()
; #define PG8_SCHED __builtin_amdgcn_sched_barrier(0)
; template <class Epi, class Sched, bool ALIGN_EPI = false, bool SP2 = false>
; __device__ __forceinline__ void gemm_phase(PG8_LAS unsigned char* lds, const Gemm g, const Sched& S, const Epi& E) {
;     ...
;         for (int t = 0; t < nt; t += 2) {
;     ...
;             PG8_WAIT_V(8); PG8_WAIT_L(0); PG8_BAR; PG8_MMA(0, 0, At, B0); PG8_MMA(0, 1, At, B1); PG8_BAR; PG8_SCHED;
;             PG8_LDA(At, 1, 1); PG8_STAGE(PG8_SB(1, 0), b3, voffB); PG8_STAGE(PG8_SB(1, 1), b3 + hstep, voffB); PG8_STAGE(PG8_SA(1, 0), a3, voffA);
;             PG8_WAIT_V(8); PG8_WAIT_L(0); PG8_BAR; PG8_MMA(1, 0, At, B0); PG8_MMA(1, 1, At, B1); PG8_BAR; PG8_SCHED;
	s_add_i32 s44, s64, s33
	v_lshl_add_u64 v[148:149], v[148:149], 0, s[16:17]
	s_mov_b32 m0, s44
	ds_read_b128 v[188:191], v156 offset:49152
	ds_read_b128 v[192:195], v156 offset:50176
	ds_read_b128 v[196:199], v156 offset:51200
	ds_read_b128 v[200:203], v156 offset:52224
	ds_read_b128 v[204:207], v156 offset:53248
	ds_read_b128 v[208:211], v156 offset:54272
	ds_read_b128 v[212:215], v156 offset:55296
	ds_read_b128 v[216:219], v156 offset:56320
	global_load_lds_dwordx4 v[148:149], off
	s_add_i32 m0, s44, 0x2000
	s_add_u32 s40, s40, 0x40080
	v_lshl_add_u64 v[148:149], v[220:221], 0, s[16:17]
	s_addc_u32 s41, s41, 0
	s_add_i32 s44, s65, s33
	global_load_lds_dwordx4 v[148:149], off
	s_mov_b32 m0, s44
	s_nop 0
	global_load_lds_dwordx4 v130, s[40:41]
	s_add_i32 m0, s44, 0x2000
	s_nop 0
	global_load_lds_dwordx4 v134, s[40:41]
	v_lshl_add_u64 v[148:149], v[222:223], 0, s[16:17]
	s_mov_b32 m0, s51
	s_nop 0
	global_load_lds_dwordx4 v[148:149], off
	v_lshl_add_u64 v[148:149], v[224:225], 0, s[16:17]
	s_mov_b32 m0, s52
	s_nop 0
	global_load_lds_dwordx4 v[148:149], off
	s_waitcnt vmcnt(8)
	s_waitcnt lgkmcnt(0)
	s_barrier
	s_setprio 1
	s_waitcnt lgkmcnt(0)
	v_mfma_f32_16x16x32_bf16 v[60:63], v[144:147], v[188:191], v[60:63]
	v_mfma_f32_16x16x32_bf16 v[52:55], v[162:165], v[188:191], v[52:55]
	v_mfma_f32_16x16x32_bf16 v[44:47], v[144:147], v[196:199], v[44:47]
	v_mfma_f32_16x16x32_bf16 v[36:39], v[162:165], v[196:199], v[36:39]
	v_mfma_f32_16x16x32_bf16 v[28:31], v[144:147], v[204:207], v[28:31]
	v_mfma_f32_16x16x32_bf16 v[20:23], v[162:165], v[204:207], v[20:23]
	v_mfma_f32_16x16x32_bf16 v[12:15], v[144:147], v[212:215], v[12:15]
	v_mfma_f32_16x16x32_bf16 v[4:7], v[162:165], v[212:215], v[4:7]
	v_mfma_f32_16x16x32_bf16 v[60:63], v[158:161], v[192:195], v[60:63]
	v_mfma_f32_16x16x32_bf16 v[52:55], v[166:169], v[192:195], v[52:55]
	v_mfma_f32_16x16x32_bf16 v[44:47], v[158:161], v[200:203], v[44:47]
	v_mfma_f32_16x16x32_bf16 v[36:39], v[166:169], v[200:203], v[36:39]
	v_mfma_f32_16x16x32_bf16 v[28:31], v[158:161], v[208:211], v[28:31]
	v_mfma_f32_16x16x32_bf16 v[20:23], v[166:169], v[208:211], v[20:23]
	v_mfma_f32_16x16x32_bf16 v[12:15], v[158:161], v[216:219], v[12:15]
	v_mfma_f32_16x16x32_bf16 v[4:7], v[166:169], v[216:219], v[4:7]
	s_setprio 0
	s_setprio 1
	v_mfma_f32_16x16x32_bf16 v[56:59], v[170:173], v[188:191], v[56:59]
	v_mfma_f32_16x16x32_bf16 v[48:51], v[180:183], v[188:191], v[48:51]
	v_mfma_f32_16x16x32_bf16 v[40:43], v[170:173], v[196:199], v[40:43]
	v_mfma_f32_16x16x32_bf16 v[32:35], v[180:183], v[196:199], v[32:35]
	v_mfma_f32_16x16x32_bf16 v[24:27], v[170:173], v[204:207], v[24:27]
	v_mfma_f32_16x16x32_bf16 v[16:19], v[180:183], v[204:207], v[16:19]
	v_mfma_f32_16x16x32_bf16 v[8:11], v[170:173], v[212:215], v[8:11]
	v_mfma_f32_16x16x32_bf16 v[0:3], v[180:183], v[212:215], v[0:3]
	v_mfma_f32_16x16x32_bf16 v[56:59], v[174:177], v[192:195], v[56:59]
	v_mfma_f32_16x16x32_bf16 v[48:51], v[184:187], v[192:195], v[48:51]
	v_mfma_f32_16x16x32_bf16 v[40:43], v[174:177], v[200:203], v[40:43]
	v_mfma_f32_16x16x32_bf16 v[32:35], v[184:187], v[200:203], v[32:35]
	v_mfma_f32_16x16x32_bf16 v[24:27], v[174:177], v[208:211], v[24:27]
	v_mfma_f32_16x16x32_bf16 v[16:19], v[184:187], v[208:211], v[16:19]
	v_mfma_f32_16x16x32_bf16 v[8:11], v[174:177], v[216:219], v[8:11]
	v_mfma_f32_16x16x32_bf16 v[0:3], v[184:187], v[216:219], v[0:3]
	s_setprio 0
	s_barrier
	s_add_i32 s63, s63, 2
	s_add_u32 s38, s38, 0x100
	s_addc_u32 s39, s39, 0
	s_add_u32 s61, s61, 0x100
	s_addc_u32 s62, s62, 0
	s_cmp_gt_u32 s63, 13
	s_cbranch_scc0 .LBB0_233
	s_and_b64 vcc, exec, s[18:19]
	s_cbranch_vccz .LBB0_236
	s_barrier

; #define PG8_STAGE(bufoff, gbase, voff) do { _Pragma("unroll") for (int _i = 0; _i < 2; ++_i) \
;         __builtin_amdgcn_global_load_lds((const unsigned*)((const char*)(gbase) + (voff)[_i]), (PG8_LAS unsigned*)(lds + (bufoff) + ldsw + _i * 8192), 16, 0, 0); } while (0)
; #define PG8_LDA(dst, b, h) do { _Pragma("unroll") for (int m = 0; m < 4; ++m) _Pragma("unroll") for (int k = 0; k < 2; ++k) dst[m][k] = *(const PG8_LAS bf16x8*)(lds + PG8_SA(b, h) + aoff + m * 2048 + k * 1024); } while (0)
; #define PG8_LDB(dst, b, h) do { _Pragma("unroll") for (int n = 0; n < 2; ++n) _Pragma("unroll") for (int k = 0; k < 2; ++k) dst[n][k] = *(const PG8_LAS bf16x8*)(lds + PG8_SB(b, h) + boff + n * 2048 + k * 1024); } while (0)
; #define PG8_MMA(ai, bj, At, Bt) do { __builtin_amdgcn_s_setprio(1); _Pragma("unroll") for (int m = 0; m < 4; ++m) _Pragma("unroll") for (int n = 0; n < 2; ++n) _Pragma("unroll") for (int k = 0; k < 2; ++k) \
;         acc[ai][bj][m][n] = __builtin_amdgcn_mfma_f32_16x16x32_bf16(Bt[n][k], At[m][k], acc[ai][bj][m][n], 0, 0, 0); __builtin_amdgcn_s_setprio(0); } while (0)
; #define PG8_WAIT_V(n) asm volatile("s_waitcnt vmcnt(" #n ")" ::: "memory")
; #define PG8_WAIT_L(n) asm volatile("s_waitcnt lgkmcnt(" #n ")" ::: "memory")
; #define PG8_BAR __builtin_amdgcn_s_barrier()
; #define PG8_SCHED __builtin_amdgcn_sched_barrier(0)
; template <class Epi, class Sched, bool ALIGN_EPI = false, bool SP2 = false>
; __device__ __forceinline__ void gemm_phase(PG8_LAS unsigned char* lds, const Gemm g, const Sched& S, const Epi& E) {
;     ...
;             PG8_LDB(B0, 0, 0); PG8_LDB(B1, 0, 1); PG8_SCHED; PG8_LDA(At, 0, 0); PG8_STAGE(PG8_SA(1, 1), a1 + hstep, voffA);
;             PG8_WAIT_V(8); PG8_WAIT_L(0); PG8_BAR; PG8_MMA(0, 0, At, B0); PG8_MMA(0, 1, At, B1); PG8_BAR; PG8_SCHED;
;             PG8_LDA(At, 0, 1); PG8_STAGE(PG8_SB(0, 0), b2, voffB); PG8_STAGE(PG8_SB(0, 1), b2 + hstep, voffB); PG8_STAGE(PG8_SA(0, 0), a2, voffA);
.LBB0_405:
	v_add_u32_e32 v156, s56, v181
	v_add_u32_e32 v172, s57, v181
	ds_read_b128 v[144:147], v156
	ds_read_b128 v[148:151], v156 offset:1024
	ds_read_b128 v[152:155], v156 offset:2048
	ds_read_b128 v[156:159], v156 offset:3072
	ds_read_b128 v[160:163], v172
	ds_read_b128 v[164:167], v172 offset:1024
	ds_read_b128 v[168:171], v172 offset:2048
	ds_read_b128 v[172:175], v172 offset:3072
	s_add_u32 s36, s38, 0xfff50080
	s_addc_u32 s37, s39, -1
	s_cmp_eq_u32 s64, 40
	s_cselect_b32 s41, s5, s37
	s_cselect_b32 s40, s4, s36
	s_cselect_b32 s37, s35, s63
	s_cselect_b32 s36, s34, s62
	s_add_i32 m0, s47, 0xc000
	ds_read_b128 v[186:189], v183
	ds_read_b128 v[190:193], v183 offset:1024
	ds_read_b128 v[194:197], v183 offset:2048
	ds_read_b128 v[198:201], v183 offset:3072
	ds_read_b128 v[202:205], v183 offset:4096
	ds_read_b128 v[206:209], v183 offset:5120
	ds_read_b128 v[210:213], v183 offset:6144
	ds_read_b128 v[214:217], v183 offset:7168
	global_load_lds_dwordx4 v136, s[38:39]
	s_add_i32 m0, s47, 0xe000
	s_nop 0
	global_load_lds_dwordx4 v138, s[38:39]
	s_waitcnt vmcnt(8)
	s_waitcnt lgkmcnt(0)
	s_barrier
	s_setprio 1
	s_waitcnt lgkmcnt(0)
	v_mfma_f32_16x16x32_bf16 v[112:115], v[144:147], v[186:189], v[112:115]
	v_mfma_f32_16x16x32_bf16 v[116:119], v[152:155], v[186:189], v[116:119]
	v_mfma_f32_16x16x32_bf16 v[96:99], v[144:147], v[194:197], v[96:99]
	v_mfma_f32_16x16x32_bf16 v[100:103], v[152:155], v[194:197], v[100:103]
	v_mfma_f32_16x16x32_bf16 v[80:83], v[144:147], v[202:205], v[80:83]
	v_mfma_f32_16x16x32_bf16 v[84:87], v[152:155], v[202:205], v[84:87]
	v_mfma_f32_16x16x32_bf16 v[52:55], v[144:147], v[210:213], v[52:55]
	v_mfma_f32_16x16x32_bf16 v[60:63], v[152:155], v[210:213], v[60:63]
	v_mfma_f32_16x16x32_bf16 v[112:115], v[148:151], v[190:193], v[112:115]
	v_mfma_f32_16x16x32_bf16 v[116:119], v[156:159], v[190:193], v[116:119]
	v_mfma_f32_16x16x32_bf16 v[96:99], v[148:151], v[198:201], v[96:99]
	v_mfma_f32_16x16x32_bf16 v[100:103], v[156:159], v[198:201], v[100:103]
	v_mfma_f32_16x16x32_bf16 v[80:83], v[148:151], v[206:209], v[80:83]
	v_mfma_f32_16x16x32_bf16 v[84:87], v[156:159], v[206:209], v[84:87]
	v_mfma_f32_16x16x32_bf16 v[52:55], v[148:151], v[214:217], v[52:55]
	v_mfma_f32_16x16x32_bf16 v[60:63], v[156:159], v[214:217], v[60:63]
	s_setprio 0
	s_setprio 1
	v_mfma_f32_16x16x32_bf16 v[120:123], v[160:163], v[186:189], v[120:123]
	v_mfma_f32_16x16x32_bf16 v[124:127], v[168:171], v[186:189], v[124:127]
	v_mfma_f32_16x16x32_bf16 v[104:107], v[160:163], v[194:197], v[104:107]
	v_mfma_f32_16x16x32_bf16 v[108:111], v[168:171], v[194:197], v[108:111]
	v_mfma_f32_16x16x32_bf16 v[88:91], v[160:163], v[202:205], v[88:91]
	v_mfma_f32_16x16x32_bf16 v[92:95], v[168:171], v[202:205], v[92:95]
	v_mfma_f32_16x16x32_bf16 v[68:71], v[160:163], v[210:213], v[68:71]
	v_mfma_f32_16x16x32_bf16 v[76:79], v[168:171], v[210:213], v[76:79]
	v_mfma_f32_16x16x32_bf16 v[120:123], v[164:167], v[190:193], v[120:123]
	v_mfma_f32_16x16x32_bf16 v[124:127], v[172:175], v[190:193], v[124:127]
	v_mfma_f32_16x16x32_bf16 v[104:107], v[164:167], v[198:201], v[104:107]
	v_mfma_f32_16x16x32_bf16 v[108:111], v[172:175], v[198:201], v[108:111]
	v_mfma_f32_16x16x32_bf16 v[88:91], v[164:167], v[206:209], v[88:91]
	v_mfma_f32_16x16x32_bf16 v[92:95], v[172:175], v[206:209], v[92:95]
	v_mfma_f32_16x16x32_bf16 v[68:71], v[164:167], v[214:217], v[68:71]
	v_mfma_f32_16x16x32_bf16 v[76:79], v[172:175], v[214:217], v[76:79]
	s_setprio 0
	s_barrier
	s_add_i32 s65, s56, s44
	v_lshl_add_u64 v[176:177], s[36:37], 0, v[130:131]
	s_mov_b32 m0, s65
	ds_read_b128 v[186:189], v183 offset:16384
	ds_read_b128 v[190:193], v183 offset:17408
	ds_read_b128 v[194:197], v183 offset:18432
	ds_read_b128 v[198:201], v183 offset:19456
	ds_read_b128 v[202:205], v183 offset:20480
	ds_read_b128 v[206:209], v183 offset:21504
	ds_read_b128 v[210:213], v183 offset:22528
	ds_read_b128 v[214:217], v183 offset:23552
	global_load_lds_dwordx4 v[176:177], off
	s_add_i32 m0, s65, 0x2000
	s_add_u32 s66, s36, 0xb0000
	v_lshl_add_u64 v[218:219], s[36:37], 0, v[134:135]
	s_addc_u32 s67, s37, 0
	s_add_i32 s65, s57, s44
	global_load_lds_dwordx4 v[218:219], off
	s_mov_b32 m0, s65
	v_lshl_add_u64 v[222:223], s[40:41], 0, v[132:133]
	global_load_lds_dwordx4 v130, s[66:67]
	s_add_i32 m0, s65, 0x2000
	s_nop 0
	global_load_lds_dwordx4 v134, s[66:67]
	v_lshl_add_u64 v[220:221], s[40:41], 0, v[128:129]
	s_mov_b32 m0, s47
	s_nop 0
	global_load_lds_dwordx4 v[220:221], off
	s_mov_b32 m0, s48
	s_nop 0
	global_load_lds_dwordx4 v[222:223], off
	s_waitcnt vmcnt(8)
	s_waitcnt lgkmcnt(0)
	s_barrier
; #define PG8_STAGE(bufoff, gbase, voff) do { _Pragma("unroll") for (int _i = 0; _i < 2; ++_i) \
;         __builtin_amdgcn_global_load_lds((const unsigned*)((const char*)(gbase) + (voff)[_i]), (PG8_LAS unsigned*)(lds + (bufoff) + ldsw + _i * 8192), 16, 0, 0); } while (0)
; #define PG8_LDA(dst, b, h) do { _Pragma("unroll") for (int m = 0; m < 4; ++m) _Pragma("unroll") for (int k = 0; k < 2; ++k) dst[m][k] = *(const PG8_LAS bf16x8*)(lds + PG8_SA(b, h) + aoff + m * 2048 + k * 1024); } while (0)
; #define PG8_LDB(dst, b, h) do { _Pragma("unroll") for (int n = 0; n < 2; ++n) _Pragma("unroll") for (int k = 0; k < 2; ++k) dst[n][k] = *(const PG8_LAS bf16x8*)(lds + PG8_SB(b, h) + boff + n * 2048 + k * 1024); } while (0)
; #define PG8_MMA(ai, bj, At, Bt) do { __builtin_amdgcn_s_setprio(1); _Pragma("unroll") for (int m = 0; m < 4; ++m) _Pragma("unroll") for (int n = 0; n < 2; ++n) _Pragma("unroll") for (int k = 0; k < 2; ++k) \
;         acc[ai][bj][m][n] = __builtin_amdgcn_mfma_f32_16x16x32_bf16(Bt[n][k], At[m][k], acc[ai][bj][m][n], 0, 0, 0); __builtin_amdgcn_s_setprio(0); } while (0)
; #define PG8_WAIT_V(n) asm volatile("s_waitcnt vmcnt(" #n ")" ::: "memory")
; #define PG8_WAIT_L(n) asm volatile("s_waitcnt lgkmcnt(" #n ")" ::: "memory")
; #define PG8_BAR __builtin_amdgcn_s_barrier()
; #define PG8_SCHED __builtin_amdgcn_sched_barrier(0)
; template <class Epi, class Sched, bool ALIGN_EPI = false, bool SP2 = false>
; __device__ __forceinline__ void gemm_phase(PG8_LAS unsigned char* lds, const Gemm g, const Sched& S, const Epi& E) {
;     ...
;             PG8_WAIT_V(8); PG8_WAIT_L(0); PG8_BAR; PG8_MMA(1, 0, At, B0); PG8_MMA(1, 1, At, B1); PG8_BAR; PG8_SCHED;
;             PG8_LDB(B0, 1, 0); PG8_LDB(B1, 1, 1); PG8_SCHED; PG8_LDA(At, 1, 0); PG8_STAGE(PG8_SA(0, 1), a2 + hstep, voffA);
;             PG8_WAIT_V(8); PG8_WAIT_L(0); PG8_BAR; PG8_MMA(0, 0, At, B0); PG8_MMA(0, 1, At, B1); PG8_BAR; PG8_SCHED;
	s_setprio 1
	s_waitcnt lgkmcnt(0)
	v_mfma_f32_16x16x32_bf16 v[48:51], v[144:147], v[186:189], v[48:51]
	v_mfma_f32_16x16x32_bf16 v[56:59], v[152:155], v[186:189], v[56:59]
	v_mfma_f32_16x16x32_bf16 v[32:35], v[144:147], v[194:197], v[32:35]
	v_mfma_f32_16x16x32_bf16 v[36:39], v[152:155], v[194:197], v[36:39]
	v_mfma_f32_16x16x32_bf16 v[16:19], v[144:147], v[202:205], v[16:19]
	v_mfma_f32_16x16x32_bf16 v[20:23], v[152:155], v[202:205], v[20:23]
	v_mfma_f32_16x16x32_bf16 v[0:3], v[144:147], v[210:213], v[0:3]
	v_mfma_f32_16x16x32_bf16 v[4:7], v[152:155], v[210:213], v[4:7]
	v_mfma_f32_16x16x32_bf16 v[48:51], v[148:151], v[190:193], v[48:51]
	v_mfma_f32_16x16x32_bf16 v[56:59], v[156:159], v[190:193], v[56:59]
	v_mfma_f32_16x16x32_bf16 v[32:35], v[148:151], v[198:201], v[32:35]
	v_mfma_f32_16x16x32_bf16 v[36:39], v[156:159], v[198:201], v[36:39]
	v_mfma_f32_16x16x32_bf16 v[16:19], v[148:151], v[206:209], v[16:19]
	v_mfma_f32_16x16x32_bf16 v[20:23], v[156:159], v[206:209], v[20:23]
	v_mfma_f32_16x16x32_bf16 v[0:3], v[148:151], v[214:217], v[0:3]
	v_mfma_f32_16x16x32_bf16 v[4:7], v[156:159], v[214:217], v[4:7]
	s_setprio 0
	s_setprio 1
	v_mfma_f32_16x16x32_bf16 v[64:67], v[160:163], v[186:189], v[64:67]
	v_mfma_f32_16x16x32_bf16 v[72:75], v[168:171], v[186:189], v[72:75]
	v_mfma_f32_16x16x32_bf16 v[40:43], v[160:163], v[194:197], v[40:43]
	v_mfma_f32_16x16x32_bf16 v[44:47], v[168:171], v[194:197], v[44:47]
	v_mfma_f32_16x16x32_bf16 v[24:27], v[160:163], v[202:205], v[24:27]
	v_mfma_f32_16x16x32_bf16 v[28:31], v[168:171], v[202:205], v[28:31]
	v_mfma_f32_16x16x32_bf16 v[8:11], v[160:163], v[210:213], v[8:11]
	v_mfma_f32_16x16x32_bf16 v[12:15], v[168:171], v[210:213], v[12:15]
	v_mfma_f32_16x16x32_bf16 v[64:67], v[164:167], v[190:193], v[64:67]
	v_mfma_f32_16x16x32_bf16 v[72:75], v[172:175], v[190:193], v[72:75]
	v_mfma_f32_16x16x32_bf16 v[40:43], v[164:167], v[198:201], v[40:43]
	v_mfma_f32_16x16x32_bf16 v[44:47], v[172:175], v[198:201], v[44:47]
	v_mfma_f32_16x16x32_bf16 v[24:27], v[164:167], v[206:209], v[24:27]
	v_mfma_f32_16x16x32_bf16 v[28:31], v[172:175], v[206:209], v[28:31]
	v_mfma_f32_16x16x32_bf16 v[8:11], v[164:167], v[214:217], v[8:11]
	v_mfma_f32_16x16x32_bf16 v[12:15], v[172:175], v[214:217], v[12:15]
	s_setprio 0
	s_barrier
	s_add_i32 s65, 0, 0x18000
	s_add_i32 s66, 0, 0x1c000
	v_add_u32_e32 v156, s65, v181
	v_add_u32_e32 v172, s66, v181
	ds_read_b128 v[144:147], v156
	ds_read_b128 v[148:151], v156 offset:1024
	ds_read_b128 v[152:155], v156 offset:2048
	ds_read_b128 v[156:159], v156 offset:3072
	ds_read_b128 v[160:163], v172
	ds_read_b128 v[164:167], v172 offset:1024
	ds_read_b128 v[168:171], v172 offset:2048
	ds_read_b128 v[172:175], v172 offset:3072
	s_add_u32 s40, s40, 0xb0000
	s_addc_u32 s41, s41, 0
	s_mov_b32 m0, s49
	ds_read_b128 v[186:189], v183 offset:32768
	ds_read_b128 v[190:193], v183 offset:33792
	ds_read_b128 v[194:197], v183 offset:34816
	ds_read_b128 v[198:201], v183 offset:35840
	ds_read_b128 v[202:205], v183 offset:36864
	ds_read_b128 v[206:209], v183 offset:37888
	ds_read_b128 v[210:213], v183 offset:38912
	ds_read_b128 v[214:217], v183 offset:39936
	global_load_lds_dwordx4 v128, s[40:41]
	v_lshl_add_u64 v[224:225], s[40:41], 0, v[132:133]
	s_mov_b32 m0, s50
	s_nop 0
	global_load_lds_dwordx4 v[224:225], off
	s_waitcnt vmcnt(8)
	s_waitcnt lgkmcnt(0)
	s_barrier
	s_setprio 1
	s_waitcnt lgkmcnt(0)
	v_mfma_f32_16x16x32_bf16 v[112:115], v[144:147], v[186:189], v[112:115]
	v_mfma_f32_16x16x32_bf16 v[116:119], v[152:155], v[186:189], v[116:119]
	v_mfma_f32_16x16x32_bf16 v[96:99], v[144:147], v[194:197], v[96:99]
	v_mfma_f32_16x16x32_bf16 v[100:103], v[152:155], v[194:197], v[100:103]
	v_mfma_f32_16x16x32_bf16 v[80:83], v[144:147], v[202:205], v[80:83]
	v_mfma_f32_16x16x32_bf16 v[84:87], v[152:155], v[202:205], v[84:87]
	v_mfma_f32_16x16x32_bf16 v[52:55], v[144:147], v[210:213], v[52:55]
	v_mfma_f32_16x16x32_bf16 v[60:63], v[152:155], v[210:213], v[60:63]
	v_mfma_f32_16x16x32_bf16 v[112:115], v[148:151], v[190:193], v[112:115]
	v_mfma_f32_16x16x32_bf16 v[116:119], v[156:159], v[190:193], v[116:119]
	v_mfma_f32_16x16x32_bf16 v[96:99], v[148:151], v[198:201], v[96:99]
	v_mfma_f32_16x16x32_bf16 v[100:103], v[156:159], v[198:201], v[100:103]
	v_mfma_f32_16x16x32_bf16 v[80:83], v[148:151], v[206:209], v[80:83]
	v_mfma_f32_16x16x32_bf16 v[84:87], v[156:159], v[206:209], v[84:87]
	v_mfma_f32_16x16x32_bf16 v[52:55], v[148:151], v[214:217], v[52:55]
	v_mfma_f32_16x16x32_bf16 v[60:63], v[156:159], v[214:217], v[60:63]
	s_setprio 0
	s_setprio 1
	v_mfma_f32_16x16x32_bf16 v[120:123], v[160:163], v[186:189], v[120:123]
	v_mfma_f32_16x16x32_bf16 v[124:127], v[168:171], v[186:189], v[124:127]
	v_mfma_f32_16x16x32_bf16 v[104:107], v[160:163], v[194:197], v[104:107]
	v_mfma_f32_16x16x32_bf16 v[108:111], v[168:171], v[194:197], v[108:111]
	v_mfma_f32_16x16x32_bf16 v[88:91], v[160:163], v[202:205], v[88:91]
	v_mfma_f32_16x16x32_bf16 v[92:95], v[168:171], v[202:205], v[92:95]
	v_mfma_f32_16x16x32_bf16 v[68:71], v[160:163], v[210:213], v[68:71]
	v_mfma_f32_16x16x32_bf16 v[76:79], v[168:171], v[210:213], v[76:79]
	v_mfma_f32_16x16x32_bf16 v[120:123], v[164:167], v[190:193], v[120:123]
	v_mfma_f32_16x16x32_bf16 v[124:127], v[172:175], v[190:193], v[124:127]
	v_mfma_f32_16x16x32_bf16 v[104:107], v[164:167], v[198:201], v[104:107]
	v_mfma_f32_16x16x32_bf16 v[108:111], v[172:175], v[198:201], v[108:111]
	v_mfma_f32_16x16x32_bf16 v[88:91], v[164:167], v[206:209], v[88:91]
	v_mfma_f32_16x16x32_bf16 v[92:95], v[172:175], v[206:209], v[92:95]
	v_mfma_f32_16x16x32_bf16 v[68:71], v[164:167], v[214:217], v[68:71]
	v_mfma_f32_16x16x32_bf16 v[76:79], v[172:175], v[214:217], v[76:79]
	s_setprio 0
	s_barrier
; #define PG8_STAGE(bufoff, gbase, voff) do { _Pragma("unroll") for (int _i = 0; _i < 2; ++_i) \
;         __builtin_amdgcn_global_load_lds((const unsigned*)((const char*)(gbase) + (voff)[_i]), (PG8_LAS unsigned*)(lds + (bufoff) + ldsw + _i * 8192), 16, 0, 0); } while (0)
; #define PG8_LDA(dst, b, h) do { _Pragma("unroll") for (int m = 0; m < 4; ++m) _Pragma("unroll") for (int k = 0; k < 2; ++k) dst[m][k] = *(const PG8_LAS bf16x8*)(lds + PG8_SA(b, h) + aoff + m * 2048 + k * 1024); } while (0)
; #define PG8_MMA(ai, bj, At, Bt) do { __builtin_amdgcn_s_setprio(1); _Pragma("unroll") for (int m = 0; m < 4; ++m) _Pragma("unroll") for (int n = 0; n < 2; ++n) _Pragma("unroll") for (int k = 0; k < 2; ++k) \
;         acc[ai][bj][m][n] = __builtin_amdgcn_mfma_f32_16x16x32_bf16(Bt[n][k], At[m][k], acc[ai][bj][m][n], 0, 0, 0); __builtin_amdgcn_s_setprio(0); } while (0)
; #define PG8_WAIT_V(n) asm volatile("s_waitcnt vmcnt(" #n ")" ::: "memory")
; #define PG8_WAIT_L(n) asm volatile("s_waitcnt lgkmcnt(" #n ")" ::: "memory")
; #define PG8_BAR __builtin_amdgcn_s_barrier()
; #define PG8_SCHED __builtin_amdgcn_sched_barrier(0)
; template <class Epi, class Sched, bool ALIGN_EPI = false, bool SP2 = false>
; __device__ __forceinline__ void gemm_phase(PG8_LAS unsigned char* lds, const Gemm g, const Sched& S, const Epi& E) {
;     ...
;         for (int t = 0; t < nt; t += 2) {
;     ...
;             PG8_WAIT_V(8); PG8_WAIT_L(0); PG8_BAR; PG8_MMA(0, 0, At, B0); PG8_MMA(0, 1, At, B1); PG8_BAR; PG8_SCHED;
;             PG8_LDA(At, 1, 1); PG8_STAGE(PG8_SB(1, 0), b3, voffB); PG8_STAGE(PG8_SB(1, 1), b3 + hstep, voffB); PG8_STAGE(PG8_SA(1, 0), a3, voffA);
;             PG8_WAIT_V(8); PG8_WAIT_L(0); PG8_BAR; PG8_MMA(1, 0, At, B0); PG8_MMA(1, 1, At, B1); PG8_BAR; PG8_SCHED;
	s_add_i32 s40, s65, s44
	v_lshl_add_u64 v[176:177], v[176:177], 0, s[28:29]
	s_mov_b32 m0, s40
	ds_read_b128 v[186:189], v183 offset:49152
	ds_read_b128 v[190:193], v183 offset:50176
	ds_read_b128 v[194:197], v183 offset:51200
	ds_read_b128 v[198:201], v183 offset:52224
	ds_read_b128 v[202:205], v183 offset:53248
	ds_read_b128 v[206:209], v183 offset:54272
	ds_read_b128 v[210:213], v183 offset:55296
	ds_read_b128 v[214:217], v183 offset:56320
	global_load_lds_dwordx4 v[176:177], off
	s_add_i32 m0, s40, 0x2000
	s_add_u32 s36, s36, 0xb0080
	v_lshl_add_u64 v[176:177], v[218:219], 0, s[28:29]
	s_addc_u32 s37, s37, 0
	s_add_i32 s40, s66, s44
	global_load_lds_dwordx4 v[176:177], off
	s_mov_b32 m0, s40
	s_nop 0
	global_load_lds_dwordx4 v130, s[36:37]
	s_add_i32 m0, s40, 0x2000
	s_nop 0
	global_load_lds_dwordx4 v134, s[36:37]
	v_lshl_add_u64 v[176:177], v[220:221], 0, s[28:29]
	s_mov_b32 m0, s51
	s_nop 0
	global_load_lds_dwordx4 v[176:177], off
	v_lshl_add_u64 v[176:177], v[222:223], 0, s[28:29]
	s_mov_b32 m0, s52
	s_nop 0
	global_load_lds_dwordx4 v[176:177], off
	s_waitcnt vmcnt(8)
	s_waitcnt lgkmcnt(0)
	s_barrier
	s_setprio 1
	s_waitcnt lgkmcnt(0)
	v_mfma_f32_16x16x32_bf16 v[48:51], v[144:147], v[186:189], v[48:51]
	v_mfma_f32_16x16x32_bf16 v[56:59], v[152:155], v[186:189], v[56:59]
	v_mfma_f32_16x16x32_bf16 v[32:35], v[144:147], v[194:197], v[32:35]
	v_mfma_f32_16x16x32_bf16 v[36:39], v[152:155], v[194:197], v[36:39]
	v_mfma_f32_16x16x32_bf16 v[16:19], v[144:147], v[202:205], v[16:19]
	v_mfma_f32_16x16x32_bf16 v[20:23], v[152:155], v[202:205], v[20:23]
	v_mfma_f32_16x16x32_bf16 v[0:3], v[144:147], v[210:213], v[0:3]
	v_mfma_f32_16x16x32_bf16 v[4:7], v[152:155], v[210:213], v[4:7]
	v_mfma_f32_16x16x32_bf16 v[48:51], v[148:151], v[190:193], v[48:51]
	v_mfma_f32_16x16x32_bf16 v[56:59], v[156:159], v[190:193], v[56:59]
	v_mfma_f32_16x16x32_bf16 v[32:35], v[148:151], v[198:201], v[32:35]
	v_mfma_f32_16x16x32_bf16 v[36:39], v[156:159], v[198:201], v[36:39]
	v_mfma_f32_16x16x32_bf16 v[16:19], v[148:151], v[206:209], v[16:19]
	v_mfma_f32_16x16x32_bf16 v[20:23], v[156:159], v[206:209], v[20:23]
	v_mfma_f32_16x16x32_bf16 v[0:3], v[148:151], v[214:217], v[0:3]
	v_mfma_f32_16x16x32_bf16 v[4:7], v[156:159], v[214:217], v[4:7]
	s_setprio 0
	s_setprio 1
	v_mfma_f32_16x16x32_bf16 v[64:67], v[160:163], v[186:189], v[64:67]
	v_mfma_f32_16x16x32_bf16 v[72:75], v[168:171], v[186:189], v[72:75]
	v_mfma_f32_16x16x32_bf16 v[40:43], v[160:163], v[194:197], v[40:43]
	v_mfma_f32_16x16x32_bf16 v[44:47], v[168:171], v[194:197], v[44:47]
	v_mfma_f32_16x16x32_bf16 v[24:27], v[160:163], v[202:205], v[24:27]
	v_mfma_f32_16x16x32_bf16 v[28:31], v[168:171], v[202:205], v[28:31]
	v_mfma_f32_16x16x32_bf16 v[8:11], v[160:163], v[210:213], v[8:11]
	v_mfma_f32_16x16x32_bf16 v[12:15], v[168:171], v[210:213], v[12:15]
	v_mfma_f32_16x16x32_bf16 v[64:67], v[164:167], v[190:193], v[64:67]
	v_mfma_f32_16x16x32_bf16 v[72:75], v[172:175], v[190:193], v[72:75]
	v_mfma_f32_16x16x32_bf16 v[40:43], v[164:167], v[198:201], v[40:43]
	v_mfma_f32_16x16x32_bf16 v[44:47], v[172:175], v[198:201], v[44:47]
	v_mfma_f32_16x16x32_bf16 v[24:27], v[164:167], v[206:209], v[24:27]
	v_mfma_f32_16x16x32_bf16 v[28:31], v[172:175], v[206:209], v[28:31]
	v_mfma_f32_16x16x32_bf16 v[8:11], v[164:167], v[214:217], v[8:11]
	v_mfma_f32_16x16x32_bf16 v[12:15], v[172:175], v[214:217], v[12:15]
	s_setprio 0
	s_barrier
	s_add_i32 s64, s64, 2
	s_add_u32 s38, s38, 0x100
	s_addc_u32 s39, s39, 0
	s_add_u32 s62, s62, 0x100
	s_addc_u32 s63, s63, 0
	s_cmp_gt_u32 s64, 41
	s_cbranch_scc0 .LBB0_405
	s_and_b64 vcc, exec, s[30:31]
	s_cbranch_vccz .LBB0_408
	s_barrier

; #define PG8_STAGE(bufoff, gbase, voff) do { _Pragma("unroll") for (int _i = 0; _i < 2; ++_i) \
;         __builtin_amdgcn_global_load_lds((const unsigned*)((const char*)(gbase) + (voff)[_i]), (PG8_LAS unsigned*)(lds + (bufoff) + ldsw + _i * 8192), 16, 0, 0); } while (0)
; #define PG8_LDA(dst, b, h) do { _Pragma("unroll") for (int m = 0; m < 4; ++m) _Pragma("unroll") for (int k = 0; k < 2; ++k) dst[m][k] = *(const PG8_LAS bf16x8*)(lds + PG8_SA(b, h) + aoff + m * 2048 + k * 1024); } while (0)
; #define PG8_LDB(dst, b, h) do { _Pragma("unroll") for (int n = 0; n < 2; ++n) _Pragma("unroll") for (int k = 0; k < 2; ++k) dst[n][k] = *(const PG8_LAS bf16x8*)(lds + PG8_SB(b, h) + boff + n * 2048 + k * 1024); } while (0)
; #define PG8_MMA(ai, bj, At, Bt) do { __builtin_amdgcn_s_setprio(1); _Pragma("unroll") for (int m = 0; m < 4; ++m) _Pragma("unroll") for (int n = 0; n < 2; ++n) _Pragma("unroll") for (int k = 0; k < 2; ++k) \
;         acc[ai][bj][m][n] = __builtin_amdgcn_mfma_f32_16x16x32_bf16(Bt[n][k], At[m][k], acc[ai][bj][m][n], 0, 0, 0); __builtin_amdgcn_s_setprio(0); } while (0)
; #define PG8_BAR __builtin_amdgcn_s_barrier()
; template <class Epi, class Sched, bool ALIGN_EPI = false, bool SP2 = false>
; __device__ __forceinline__ void gemm_phase(PG8_LAS unsigned char* lds, const Gemm g, const Sched& S, const Epi& E) {
;     ...
;         const bool has_next = S.next(ui + 1, nxt);
;         const char* nA = has_next ? (const char*)g.A + (size_t)nxt.pm * tstep : cA; const char* nB = has_next ? (const char*)g.Bt + (size_t)nxt.pn * tstep : cB;
;         for (int t = 0; t < nt; t += 2) {
;             const bool last = (t == nt - 2);
;             const char* a1 = cA + (size_t)(t + 1) * kstep;
;             const char* a2 = last ? nA : cA + (size_t)(t + 2) * kstep; const char* b2 = last ? nB : cB + (size_t)(t + 2) * kstep;
;             const char* a3 = a2 + kstep; const char* b3 = b2 + kstep;
;             if (last && has_next) S.a_ready(nxt);
;             if constexpr (SP2) {
;             PG8_LDB(B0, 0, 0); PG8_LDB(B1, 0, 1); PG8_SCHED; PG8_LDA(At, 0, 0); PG8_STAGE(PG8_SA(1, 1), a1 + hstep, voffA);
;             PG8_WAIT_V(8); PG8_WAIT_L(0); PG8_BAR; PG8_MMA(0, 0, At, B0); PG8_MMA(0, 1, At, B1); PG8_BAR; PG8_SCHED;
;             PG8_LDA(At, 0, 1); PG8_STAGE(PG8_SB(0, 0), b2, voffB); PG8_STAGE(PG8_SB(0, 1), b2 + hstep, voffB); PG8_STAGE(PG8_SA(0, 0), a2, voffA);
.LBB0_505:
	s_ashr_i32 s27, s26, 31
	s_lshl_b64 s[4:5], s[26:27], 19
	s_add_u32 s28, s80, s4
	s_addc_u32 s29, s81, s5
	s_and_b64 s[4:5], s[0:1], exec
	s_cselect_b32 s9, s29, s37
	s_cselect_b32 s27, s28, s36
	s_ashr_i32 s25, s24, 31
	s_lshl_b64 s[4:5], s[24:25], 19
	s_add_u32 s30, s2, s4
	s_addc_u32 s31, s3, s5
	s_and_b64 s[4:5], s[0:1], exec
	s_cselect_b32 s25, s31, s35
	s_cselect_b32 s56, s30, s34
	s_add_u32 s4, s36, 0x40080
	s_addc_u32 s5, s37, 0
	s_add_u32 s57, s34, 0x100
	s_addc_u32 s58, s35, 0
	s_mov_b32 s59, -2
	ds_read_b128 v[128:131], v181
	ds_read_b128 v[132:135], v181 offset:1024
	ds_read_b128 v[136:139], v181 offset:2048
	ds_read_b128 v[140:143], v181 offset:3072
	s_waitcnt lgkmcnt(0)
	ds_read_b128 v[162:165], v182
	ds_read_b128 v[166:169], v182 offset:1024
	ds_read_b128 v[170:173], v182 offset:2048
	ds_read_b128 v[188:191], v182 offset:3072
	s_add_u32 s34, s4, 0xfffc0080
	s_addc_u32 s35, s5, -1
	s_cmp_eq_u32 s59, 12
	s_cselect_b32 s37, s9, s35
	s_cselect_b32 s36, s27, s34
	s_cselect_b32 s35, s25, s58
	s_cselect_b32 s34, s56, s57
	s_add_i32 m0, s38, 0xc000
	ds_read_b128 v[192:195], v183
	ds_read_b128 v[196:199], v183 offset:1024
	ds_read_b128 v[200:203], v183 offset:2048
	ds_read_b128 v[204:207], v183 offset:3072
	ds_read_b128 v[208:211], v183 offset:4096
	ds_read_b128 v[212:215], v183 offset:5120
	ds_read_b128 v[216:219], v183 offset:6144
	ds_read_b128 v[220:223], v183 offset:7168
	global_load_lds_dwordx4 v154, s[4:5]
	s_add_i32 m0, s38, 0xe000
	s_nop 0
	global_load_lds_dwordx4 v156, s[4:5]
	s_waitcnt vmcnt(8)
	s_waitcnt lgkmcnt(0)
	s_barrier
	s_setprio 1
	s_waitcnt lgkmcnt(0)
	v_mfma_f32_16x16x32_bf16 v[124:127], v[128:131], v[192:195], 0
	v_mfma_f32_16x16x32_bf16 v[120:123], v[136:139], v[192:195], 0
	v_mfma_f32_16x16x32_bf16 v[108:111], v[128:131], v[200:203], 0
	v_mfma_f32_16x16x32_bf16 v[104:107], v[136:139], v[200:203], 0
	v_mfma_f32_16x16x32_bf16 v[92:95], v[128:131], v[208:211], 0
	v_mfma_f32_16x16x32_bf16 v[88:91], v[136:139], v[208:211], 0
	v_mfma_f32_16x16x32_bf16 v[76:79], v[128:131], v[216:219], 0
	v_mfma_f32_16x16x32_bf16 v[72:75], v[136:139], v[216:219], 0
	v_mfma_f32_16x16x32_bf16 v[124:127], v[132:135], v[196:199], v[124:127]
	v_mfma_f32_16x16x32_bf16 v[120:123], v[140:143], v[196:199], v[120:123]
	v_mfma_f32_16x16x32_bf16 v[108:111], v[132:135], v[204:207], v[108:111]
	v_mfma_f32_16x16x32_bf16 v[104:107], v[140:143], v[204:207], v[104:107]
	v_mfma_f32_16x16x32_bf16 v[92:95], v[132:135], v[212:215], v[92:95]
	v_mfma_f32_16x16x32_bf16 v[88:91], v[140:143], v[212:215], v[88:91]
	v_mfma_f32_16x16x32_bf16 v[76:79], v[132:135], v[220:223], v[76:79]
	v_mfma_f32_16x16x32_bf16 v[72:75], v[140:143], v[220:223], v[72:75]
	s_setprio 0
	s_setprio 1
	v_mfma_f32_16x16x32_bf16 v[116:119], v[162:165], v[192:195], 0
	v_mfma_f32_16x16x32_bf16 v[112:115], v[170:173], v[192:195], 0
	v_mfma_f32_16x16x32_bf16 v[100:103], v[162:165], v[200:203], 0
	v_mfma_f32_16x16x32_bf16 v[96:99], v[170:173], v[200:203], 0
	v_mfma_f32_16x16x32_bf16 v[84:87], v[162:165], v[208:211], 0
	v_mfma_f32_16x16x32_bf16 v[80:83], v[170:173], v[208:211], 0
	v_mfma_f32_16x16x32_bf16 v[68:71], v[162:165], v[216:219], 0
	v_mfma_f32_16x16x32_bf16 v[64:67], v[170:173], v[216:219], 0
	v_mfma_f32_16x16x32_bf16 v[116:119], v[166:169], v[196:199], v[116:119]
	v_mfma_f32_16x16x32_bf16 v[112:115], v[188:191], v[196:199], v[112:115]
	v_mfma_f32_16x16x32_bf16 v[100:103], v[166:169], v[204:207], v[100:103]
	v_mfma_f32_16x16x32_bf16 v[96:99], v[188:191], v[204:207], v[96:99]
	v_mfma_f32_16x16x32_bf16 v[84:87], v[166:169], v[212:215], v[84:87]
	v_mfma_f32_16x16x32_bf16 v[80:83], v[188:191], v[212:215], v[80:83]
	v_mfma_f32_16x16x32_bf16 v[68:71], v[166:169], v[220:223], v[68:71]
	v_mfma_f32_16x16x32_bf16 v[64:67], v[188:191], v[220:223], v[64:67]
	s_setprio 0
	s_barrier
	s_add_i32 s60, s48, s33
	v_lshl_add_u64 v[224:225], s[34:35], 0, v[146:147]
	s_mov_b32 m0, s60
	ds_read_b128 v[192:195], v183 offset:16384
	ds_read_b128 v[196:199], v183 offset:17408
	ds_read_b128 v[200:203], v183 offset:18432
	ds_read_b128 v[204:207], v183 offset:19456
	ds_read_b128 v[208:211], v183 offset:20480
	ds_read_b128 v[212:215], v183 offset:21504
	ds_read_b128 v[216:219], v183 offset:22528
	ds_read_b128 v[220:223], v183 offset:23552
	global_load_lds_dwordx4 v[224:225], off
	s_add_i32 m0, s60, 0x2000
	s_add_u32 s60, s34, 0x40000
	v_lshl_add_u64 v[226:227], s[34:35], 0, v[150:151]
	s_addc_u32 s61, s35, 0
	s_add_i32 s62, s49, s33
	global_load_lds_dwordx4 v[226:227], off
	s_mov_b32 m0, s62
	v_lshl_add_u64 v[230:231], s[36:37], 0, v[148:149]
	global_load_lds_dwordx4 v146, s[60:61]
	s_add_i32 m0, s62, 0x2000
	s_nop 0
	global_load_lds_dwordx4 v150, s[60:61]
	v_lshl_add_u64 v[228:229], s[36:37], 0, v[144:145]
	s_mov_b32 m0, s38
	s_nop 0
	global_load_lds_dwordx4 v[228:229], off
	s_mov_b32 m0, s39
	s_nop 0
	global_load_lds_dwordx4 v[230:231], off
	s_waitcnt vmcnt(8)
	s_waitcnt lgkmcnt(0)
	s_barrier
; #define PG8_STAGE(bufoff, gbase, voff) do { _Pragma("unroll") for (int _i = 0; _i < 2; ++_i) \
;         __builtin_amdgcn_global_load_lds((const unsigned*)((const char*)(gbase) + (voff)[_i]), (PG8_LAS unsigned*)(lds + (bufoff) + ldsw + _i * 8192), 16, 0, 0); } while (0)
; #define PG8_LDA(dst, b, h) do { _Pragma("unroll") for (int m = 0; m < 4; ++m) _Pragma("unroll") for (int k = 0; k < 2; ++k) dst[m][k] = *(const PG8_LAS bf16x8*)(lds + PG8_SA(b, h) + aoff + m * 2048 + k * 1024); } while (0)
; #define PG8_LDB(dst, b, h) do { _Pragma("unroll") for (int n = 0; n < 2; ++n) _Pragma("unroll") for (int k = 0; k < 2; ++k) dst[n][k] = *(const PG8_LAS bf16x8*)(lds + PG8_SB(b, h) + boff + n * 2048 + k * 1024); } while (0)
; #define PG8_MMA(ai, bj, At, Bt) do { __builtin_amdgcn_s_setprio(1); _Pragma("unroll") for (int m = 0; m < 4; ++m) _Pragma("unroll") for (int n = 0; n < 2; ++n) _Pragma("unroll") for (int k = 0; k < 2; ++k) \
;         acc[ai][bj][m][n] = __builtin_amdgcn_mfma_f32_16x16x32_bf16(Bt[n][k], At[m][k], acc[ai][bj][m][n], 0, 0, 0); __builtin_amdgcn_s_setprio(0); } while (0)
; #define PG8_WAIT_V(n) asm volatile("s_waitcnt vmcnt(" #n ")" ::: "memory")
; #define PG8_WAIT_L(n) asm volatile("s_waitcnt lgkmcnt(" #n ")" ::: "memory")
; #define PG8_BAR __builtin_amdgcn_s_barrier()
; #define PG8_SCHED __builtin_amdgcn_sched_barrier(0)
; template <class Epi, class Sched, bool ALIGN_EPI = false, bool SP2 = false>
; __device__ __forceinline__ void gemm_phase(PG8_LAS unsigned char* lds, const Gemm g, const Sched& S, const Epi& E) {
;     ...
;             PG8_WAIT_V(8); PG8_WAIT_L(0); PG8_BAR; PG8_MMA(0, 0, At, B0); PG8_MMA(0, 1, At, B1); PG8_BAR; PG8_SCHED;
;             PG8_LDA(At, 0, 1); PG8_STAGE(PG8_SB(0, 0), b2, voffB); PG8_STAGE(PG8_SB(0, 1), b2 + hstep, voffB); PG8_STAGE(PG8_SA(0, 0), a2, voffA);
;             PG8_WAIT_V(8); PG8_WAIT_L(0); PG8_BAR; PG8_MMA(1, 0, At, B0); PG8_MMA(1, 1, At, B1); PG8_BAR; PG8_SCHED;
;             PG8_LDB(B0, 1, 0); PG8_LDB(B1, 1, 1); PG8_SCHED; PG8_LDA(At, 1, 0); PG8_STAGE(PG8_SA(0, 1), a2 + hstep, voffA);
	s_setprio 1
	s_waitcnt lgkmcnt(0)
	v_mfma_f32_16x16x32_bf16 v[60:63], v[128:131], v[192:195], 0
	v_mfma_f32_16x16x32_bf16 v[56:59], v[136:139], v[192:195], 0
	v_mfma_f32_16x16x32_bf16 v[44:47], v[128:131], v[200:203], 0
	v_mfma_f32_16x16x32_bf16 v[40:43], v[136:139], v[200:203], 0
	v_mfma_f32_16x16x32_bf16 v[28:31], v[128:131], v[208:211], 0
	v_mfma_f32_16x16x32_bf16 v[24:27], v[136:139], v[208:211], 0
	v_mfma_f32_16x16x32_bf16 v[12:15], v[128:131], v[216:219], 0
	v_mfma_f32_16x16x32_bf16 v[8:11], v[136:139], v[216:219], 0
	v_mfma_f32_16x16x32_bf16 v[60:63], v[132:135], v[196:199], v[60:63]
	v_mfma_f32_16x16x32_bf16 v[56:59], v[140:143], v[196:199], v[56:59]
	v_mfma_f32_16x16x32_bf16 v[44:47], v[132:135], v[204:207], v[44:47]
	v_mfma_f32_16x16x32_bf16 v[40:43], v[140:143], v[204:207], v[40:43]
	v_mfma_f32_16x16x32_bf16 v[28:31], v[132:135], v[212:215], v[28:31]
	v_mfma_f32_16x16x32_bf16 v[24:27], v[140:143], v[212:215], v[24:27]
	v_mfma_f32_16x16x32_bf16 v[12:15], v[132:135], v[220:223], v[12:15]
	v_mfma_f32_16x16x32_bf16 v[8:11], v[140:143], v[220:223], v[8:11]
	s_setprio 0
	s_setprio 1
	v_mfma_f32_16x16x32_bf16 v[52:55], v[162:165], v[192:195], 0
	v_mfma_f32_16x16x32_bf16 v[48:51], v[170:173], v[192:195], 0
	v_mfma_f32_16x16x32_bf16 v[36:39], v[162:165], v[200:203], 0
	v_mfma_f32_16x16x32_bf16 v[32:35], v[170:173], v[200:203], 0
	v_mfma_f32_16x16x32_bf16 v[20:23], v[162:165], v[208:211], 0
	v_mfma_f32_16x16x32_bf16 v[16:19], v[170:173], v[208:211], 0
	v_mfma_f32_16x16x32_bf16 v[4:7], v[162:165], v[216:219], 0
	v_mfma_f32_16x16x32_bf16 v[0:3], v[170:173], v[216:219], 0
	v_mfma_f32_16x16x32_bf16 v[52:55], v[166:169], v[196:199], v[52:55]
	v_mfma_f32_16x16x32_bf16 v[48:51], v[188:191], v[196:199], v[48:51]
	v_mfma_f32_16x16x32_bf16 v[36:39], v[166:169], v[204:207], v[36:39]
	v_mfma_f32_16x16x32_bf16 v[32:35], v[188:191], v[204:207], v[32:35]
	v_mfma_f32_16x16x32_bf16 v[20:23], v[166:169], v[212:215], v[20:23]
	v_mfma_f32_16x16x32_bf16 v[16:19], v[188:191], v[212:215], v[16:19]
	v_mfma_f32_16x16x32_bf16 v[4:7], v[166:169], v[220:223], v[4:7]
	v_mfma_f32_16x16x32_bf16 v[0:3], v[188:191], v[220:223], v[0:3]
	s_setprio 0
	s_barrier
	s_add_i32 s60, 0, 0x18000
	s_add_i32 s61, 0, 0x1c000
	v_add_u32_e32 v140, s60, v175
	v_add_u32_e32 v187, s61, v175
	ds_read_b128 v[128:131], v140
	ds_read_b128 v[132:135], v140 offset:1024
	ds_read_b128 v[136:139], v140 offset:2048
	ds_read_b128 v[140:143], v140 offset:3072
	ds_read_b128 v[162:165], v187
	ds_read_b128 v[166:169], v187 offset:1024
	ds_read_b128 v[170:173], v187 offset:2048
	ds_read_b128 v[188:191], v187 offset:3072
	s_add_u32 s36, s36, 0x40000
	s_addc_u32 s37, s37, 0
	s_mov_b32 m0, s40
	ds_read_b128 v[192:195], v183 offset:32768
	ds_read_b128 v[196:199], v183 offset:33792
	ds_read_b128 v[200:203], v183 offset:34816
	ds_read_b128 v[204:207], v183 offset:35840
	ds_read_b128 v[208:211], v183 offset:36864
	ds_read_b128 v[212:215], v183 offset:37888
	ds_read_b128 v[216:219], v183 offset:38912
	ds_read_b128 v[220:223], v183 offset:39936
	global_load_lds_dwordx4 v144, s[36:37]
	v_lshl_add_u64 v[232:233], s[36:37], 0, v[148:149]
	s_mov_b32 m0, s41
	s_nop 0
	global_load_lds_dwordx4 v[232:233], off
	s_waitcnt vmcnt(8)
	s_waitcnt lgkmcnt(0)
	s_barrier
	s_setprio 1
	s_waitcnt lgkmcnt(0)
	v_mfma_f32_16x16x32_bf16 v[124:127], v[128:131], v[192:195], v[124:127]
	v_mfma_f32_16x16x32_bf16 v[120:123], v[136:139], v[192:195], v[120:123]
	v_mfma_f32_16x16x32_bf16 v[108:111], v[128:131], v[200:203], v[108:111]
	v_mfma_f32_16x16x32_bf16 v[104:107], v[136:139], v[200:203], v[104:107]
	v_mfma_f32_16x16x32_bf16 v[92:95], v[128:131], v[208:211], v[92:95]
	v_mfma_f32_16x16x32_bf16 v[88:91], v[136:139], v[208:211], v[88:91]
	v_mfma_f32_16x16x32_bf16 v[76:79], v[128:131], v[216:219], v[76:79]
	v_mfma_f32_16x16x32_bf16 v[72:75], v[136:139], v[216:219], v[72:75]
	v_mfma_f32_16x16x32_bf16 v[124:127], v[132:135], v[196:199], v[124:127]
	v_mfma_f32_16x16x32_bf16 v[120:123], v[140:143], v[196:199], v[120:123]
	v_mfma_f32_16x16x32_bf16 v[108:111], v[132:135], v[204:207], v[108:111]
	v_mfma_f32_16x16x32_bf16 v[104:107], v[140:143], v[204:207], v[104:107]
	v_mfma_f32_16x16x32_bf16 v[92:95], v[132:135], v[212:215], v[92:95]
	v_mfma_f32_16x16x32_bf16 v[88:91], v[140:143], v[212:215], v[88:91]
	v_mfma_f32_16x16x32_bf16 v[76:79], v[132:135], v[220:223], v[76:79]
	v_mfma_f32_16x16x32_bf16 v[72:75], v[140:143], v[220:223], v[72:75]
	s_setprio 0
	s_setprio 1
	v_mfma_f32_16x16x32_bf16 v[116:119], v[162:165], v[192:195], v[116:119]
	v_mfma_f32_16x16x32_bf16 v[112:115], v[170:173], v[192:195], v[112:115]
	v_mfma_f32_16x16x32_bf16 v[100:103], v[162:165], v[200:203], v[100:103]
	v_mfma_f32_16x16x32_bf16 v[96:99], v[170:173], v[200:203], v[96:99]
	v_mfma_f32_16x16x32_bf16 v[84:87], v[162:165], v[208:211], v[84:87]
	v_mfma_f32_16x16x32_bf16 v[80:83], v[170:173], v[208:211], v[80:83]
	v_mfma_f32_16x16x32_bf16 v[68:71], v[162:165], v[216:219], v[68:71]
	v_mfma_f32_16x16x32_bf16 v[64:67], v[170:173], v[216:219], v[64:67]
	v_mfma_f32_16x16x32_bf16 v[116:119], v[166:169], v[196:199], v[116:119]
	v_mfma_f32_16x16x32_bf16 v[112:115], v[188:191], v[196:199], v[112:115]
	v_mfma_f32_16x16x32_bf16 v[100:103], v[166:169], v[204:207], v[100:103]
	v_mfma_f32_16x16x32_bf16 v[96:99], v[188:191], v[204:207], v[96:99]
	v_mfma_f32_16x16x32_bf16 v[84:87], v[166:169], v[212:215], v[84:87]
	v_mfma_f32_16x16x32_bf16 v[80:83], v[188:191], v[212:215], v[80:83]
	v_mfma_f32_16x16x32_bf16 v[68:71], v[166:169], v[220:223], v[68:71]
	v_mfma_f32_16x16x32_bf16 v[64:67], v[188:191], v[220:223], v[64:67]
	s_setprio 0
	s_barrier
; #define PG8_STAGE(bufoff, gbase, voff) do { _Pragma("unroll") for (int _i = 0; _i < 2; ++_i) \
;         __builtin_amdgcn_global_load_lds((const unsigned*)((const char*)(gbase) + (voff)[_i]), (PG8_LAS unsigned*)(lds + (bufoff) + ldsw + _i * 8192), 16, 0, 0); } while (0)
; #define PG8_LDA(dst, b, h) do { _Pragma("unroll") for (int m = 0; m < 4; ++m) _Pragma("unroll") for (int k = 0; k < 2; ++k) dst[m][k] = *(const PG8_LAS bf16x8*)(lds + PG8_SA(b, h) + aoff + m * 2048 + k * 1024); } while (0)
; #define PG8_LDB(dst, b, h) do { _Pragma("unroll") for (int n = 0; n < 2; ++n) _Pragma("unroll") for (int k = 0; k < 2; ++k) dst[n][k] = *(const PG8_LAS bf16x8*)(lds + PG8_SB(b, h) + boff + n * 2048 + k * 1024); } while (0)
; #define PG8_MMA(ai, bj, At, Bt) do { __builtin_amdgcn_s_setprio(1); _Pragma("unroll") for (int m = 0; m < 4; ++m) _Pragma("unroll") for (int n = 0; n < 2; ++n) _Pragma("unroll") for (int k = 0; k < 2; ++k) \
;         acc[ai][bj][m][n] = __builtin_amdgcn_mfma_f32_16x16x32_bf16(Bt[n][k], At[m][k], acc[ai][bj][m][n], 0, 0, 0); __builtin_amdgcn_s_setprio(0); } while (0)
; #define PG8_WAIT_V(n) asm volatile("s_waitcnt vmcnt(" #n ")" ::: "memory")
; #define PG8_WAIT_L(n) asm volatile("s_waitcnt lgkmcnt(" #n ")" ::: "memory")
; #define PG8_BAR __builtin_amdgcn_s_barrier()
; #define PG8_SCHED __builtin_amdgcn_sched_barrier(0)
; template <class Epi, class Sched, bool ALIGN_EPI = false, bool SP2 = false>
; __device__ __forceinline__ void gemm_phase(PG8_LAS unsigned char* lds, const Gemm g, const Sched& S, const Epi& E) {
;     ...
;             PG8_LDB(B0, 0, 0); PG8_LDB(B1, 0, 1); PG8_SCHED; PG8_LDA(At, 0, 0); PG8_STAGE(PG8_SA(1, 1), a1 + hstep, voffA);
;     ...
;             PG8_WAIT_V(8); PG8_WAIT_L(0); PG8_BAR; PG8_MMA(0, 0, At, B0); PG8_MMA(0, 1, At, B1); PG8_BAR; PG8_SCHED;
;             PG8_LDA(At, 1, 1); PG8_STAGE(PG8_SB(1, 0), b3, voffB); PG8_STAGE(PG8_SB(1, 1), b3 + hstep, voffB); PG8_STAGE(PG8_SA(1, 0), a3, voffA);
;             PG8_WAIT_V(8); PG8_WAIT_L(0); PG8_BAR; PG8_MMA(1, 0, At, B0); PG8_MMA(1, 1, At, B1); PG8_BAR; PG8_SCHED;
	s_add_i32 s36, s60, s33
	v_lshl_add_u64 v[224:225], v[224:225], 0, s[16:17]
	s_mov_b32 m0, s36
	ds_read_b128 v[192:195], v183 offset:49152
	ds_read_b128 v[196:199], v183 offset:50176
	ds_read_b128 v[200:203], v183 offset:51200
	ds_read_b128 v[204:207], v183 offset:52224
	ds_read_b128 v[208:211], v183 offset:53248
	ds_read_b128 v[212:215], v183 offset:54272
	ds_read_b128 v[216:219], v183 offset:55296
	ds_read_b128 v[220:223], v183 offset:56320
	global_load_lds_dwordx4 v[224:225], off
	s_add_i32 m0, s36, 0x2000
	s_add_u32 s34, s34, 0x40080
	v_lshl_add_u64 v[224:225], v[226:227], 0, s[16:17]
	s_addc_u32 s35, s35, 0
	s_add_i32 s36, s61, s33
	global_load_lds_dwordx4 v[224:225], off
	s_mov_b32 m0, s36
	s_nop 0
	global_load_lds_dwordx4 v146, s[34:35]
	s_add_i32 m0, s36, 0x2000
	s_nop 0
	global_load_lds_dwordx4 v150, s[34:35]
	v_lshl_add_u64 v[224:225], v[228:229], 0, s[16:17]
	s_mov_b32 m0, s46
	s_nop 0
	global_load_lds_dwordx4 v[224:225], off
	v_lshl_add_u64 v[224:225], v[230:231], 0, s[16:17]
	s_mov_b32 m0, s47
	s_nop 0
	global_load_lds_dwordx4 v[224:225], off
	s_waitcnt vmcnt(8)
	s_waitcnt lgkmcnt(0)
	s_barrier
	s_setprio 1
	s_waitcnt lgkmcnt(0)
	v_mfma_f32_16x16x32_bf16 v[60:63], v[128:131], v[192:195], v[60:63]
	v_mfma_f32_16x16x32_bf16 v[56:59], v[136:139], v[192:195], v[56:59]
	v_mfma_f32_16x16x32_bf16 v[44:47], v[128:131], v[200:203], v[44:47]
	v_mfma_f32_16x16x32_bf16 v[40:43], v[136:139], v[200:203], v[40:43]
	v_mfma_f32_16x16x32_bf16 v[28:31], v[128:131], v[208:211], v[28:31]
	v_mfma_f32_16x16x32_bf16 v[24:27], v[136:139], v[208:211], v[24:27]
	v_mfma_f32_16x16x32_bf16 v[12:15], v[128:131], v[216:219], v[12:15]
	v_mfma_f32_16x16x32_bf16 v[8:11], v[136:139], v[216:219], v[8:11]
	v_mfma_f32_16x16x32_bf16 v[60:63], v[132:135], v[196:199], v[60:63]
	v_mfma_f32_16x16x32_bf16 v[56:59], v[140:143], v[196:199], v[56:59]
	v_mfma_f32_16x16x32_bf16 v[44:47], v[132:135], v[204:207], v[44:47]
	v_mfma_f32_16x16x32_bf16 v[40:43], v[140:143], v[204:207], v[40:43]
	v_mfma_f32_16x16x32_bf16 v[28:31], v[132:135], v[212:215], v[28:31]
	v_mfma_f32_16x16x32_bf16 v[24:27], v[140:143], v[212:215], v[24:27]
	v_mfma_f32_16x16x32_bf16 v[12:15], v[132:135], v[220:223], v[12:15]
	v_mfma_f32_16x16x32_bf16 v[8:11], v[140:143], v[220:223], v[8:11]
	s_setprio 0
	s_setprio 1
	v_mfma_f32_16x16x32_bf16 v[52:55], v[162:165], v[192:195], v[52:55]
	v_mfma_f32_16x16x32_bf16 v[48:51], v[170:173], v[192:195], v[48:51]
	v_mfma_f32_16x16x32_bf16 v[36:39], v[162:165], v[200:203], v[36:39]
	v_mfma_f32_16x16x32_bf16 v[32:35], v[170:173], v[200:203], v[32:35]
	v_mfma_f32_16x16x32_bf16 v[20:23], v[162:165], v[208:211], v[20:23]
	v_mfma_f32_16x16x32_bf16 v[16:19], v[170:173], v[208:211], v[16:19]
	v_mfma_f32_16x16x32_bf16 v[4:7], v[162:165], v[216:219], v[4:7]
	v_mfma_f32_16x16x32_bf16 v[0:3], v[170:173], v[216:219], v[0:3]
	v_mfma_f32_16x16x32_bf16 v[52:55], v[166:169], v[196:199], v[52:55]
	v_mfma_f32_16x16x32_bf16 v[48:51], v[188:191], v[196:199], v[48:51]
	v_mfma_f32_16x16x32_bf16 v[36:39], v[166:169], v[204:207], v[36:39]
	v_mfma_f32_16x16x32_bf16 v[32:35], v[188:191], v[204:207], v[32:35]
	v_mfma_f32_16x16x32_bf16 v[20:23], v[166:169], v[212:215], v[20:23]
	v_mfma_f32_16x16x32_bf16 v[16:19], v[188:191], v[212:215], v[16:19]
	v_mfma_f32_16x16x32_bf16 v[4:7], v[166:169], v[220:223], v[4:7]
	v_mfma_f32_16x16x32_bf16 v[0:3], v[188:191], v[220:223], v[0:3]
	s_setprio 0
	s_barrier
	s_add_i32 s59, s59, 2
	s_add_u32 s4, s4, 0x100
	s_addc_u32 s5, s5, 0
	s_add_u32 s57, s57, 0x100
	s_addc_u32 s58, s58, 0
	s_cmp_gt_u32 s59, 13
	s_cbranch_scc0 .LBB0_506
.LBB0_506:
	ds_read_b128 v[128:131], v181
	ds_read_b128 v[132:135], v181 offset:1024
	ds_read_b128 v[136:139], v181 offset:2048
	ds_read_b128 v[140:143], v181 offset:3072
	s_waitcnt lgkmcnt(0)
	ds_read_b128 v[162:165], v182
	ds_read_b128 v[166:169], v182 offset:1024
	ds_read_b128 v[170:173], v182 offset:2048
	ds_read_b128 v[188:191], v182 offset:3072
	s_add_u32 s34, s4, 0xfffc0080
	s_addc_u32 s35, s5, -1
	s_cmp_eq_u32 s59, 12
	s_cselect_b32 s37, s9, s35
	s_cselect_b32 s36, s27, s34
	s_cselect_b32 s35, s25, s58
	s_cselect_b32 s34, s56, s57
	s_add_i32 m0, s38, 0xc000
	ds_read_b128 v[192:195], v183
	ds_read_b128 v[196:199], v183 offset:1024
	ds_read_b128 v[200:203], v183 offset:2048
	ds_read_b128 v[204:207], v183 offset:3072
	ds_read_b128 v[208:211], v183 offset:4096
	ds_read_b128 v[212:215], v183 offset:5120
	ds_read_b128 v[216:219], v183 offset:6144
	ds_read_b128 v[220:223], v183 offset:7168
	global_load_lds_dwordx4 v154, s[4:5]
	s_add_i32 m0, s38, 0xe000
	s_nop 0
	global_load_lds_dwordx4 v156, s[4:5]
	s_waitcnt vmcnt(8)
	s_waitcnt lgkmcnt(0)
	s_barrier
; #define PG8_STAGE(bufoff, gbase, voff) do { _Pragma("unroll") for (int _i = 0; _i < 2; ++_i) \
;         __builtin_amdgcn_global_load_lds((const unsigned*)((const char*)(gbase) + (voff)[_i]), (PG8_LAS unsigned*)(lds + (bufoff) + ldsw + _i * 8192), 16, 0, 0); } while (0)
; #define PG8_LDA(dst, b, h) do { _Pragma("unroll") for (int m = 0; m < 4; ++m) _Pragma("unroll") for (int k = 0; k < 2; ++k) dst[m][k] = *(const PG8_LAS bf16x8*)(lds + PG8_SA(b, h) + aoff + m * 2048 + k * 1024); } while (0)
; #define PG8_MMA(ai, bj, At, Bt) do { __builtin_amdgcn_s_setprio(1); _Pragma("unroll") for (int m = 0; m < 4; ++m) _Pragma("unroll") for (int n = 0; n < 2; ++n) _Pragma("unroll") for (int k = 0; k < 2; ++k) \
;         acc[ai][bj][m][n] = __builtin_amdgcn_mfma_f32_16x16x32_bf16(Bt[n][k], At[m][k], acc[ai][bj][m][n], 0, 0, 0); __builtin_amdgcn_s_setprio(0); } while (0)
; #define PG8_WAIT_V(n) asm volatile("s_waitcnt vmcnt(" #n ")" ::: "memory")
; #define PG8_WAIT_L(n) asm volatile("s_waitcnt lgkmcnt(" #n ")" ::: "memory")
; #define PG8_BAR __builtin_amdgcn_s_barrier()
; #define PG8_SCHED __builtin_amdgcn_sched_barrier(0)
; template <class Epi, class Sched, bool ALIGN_EPI = false, bool SP2 = false>
; __device__ __forceinline__ void gemm_phase(PG8_LAS unsigned char* lds, const Gemm g, const Sched& S, const Epi& E) {
;     ...
;             PG8_WAIT_V(8); PG8_WAIT_L(0); PG8_BAR; PG8_MMA(0, 0, At, B0); PG8_MMA(0, 1, At, B1); PG8_BAR; PG8_SCHED;
;             PG8_LDA(At, 0, 1); PG8_STAGE(PG8_SB(0, 0), b2, voffB); PG8_STAGE(PG8_SB(0, 1), b2 + hstep, voffB); PG8_STAGE(PG8_SA(0, 0), a2, voffA);
;             PG8_WAIT_V(8); PG8_WAIT_L(0); PG8_BAR; PG8_MMA(1, 0, At, B0); PG8_MMA(1, 1, At, B1); PG8_BAR; PG8_SCHED;
	s_setprio 1
	s_waitcnt lgkmcnt(0)
	v_mfma_f32_16x16x32_bf16 v[124:127], v[128:131], v[192:195], v[124:127]
	v_mfma_f32_16x16x32_bf16 v[120:123], v[136:139], v[192:195], v[120:123]
	v_mfma_f32_16x16x32_bf16 v[108:111], v[128:131], v[200:203], v[108:111]
	v_mfma_f32_16x16x32_bf16 v[104:107], v[136:139], v[200:203], v[104:107]
	v_mfma_f32_16x16x32_bf16 v[92:95], v[128:131], v[208:211], v[92:95]
	v_mfma_f32_16x16x32_bf16 v[88:91], v[136:139], v[208:211], v[88:91]
	v_mfma_f32_16x16x32_bf16 v[76:79], v[128:131], v[216:219], v[76:79]
	v_mfma_f32_16x16x32_bf16 v[72:75], v[136:139], v[216:219], v[72:75]
	v_mfma_f32_16x16x32_bf16 v[124:127], v[132:135], v[196:199], v[124:127]
	v_mfma_f32_16x16x32_bf16 v[120:123], v[140:143], v[196:199], v[120:123]
	v_mfma_f32_16x16x32_bf16 v[108:111], v[132:135], v[204:207], v[108:111]
	v_mfma_f32_16x16x32_bf16 v[104:107], v[140:143], v[204:207], v[104:107]
	v_mfma_f32_16x16x32_bf16 v[92:95], v[132:135], v[212:215], v[92:95]
	v_mfma_f32_16x16x32_bf16 v[88:91], v[140:143], v[212:215], v[88:91]
	v_mfma_f32_16x16x32_bf16 v[76:79], v[132:135], v[220:223], v[76:79]
	v_mfma_f32_16x16x32_bf16 v[72:75], v[140:143], v[220:223], v[72:75]
	s_setprio 0
	s_setprio 1
	v_mfma_f32_16x16x32_bf16 v[116:119], v[162:165], v[192:195], v[116:119]
	v_mfma_f32_16x16x32_bf16 v[112:115], v[170:173], v[192:195], v[112:115]
	v_mfma_f32_16x16x32_bf16 v[100:103], v[162:165], v[200:203], v[100:103]
	v_mfma_f32_16x16x32_bf16 v[96:99], v[170:173], v[200:203], v[96:99]
	v_mfma_f32_16x16x32_bf16 v[84:87], v[162:165], v[208:211], v[84:87]
	v_mfma_f32_16x16x32_bf16 v[80:83], v[170:173], v[208:211], v[80:83]
	v_mfma_f32_16x16x32_bf16 v[68:71], v[162:165], v[216:219], v[68:71]
	v_mfma_f32_16x16x32_bf16 v[64:67], v[170:173], v[216:219], v[64:67]
	v_mfma_f32_16x16x32_bf16 v[116:119], v[166:169], v[196:199], v[116:119]
	v_mfma_f32_16x16x32_bf16 v[112:115], v[188:191], v[196:199], v[112:115]
	v_mfma_f32_16x16x32_bf16 v[100:103], v[166:169], v[204:207], v[100:103]
	v_mfma_f32_16x16x32_bf16 v[96:99], v[188:191], v[204:207], v[96:99]
	v_mfma_f32_16x16x32_bf16 v[84:87], v[166:169], v[212:215], v[84:87]
	v_mfma_f32_16x16x32_bf16 v[80:83], v[188:191], v[212:215], v[80:83]
	v_mfma_f32_16x16x32_bf16 v[68:71], v[166:169], v[220:223], v[68:71]
	v_mfma_f32_16x16x32_bf16 v[64:67], v[188:191], v[220:223], v[64:67]
	s_setprio 0
	s_barrier
	s_add_i32 s60, s48, s33
	v_lshl_add_u64 v[224:225], s[34:35], 0, v[146:147]
	s_mov_b32 m0, s60
	ds_read_b128 v[192:195], v183 offset:16384
	ds_read_b128 v[196:199], v183 offset:17408
	ds_read_b128 v[200:203], v183 offset:18432
	ds_read_b128 v[204:207], v183 offset:19456
	ds_read_b128 v[208:211], v183 offset:20480
	ds_read_b128 v[212:215], v183 offset:21504
	ds_read_b128 v[216:219], v183 offset:22528
	ds_read_b128 v[220:223], v183 offset:23552
	global_load_lds_dwordx4 v[224:225], off
	s_add_i32 m0, s60, 0x2000
	s_add_u32 s60, s34, 0x40000
	v_lshl_add_u64 v[226:227], s[34:35], 0, v[150:151]
	s_addc_u32 s61, s35, 0
	s_add_i32 s62, s49, s33
	global_load_lds_dwordx4 v[226:227], off
	s_mov_b32 m0, s62
	v_lshl_add_u64 v[230:231], s[36:37], 0, v[148:149]
	global_load_lds_dwordx4 v146, s[60:61]
	s_add_i32 m0, s62, 0x2000
	s_nop 0
	global_load_lds_dwordx4 v150, s[60:61]
	v_lshl_add_u64 v[228:229], s[36:37], 0, v[144:145]
	s_mov_b32 m0, s38
	s_nop 0
	global_load_lds_dwordx4 v[228:229], off
	s_mov_b32 m0, s39
	s_nop 0
	global_load_lds_dwordx4 v[230:231], off
	s_waitcnt vmcnt(8)
	s_waitcnt lgkmcnt(0)
	s_barrier
	s_setprio 1
	s_waitcnt lgkmcnt(0)
	v_mfma_f32_16x16x32_bf16 v[60:63], v[128:131], v[192:195], v[60:63]
	v_mfma_f32_16x16x32_bf16 v[56:59], v[136:139], v[192:195], v[56:59]
	v_mfma_f32_16x16x32_bf16 v[44:47], v[128:131], v[200:203], v[44:47]
	v_mfma_f32_16x16x32_bf16 v[40:43], v[136:139], v[200:203], v[40:43]
	v_mfma_f32_16x16x32_bf16 v[28:31], v[128:131], v[208:211], v[28:31]
	v_mfma_f32_16x16x32_bf16 v[24:27], v[136:139], v[208:211], v[24:27]
	v_mfma_f32_16x16x32_bf16 v[12:15], v[128:131], v[216:219], v[12:15]
	v_mfma_f32_16x16x32_bf16 v[8:11], v[136:139], v[216:219], v[8:11]
	v_mfma_f32_16x16x32_bf16 v[60:63], v[132:135], v[196:199], v[60:63]
	v_mfma_f32_16x16x32_bf16 v[56:59], v[140:143], v[196:199], v[56:59]
	v_mfma_f32_16x16x32_bf16 v[44:47], v[132:135], v[204:207], v[44:47]
	v_mfma_f32_16x16x32_bf16 v[40:43], v[140:143], v[204:207], v[40:43]
	v_mfma_f32_16x16x32_bf16 v[28:31], v[132:135], v[212:215], v[28:31]
	v_mfma_f32_16x16x32_bf16 v[24:27], v[140:143], v[212:215], v[24:27]
	v_mfma_f32_16x16x32_bf16 v[12:15], v[132:135], v[220:223], v[12:15]
	v_mfma_f32_16x16x32_bf16 v[8:11], v[140:143], v[220:223], v[8:11]
	s_setprio 0
	s_setprio 1
	v_mfma_f32_16x16x32_bf16 v[52:55], v[162:165], v[192:195], v[52:55]
	v_mfma_f32_16x16x32_bf16 v[48:51], v[170:173], v[192:195], v[48:51]
	v_mfma_f32_16x16x32_bf16 v[36:39], v[162:165], v[200:203], v[36:39]
	v_mfma_f32_16x16x32_bf16 v[32:35], v[170:173], v[200:203], v[32:35]
	v_mfma_f32_16x16x32_bf16 v[20:23], v[162:165], v[208:211], v[20:23]
	v_mfma_f32_16x16x32_bf16 v[16:19], v[170:173], v[208:211], v[16:19]
	v_mfma_f32_16x16x32_bf16 v[4:7], v[162:165], v[216:219], v[4:7]
	v_mfma_f32_16x16x32_bf16 v[0:3], v[170:173], v[216:219], v[0:3]
	v_mfma_f32_16x16x32_bf16 v[52:55], v[166:169], v[196:199], v[52:55]
	v_mfma_f32_16x16x32_bf16 v[48:51], v[188:191], v[196:199], v[48:51]
	v_mfma_f32_16x16x32_bf16 v[36:39], v[166:169], v[204:207], v[36:39]
	v_mfma_f32_16x16x32_bf16 v[32:35], v[188:191], v[204:207], v[32:35]
	v_mfma_f32_16x16x32_bf16 v[20:23], v[166:169], v[212:215], v[20:23]
	v_mfma_f32_16x16x32_bf16 v[16:19], v[188:191], v[212:215], v[16:19]
	v_mfma_f32_16x16x32_bf16 v[4:7], v[166:169], v[220:223], v[4:7]
	v_mfma_f32_16x16x32_bf16 v[0:3], v[188:191], v[220:223], v[0:3]
	s_setprio 0
	s_barrier
; #define PG8_STAGE(bufoff, gbase, voff) do { _Pragma("unroll") for (int _i = 0; _i < 2; ++_i) \
;         __builtin_amdgcn_global_load_lds((const unsigned*)((const char*)(gbase) + (voff)[_i]), (PG8_LAS unsigned*)(lds + (bufoff) + ldsw + _i * 8192), 16, 0, 0); } while (0)
; #define PG8_LDA(dst, b, h) do { _Pragma("unroll") for (int m = 0; m < 4; ++m) _Pragma("unroll") for (int k = 0; k < 2; ++k) dst[m][k] = *(const PG8_LAS bf16x8*)(lds + PG8_SA(b, h) + aoff + m * 2048 + k * 1024); } while (0)
; #define PG8_LDB(dst, b, h) do { _Pragma("unroll") for (int n = 0; n < 2; ++n) _Pragma("unroll") for (int k = 0; k < 2; ++k) dst[n][k] = *(const PG8_LAS bf16x8*)(lds + PG8_SB(b, h) + boff + n * 2048 + k * 1024); } while (0)
; #define PG8_MMA(ai, bj, At, Bt) do { __builtin_amdgcn_s_setprio(1); _Pragma("unroll") for (int m = 0; m < 4; ++m) _Pragma("unroll") for (int n = 0; n < 2; ++n) _Pragma("unroll") for (int k = 0; k < 2; ++k) \
;         acc[ai][bj][m][n] = __builtin_amdgcn_mfma_f32_16x16x32_bf16(Bt[n][k], At[m][k], acc[ai][bj][m][n], 0, 0, 0); __builtin_amdgcn_s_setprio(0); } while (0)
; #define PG8_WAIT_V(n) asm volatile("s_waitcnt vmcnt(" #n ")" ::: "memory")
; #define PG8_WAIT_L(n) asm volatile("s_waitcnt lgkmcnt(" #n ")" ::: "memory")
; #define PG8_BAR __builtin_amdgcn_s_barrier()
; #define PG8_SCHED __builtin_amdgcn_sched_barrier(0)
; template <class Epi, class Sched, bool ALIGN_EPI = false, bool SP2 = false>
; __device__ __forceinline__ void gemm_phase(PG8_LAS unsigned char* lds, const Gemm g, const Sched& S, const Epi& E) {
;     ...
;             PG8_LDB(B0, 1, 0); PG8_LDB(B1, 1, 1); PG8_SCHED; PG8_LDA(At, 1, 0); PG8_STAGE(PG8_SA(0, 1), a2 + hstep, voffA);
;             PG8_WAIT_V(8); PG8_WAIT_L(0); PG8_BAR; PG8_MMA(0, 0, At, B0); PG8_MMA(0, 1, At, B1); PG8_BAR; PG8_SCHED;
	s_add_i32 s60, 0, 0x18000
	s_add_i32 s61, 0, 0x1c000
	v_add_u32_e32 v140, s60, v175
	v_add_u32_e32 v187, s61, v175
	ds_read_b128 v[128:131], v140
	ds_read_b128 v[132:135], v140 offset:1024
	ds_read_b128 v[136:139], v140 offset:2048
	ds_read_b128 v[140:143], v140 offset:3072
	ds_read_b128 v[162:165], v187
	ds_read_b128 v[166:169], v187 offset:1024
	ds_read_b128 v[170:173], v187 offset:2048
	ds_read_b128 v[188:191], v187 offset:3072
	s_add_u32 s36, s36, 0x40000
	s_addc_u32 s37, s37, 0
	s_mov_b32 m0, s40
	ds_read_b128 v[192:195], v183 offset:32768
	ds_read_b128 v[196:199], v183 offset:33792
	ds_read_b128 v[200:203], v183 offset:34816
	ds_read_b128 v[204:207], v183 offset:35840
	ds_read_b128 v[208:211], v183 offset:36864
	ds_read_b128 v[212:215], v183 offset:37888
	ds_read_b128 v[216:219], v183 offset:38912
	ds_read_b128 v[220:223], v183 offset:39936
	global_load_lds_dwordx4 v144, s[36:37]
	v_lshl_add_u64 v[232:233], s[36:37], 0, v[148:149]
	s_mov_b32 m0, s41
	s_nop 0
	global_load_lds_dwordx4 v[232:233], off
	s_waitcnt vmcnt(8)
	s_waitcnt lgkmcnt(0)
	s_barrier
	s_setprio 1
	s_waitcnt lgkmcnt(0)
	v_mfma_f32_16x16x32_bf16 v[124:127], v[128:131], v[192:195], v[124:127]
	v_mfma_f32_16x16x32_bf16 v[120:123], v[136:139], v[192:195], v[120:123]
	v_mfma_f32_16x16x32_bf16 v[108:111], v[128:131], v[200:203], v[108:111]
	v_mfma_f32_16x16x32_bf16 v[104:107], v[136:139], v[200:203], v[104:107]
	v_mfma_f32_16x16x32_bf16 v[92:95], v[128:131], v[208:211], v[92:95]
	v_mfma_f32_16x16x32_bf16 v[88:91], v[136:139], v[208:211], v[88:91]
	v_mfma_f32_16x16x32_bf16 v[76:79], v[128:131], v[216:219], v[76:79]
	v_mfma_f32_16x16x32_bf16 v[72:75], v[136:139], v[216:219], v[72:75]
	v_mfma_f32_16x16x32_bf16 v[124:127], v[132:135], v[196:199], v[124:127]
	v_mfma_f32_16x16x32_bf16 v[120:123], v[140:143], v[196:199], v[120:123]
	v_mfma_f32_16x16x32_bf16 v[108:111], v[132:135], v[204:207], v[108:111]
	v_mfma_f32_16x16x32_bf16 v[104:107], v[140:143], v[204:207], v[104:107]
	v_mfma_f32_16x16x32_bf16 v[92:95], v[132:135], v[212:215], v[92:95]
	v_mfma_f32_16x16x32_bf16 v[88:91], v[140:143], v[212:215], v[88:91]
	v_mfma_f32_16x16x32_bf16 v[76:79], v[132:135], v[220:223], v[76:79]
	v_mfma_f32_16x16x32_bf16 v[72:75], v[140:143], v[220:223], v[72:75]
	s_setprio 0
	s_setprio 1
	v_mfma_f32_16x16x32_bf16 v[116:119], v[162:165], v[192:195], v[116:119]
	v_mfma_f32_16x16x32_bf16 v[112:115], v[170:173], v[192:195], v[112:115]
	v_mfma_f32_16x16x32_bf16 v[100:103], v[162:165], v[200:203], v[100:103]
	v_mfma_f32_16x16x32_bf16 v[96:99], v[170:173], v[200:203], v[96:99]
	v_mfma_f32_16x16x32_bf16 v[84:87], v[162:165], v[208:211], v[84:87]
	v_mfma_f32_16x16x32_bf16 v[80:83], v[170:173], v[208:211], v[80:83]
	v_mfma_f32_16x16x32_bf16 v[68:71], v[162:165], v[216:219], v[68:71]
	v_mfma_f32_16x16x32_bf16 v[64:67], v[170:173], v[216:219], v[64:67]
	v_mfma_f32_16x16x32_bf16 v[116:119], v[166:169], v[196:199], v[116:119]
	v_mfma_f32_16x16x32_bf16 v[112:115], v[188:191], v[196:199], v[112:115]
	v_mfma_f32_16x16x32_bf16 v[100:103], v[166:169], v[204:207], v[100:103]
	v_mfma_f32_16x16x32_bf16 v[96:99], v[188:191], v[204:207], v[96:99]
	v_mfma_f32_16x16x32_bf16 v[84:87], v[166:169], v[212:215], v[84:87]
	v_mfma_f32_16x16x32_bf16 v[80:83], v[188:191], v[212:215], v[80:83]
	v_mfma_f32_16x16x32_bf16 v[68:71], v[166:169], v[220:223], v[68:71]
	v_mfma_f32_16x16x32_bf16 v[64:67], v[188:191], v[220:223], v[64:67]
	s_setprio 0
	s_barrier
; #define PG8_STAGE(bufoff, gbase, voff) do { _Pragma("unroll") for (int _i = 0; _i < 2; ++_i) \
;         __builtin_amdgcn_global_load_lds((const unsigned*)((const char*)(gbase) + (voff)[_i]), (PG8_LAS unsigned*)(lds + (bufoff) + ldsw + _i * 8192), 16, 0, 0); } while (0)
; #define PG8_LDA(dst, b, h) do { _Pragma("unroll") for (int m = 0; m < 4; ++m) _Pragma("unroll") for (int k = 0; k < 2; ++k) dst[m][k] = *(const PG8_LAS bf16x8*)(lds + PG8_SA(b, h) + aoff + m * 2048 + k * 1024); } while (0)
; #define PG8_MMA(ai, bj, At, Bt) do { __builtin_amdgcn_s_setprio(1); _Pragma("unroll") for (int m = 0; m < 4; ++m) _Pragma("unroll") for (int n = 0; n < 2; ++n) _Pragma("unroll") for (int k = 0; k < 2; ++k) \
;         acc[ai][bj][m][n] = __builtin_amdgcn_mfma_f32_16x16x32_bf16(Bt[n][k], At[m][k], acc[ai][bj][m][n], 0, 0, 0); __builtin_amdgcn_s_setprio(0); } while (0)
; #define PG8_WAIT_V(n) asm volatile("s_waitcnt vmcnt(" #n ")" ::: "memory")
; #define PG8_WAIT_L(n) asm volatile("s_waitcnt lgkmcnt(" #n ")" ::: "memory")
; #define PG8_BAR __builtin_amdgcn_s_barrier()
; #define PG8_SCHED __builtin_amdgcn_sched_barrier(0)
; template <class Epi, class Sched, bool ALIGN_EPI = false, bool SP2 = false>
; __device__ __forceinline__ void gemm_phase(PG8_LAS unsigned char* lds, const Gemm g, const Sched& S, const Epi& E) {
;     ...
;             PG8_LDA(At, 1, 1); PG8_STAGE(PG8_SB(1, 0), b3, voffB); PG8_STAGE(PG8_SB(1, 1), b3 + hstep, voffB); PG8_STAGE(PG8_SA(1, 0), a3, voffA);
;             PG8_WAIT_V(8); PG8_WAIT_L(0); PG8_BAR; PG8_MMA(1, 0, At, B0); PG8_MMA(1, 1, At, B1); PG8_BAR; PG8_SCHED;
	s_add_i32 s36, s60, s33
	v_lshl_add_u64 v[224:225], v[224:225], 0, s[16:17]
	s_mov_b32 m0, s36
	ds_read_b128 v[192:195], v183 offset:49152
	ds_read_b128 v[196:199], v183 offset:50176
	ds_read_b128 v[200:203], v183 offset:51200
	ds_read_b128 v[204:207], v183 offset:52224
	ds_read_b128 v[208:211], v183 offset:53248
	ds_read_b128 v[212:215], v183 offset:54272
	ds_read_b128 v[216:219], v183 offset:55296
	ds_read_b128 v[220:223], v183 offset:56320
	global_load_lds_dwordx4 v[224:225], off
	s_add_i32 m0, s36, 0x2000
	s_add_u32 s34, s34, 0x40080
	v_lshl_add_u64 v[224:225], v[226:227], 0, s[16:17]
	s_addc_u32 s35, s35, 0
	s_add_i32 s36, s61, s33
	global_load_lds_dwordx4 v[224:225], off
	s_mov_b32 m0, s36
	s_nop 0
	global_load_lds_dwordx4 v146, s[34:35]
	s_add_i32 m0, s36, 0x2000
	s_nop 0
	global_load_lds_dwordx4 v150, s[34:35]
	v_lshl_add_u64 v[224:225], v[228:229], 0, s[16:17]
	s_mov_b32 m0, s46
	s_nop 0
	global_load_lds_dwordx4 v[224:225], off
	v_lshl_add_u64 v[224:225], v[230:231], 0, s[16:17]
	s_mov_b32 m0, s47
	s_nop 0
	global_load_lds_dwordx4 v[224:225], off
	s_waitcnt vmcnt(8)
	s_waitcnt lgkmcnt(0)
	s_barrier
	s_setprio 1
	s_waitcnt lgkmcnt(0)
	v_mfma_f32_16x16x32_bf16 v[60:63], v[128:131], v[192:195], v[60:63]
	v_mfma_f32_16x16x32_bf16 v[56:59], v[136:139], v[192:195], v[56:59]
	v_mfma_f32_16x16x32_bf16 v[44:47], v[128:131], v[200:203], v[44:47]
	v_mfma_f32_16x16x32_bf16 v[40:43], v[136:139], v[200:203], v[40:43]
	v_mfma_f32_16x16x32_bf16 v[28:31], v[128:131], v[208:211], v[28:31]
	v_mfma_f32_16x16x32_bf16 v[24:27], v[136:139], v[208:211], v[24:27]
	v_mfma_f32_16x16x32_bf16 v[12:15], v[128:131], v[216:219], v[12:15]
	v_mfma_f32_16x16x32_bf16 v[8:11], v[136:139], v[216:219], v[8:11]
	v_mfma_f32_16x16x32_bf16 v[60:63], v[132:135], v[196:199], v[60:63]
	v_mfma_f32_16x16x32_bf16 v[56:59], v[140:143], v[196:199], v[56:59]
	v_mfma_f32_16x16x32_bf16 v[44:47], v[132:135], v[204:207], v[44:47]
	v_mfma_f32_16x16x32_bf16 v[40:43], v[140:143], v[204:207], v[40:43]
	v_mfma_f32_16x16x32_bf16 v[28:31], v[132:135], v[212:215], v[28:31]
	v_mfma_f32_16x16x32_bf16 v[24:27], v[140:143], v[212:215], v[24:27]
	v_mfma_f32_16x16x32_bf16 v[12:15], v[132:135], v[220:223], v[12:15]
	v_mfma_f32_16x16x32_bf16 v[8:11], v[140:143], v[220:223], v[8:11]
	s_setprio 0
	s_setprio 1
	v_mfma_f32_16x16x32_bf16 v[52:55], v[162:165], v[192:195], v[52:55]
	v_mfma_f32_16x16x32_bf16 v[48:51], v[170:173], v[192:195], v[48:51]
	v_mfma_f32_16x16x32_bf16 v[36:39], v[162:165], v[200:203], v[36:39]
	v_mfma_f32_16x16x32_bf16 v[32:35], v[170:173], v[200:203], v[32:35]
	v_mfma_f32_16x16x32_bf16 v[20:23], v[162:165], v[208:211], v[20:23]
	v_mfma_f32_16x16x32_bf16 v[16:19], v[170:173], v[208:211], v[16:19]
	v_mfma_f32_16x16x32_bf16 v[4:7], v[162:165], v[216:219], v[4:7]
	v_mfma_f32_16x16x32_bf16 v[0:3], v[170:173], v[216:219], v[0:3]
	v_mfma_f32_16x16x32_bf16 v[52:55], v[166:169], v[196:199], v[52:55]
	v_mfma_f32_16x16x32_bf16 v[48:51], v[188:191], v[196:199], v[48:51]
	v_mfma_f32_16x16x32_bf16 v[36:39], v[166:169], v[204:207], v[36:39]
	v_mfma_f32_16x16x32_bf16 v[32:35], v[188:191], v[204:207], v[32:35]
	v_mfma_f32_16x16x32_bf16 v[20:23], v[166:169], v[212:215], v[20:23]
	v_mfma_f32_16x16x32_bf16 v[16:19], v[188:191], v[212:215], v[16:19]
	v_mfma_f32_16x16x32_bf16 v[4:7], v[166:169], v[220:223], v[4:7]
	v_mfma_f32_16x16x32_bf16 v[0:3], v[188:191], v[220:223], v[0:3]
	s_setprio 0
	s_barrier
	s_add_i32 s59, s59, 2
	s_add_u32 s4, s4, 0x100
	s_addc_u32 s5, s5, 0
	s_add_u32 s57, s57, 0x100
	s_addc_u32 s58, s58, 0
	s_cmp_gt_u32 s59, 13
	s_cbranch_scc0 .LBB0_506
	s_and_b64 vcc, exec, s[18:19]
	s_cbranch_vccz .LBB0_509
	s_barrier

; #define PG8_STAGE(bufoff, gbase, voff) do { _Pragma("unroll") for (int _i = 0; _i < 2; ++_i) \
;         __builtin_amdgcn_global_load_lds((const unsigned*)((const char*)(gbase) + (voff)[_i]), (PG8_LAS unsigned*)(lds + (bufoff) + ldsw + _i * 8192), 16, 0, 0); } while (0)
; #define PG8_LDA(dst, b, h) do { _Pragma("unroll") for (int m = 0; m < 4; ++m) _Pragma("unroll") for (int k = 0; k < 2; ++k) dst[m][k] = *(const PG8_LAS bf16x8*)(lds + PG8_SA(b, h) + aoff + m * 2048 + k * 1024); } while (0)
; #define PG8_LDB(dst, b, h) do { _Pragma("unroll") for (int n = 0; n < 2; ++n) _Pragma("unroll") for (int k = 0; k < 2; ++k) dst[n][k] = *(const PG8_LAS bf16x8*)(lds + PG8_SB(b, h) + boff + n * 2048 + k * 1024); } while (0)
; #define PG8_WAIT_V(n) asm volatile("s_waitcnt vmcnt(" #n ")" ::: "memory")
; #define PG8_WAIT_L(n) asm volatile("s_waitcnt lgkmcnt(" #n ")" ::: "memory")
; #define PG8_BAR __builtin_amdgcn_s_barrier()
; #define PG8_SCHED __builtin_amdgcn_sched_barrier(0)
; template <class Epi, class Sched, bool ALIGN_EPI = false, bool SP2 = false>
; __device__ __forceinline__ void gemm_phase(PG8_LAS unsigned char* lds, const Gemm g, const Sched& S, const Epi& E) {
;     ...
;         const bool has_next = S.next(ui + 1, nxt);
;         const char* nA = has_next ? (const char*)g.A + (size_t)nxt.pm * tstep : cA; const char* nB = has_next ? (const char*)g.Bt + (size_t)nxt.pn * tstep : cB;
;         for (int t = 0; t < nt; t += 2) {
;             const bool last = (t == nt - 2);
;             const char* a1 = cA + (size_t)(t + 1) * kstep;
;             const char* a2 = last ? nA : cA + (size_t)(t + 2) * kstep; const char* b2 = last ? nB : cB + (size_t)(t + 2) * kstep;
;             const char* a3 = a2 + kstep; const char* b3 = b2 + kstep;
;             if (last && has_next) S.a_ready(nxt);
;             if constexpr (SP2) {
;             PG8_LDB(B0, 0, 0); PG8_LDB(B1, 0, 1); PG8_SCHED; PG8_LDA(At, 0, 0); PG8_STAGE(PG8_SA(1, 1), a1 + hstep, voffA);
;             PG8_WAIT_V(8); PG8_WAIT_L(0); PG8_BAR; PG8_MMA(0, 0, At, B0); PG8_MMA(0, 1, At, B1); PG8_BAR; PG8_SCHED;
;             PG8_LDA(At, 0, 1); PG8_STAGE(PG8_SB(0, 0), b2, voffB); PG8_STAGE(PG8_SB(0, 1), b2 + hstep, voffB); PG8_STAGE(PG8_SA(0, 0), a2, voffA);
;             PG8_WAIT_V(8); PG8_WAIT_L(0); PG8_BAR; PG8_MMA(1, 0, At, B0); PG8_MMA(1, 1, At, B1); PG8_BAR; PG8_SCHED;
.LBB0_764:
	s_ashr_i32 s23, s22, 31
	s_lshl_b64 s[0:1], s[22:23], 19
	s_add_u32 s24, s58, s0
	s_addc_u32 s25, s59, s1
	s_and_b64 s[0:1], s[6:7], exec
	s_cselect_b32 s0, s25, s35
	s_cselect_b32 s1, s24, s34
	s_ashr_i32 s21, s20, 31
	s_lshl_b64 s[4:5], s[20:21], 19
	s_add_u32 s26, s36, s4
	s_addc_u32 s27, s37, s5
	s_and_b64 s[4:5], s[6:7], exec
	s_cselect_b32 s21, s27, s31
	s_cselect_b32 s23, s26, s30
	s_add_u32 s4, s34, 0x40080
	s_addc_u32 s5, s35, 0
	s_add_u32 s34, s30, 0x100
	s_addc_u32 s35, s31, 0
	s_mov_b32 s53, -2
	ds_read_b128 v[128:131], v183
	ds_read_b128 v[132:135], v183 offset:1024
	ds_read_b128 v[136:139], v183 offset:2048
	ds_read_b128 v[140:143], v183 offset:3072
	s_waitcnt lgkmcnt(0)
	ds_read_b128 v[162:165], v184
	ds_read_b128 v[166:169], v184 offset:1024
	ds_read_b128 v[170:173], v184 offset:2048
	ds_read_b128 v[190:193], v184 offset:3072
	s_add_u32 s10, s4, 0xfffc0080
	s_addc_u32 s11, s5, -1
	s_cmp_eq_u32 s53, 12
	s_cselect_b32 s31, s0, s11
	s_cselect_b32 s30, s1, s10
	s_cselect_b32 s11, s21, s35
	s_cselect_b32 s10, s23, s34
	s_add_i32 m0, s29, 0xc000
	ds_read_b128 v[194:197], v185
	ds_read_b128 v[198:201], v185 offset:1024
	ds_read_b128 v[202:205], v185 offset:2048
	ds_read_b128 v[206:209], v185 offset:3072
	ds_read_b128 v[210:213], v185 offset:4096
	ds_read_b128 v[214:217], v185 offset:5120
	ds_read_b128 v[218:221], v185 offset:6144
	ds_read_b128 v[222:225], v185 offset:7168
	global_load_lds_dwordx4 v154, s[4:5]
	s_add_i32 m0, s29, 0xe000
	s_nop 0
	global_load_lds_dwordx4 v156, s[4:5]
	s_waitcnt vmcnt(8)
	s_waitcnt lgkmcnt(0)
	s_barrier
	s_setprio 1
	s_waitcnt lgkmcnt(0)
	v_mfma_f32_16x16x32_bf16 v[124:127], v[128:131], v[194:197], 0
	v_mfma_f32_16x16x32_bf16 v[120:123], v[136:139], v[194:197], 0
	v_mfma_f32_16x16x32_bf16 v[108:111], v[128:131], v[202:205], 0
	v_mfma_f32_16x16x32_bf16 v[104:107], v[136:139], v[202:205], 0
	v_mfma_f32_16x16x32_bf16 v[92:95], v[128:131], v[210:213], 0
	v_mfma_f32_16x16x32_bf16 v[88:91], v[136:139], v[210:213], 0
	v_mfma_f32_16x16x32_bf16 v[76:79], v[128:131], v[218:221], 0
	v_mfma_f32_16x16x32_bf16 v[72:75], v[136:139], v[218:221], 0
	v_mfma_f32_16x16x32_bf16 v[124:127], v[132:135], v[198:201], v[124:127]
	v_mfma_f32_16x16x32_bf16 v[120:123], v[140:143], v[198:201], v[120:123]
	v_mfma_f32_16x16x32_bf16 v[108:111], v[132:135], v[206:209], v[108:111]
	v_mfma_f32_16x16x32_bf16 v[104:107], v[140:143], v[206:209], v[104:107]
	v_mfma_f32_16x16x32_bf16 v[92:95], v[132:135], v[214:217], v[92:95]
	v_mfma_f32_16x16x32_bf16 v[88:91], v[140:143], v[214:217], v[88:91]
	v_mfma_f32_16x16x32_bf16 v[76:79], v[132:135], v[222:225], v[76:79]
	v_mfma_f32_16x16x32_bf16 v[72:75], v[140:143], v[222:225], v[72:75]
	s_setprio 0
	s_setprio 1
	v_mfma_f32_16x16x32_bf16 v[116:119], v[162:165], v[194:197], 0
	v_mfma_f32_16x16x32_bf16 v[112:115], v[170:173], v[194:197], 0
	v_mfma_f32_16x16x32_bf16 v[100:103], v[162:165], v[202:205], 0
	v_mfma_f32_16x16x32_bf16 v[96:99], v[170:173], v[202:205], 0
	v_mfma_f32_16x16x32_bf16 v[84:87], v[162:165], v[210:213], 0
	v_mfma_f32_16x16x32_bf16 v[80:83], v[170:173], v[210:213], 0
	v_mfma_f32_16x16x32_bf16 v[68:71], v[162:165], v[218:221], 0
	v_mfma_f32_16x16x32_bf16 v[64:67], v[170:173], v[218:221], 0
	v_mfma_f32_16x16x32_bf16 v[116:119], v[166:169], v[198:201], v[116:119]
	v_mfma_f32_16x16x32_bf16 v[112:115], v[190:193], v[198:201], v[112:115]
	v_mfma_f32_16x16x32_bf16 v[100:103], v[166:169], v[206:209], v[100:103]
	v_mfma_f32_16x16x32_bf16 v[96:99], v[190:193], v[206:209], v[96:99]
	v_mfma_f32_16x16x32_bf16 v[84:87], v[166:169], v[214:217], v[84:87]
	v_mfma_f32_16x16x32_bf16 v[80:83], v[190:193], v[214:217], v[80:83]
	v_mfma_f32_16x16x32_bf16 v[68:71], v[166:169], v[222:225], v[68:71]
	v_mfma_f32_16x16x32_bf16 v[64:67], v[190:193], v[222:225], v[64:67]
	s_setprio 0
	s_barrier
	s_add_i32 s54, s47, s33
	v_lshl_add_u64 v[226:227], s[10:11], 0, v[146:147]
	s_mov_b32 m0, s54
	ds_read_b128 v[194:197], v185 offset:16384
	ds_read_b128 v[198:201], v185 offset:17408
	ds_read_b128 v[202:205], v185 offset:18432
	ds_read_b128 v[206:209], v185 offset:19456
	ds_read_b128 v[210:213], v185 offset:20480
	ds_read_b128 v[214:217], v185 offset:21504
	ds_read_b128 v[218:221], v185 offset:22528
	ds_read_b128 v[222:225], v185 offset:23552
	global_load_lds_dwordx4 v[226:227], off
	s_add_i32 m0, s54, 0x2000
	s_add_u32 s54, s10, 0x40000
	v_lshl_add_u64 v[228:229], s[10:11], 0, v[150:151]
	s_addc_u32 s55, s11, 0
	s_add_i32 s56, s48, s33
	global_load_lds_dwordx4 v[228:229], off
	s_mov_b32 m0, s56
	v_lshl_add_u64 v[232:233], s[30:31], 0, v[148:149]
	global_load_lds_dwordx4 v146, s[54:55]
	s_add_i32 m0, s56, 0x2000
	s_nop 0
	global_load_lds_dwordx4 v150, s[54:55]
	v_lshl_add_u64 v[230:231], s[30:31], 0, v[144:145]
	s_mov_b32 m0, s29
	s_nop 0
	global_load_lds_dwordx4 v[230:231], off
	s_mov_b32 m0, s38
	s_nop 0
	global_load_lds_dwordx4 v[232:233], off
	s_waitcnt vmcnt(8)
	s_waitcnt lgkmcnt(0)
	s_barrier
; #define PG8_STAGE(bufoff, gbase, voff) do { _Pragma("unroll") for (int _i = 0; _i < 2; ++_i) \
;         __builtin_amdgcn_global_load_lds((const unsigned*)((const char*)(gbase) + (voff)[_i]), (PG8_LAS unsigned*)(lds + (bufoff) + ldsw + _i * 8192), 16, 0, 0); } while (0)
; #define PG8_LDA(dst, b, h) do { _Pragma("unroll") for (int m = 0; m < 4; ++m) _Pragma("unroll") for (int k = 0; k < 2; ++k) dst[m][k] = *(const PG8_LAS bf16x8*)(lds + PG8_SA(b, h) + aoff + m * 2048 + k * 1024); } while (0)
; #define PG8_LDB(dst, b, h) do { _Pragma("unroll") for (int n = 0; n < 2; ++n) _Pragma("unroll") for (int k = 0; k < 2; ++k) dst[n][k] = *(const PG8_LAS bf16x8*)(lds + PG8_SB(b, h) + boff + n * 2048 + k * 1024); } while (0)
; #define PG8_MMA(ai, bj, At, Bt) do { __builtin_amdgcn_s_setprio(1); _Pragma("unroll") for (int m = 0; m < 4; ++m) _Pragma("unroll") for (int n = 0; n < 2; ++n) _Pragma("unroll") for (int k = 0; k < 2; ++k) \
;         acc[ai][bj][m][n] = __builtin_amdgcn_mfma_f32_16x16x32_bf16(Bt[n][k], At[m][k], acc[ai][bj][m][n], 0, 0, 0); __builtin_amdgcn_s_setprio(0); } while (0)
; #define PG8_WAIT_V(n) asm volatile("s_waitcnt vmcnt(" #n ")" ::: "memory")
; #define PG8_WAIT_L(n) asm volatile("s_waitcnt lgkmcnt(" #n ")" ::: "memory")
; #define PG8_BAR __builtin_amdgcn_s_barrier()
; #define PG8_SCHED __builtin_amdgcn_sched_barrier(0)
; template <class Epi, class Sched, bool ALIGN_EPI = false, bool SP2 = false>
; __device__ __forceinline__ void gemm_phase(PG8_LAS unsigned char* lds, const Gemm g, const Sched& S, const Epi& E) {
;     ...
;             PG8_WAIT_V(8); PG8_WAIT_L(0); PG8_BAR; PG8_MMA(1, 0, At, B0); PG8_MMA(1, 1, At, B1); PG8_BAR; PG8_SCHED;
;             PG8_LDB(B0, 1, 0); PG8_LDB(B1, 1, 1); PG8_SCHED; PG8_LDA(At, 1, 0); PG8_STAGE(PG8_SA(0, 1), a2 + hstep, voffA);
;             PG8_WAIT_V(8); PG8_WAIT_L(0); PG8_BAR; PG8_MMA(0, 0, At, B0); PG8_MMA(0, 1, At, B1); PG8_BAR; PG8_SCHED;
	s_setprio 1
	s_waitcnt lgkmcnt(0)
	v_mfma_f32_16x16x32_bf16 v[60:63], v[128:131], v[194:197], 0
	v_mfma_f32_16x16x32_bf16 v[56:59], v[136:139], v[194:197], 0
	v_mfma_f32_16x16x32_bf16 v[44:47], v[128:131], v[202:205], 0
	v_mfma_f32_16x16x32_bf16 v[40:43], v[136:139], v[202:205], 0
	v_mfma_f32_16x16x32_bf16 v[28:31], v[128:131], v[210:213], 0
	v_mfma_f32_16x16x32_bf16 v[24:27], v[136:139], v[210:213], 0
	v_mfma_f32_16x16x32_bf16 v[12:15], v[128:131], v[218:221], 0
	v_mfma_f32_16x16x32_bf16 v[8:11], v[136:139], v[218:221], 0
	v_mfma_f32_16x16x32_bf16 v[60:63], v[132:135], v[198:201], v[60:63]
	v_mfma_f32_16x16x32_bf16 v[56:59], v[140:143], v[198:201], v[56:59]
	v_mfma_f32_16x16x32_bf16 v[44:47], v[132:135], v[206:209], v[44:47]
	v_mfma_f32_16x16x32_bf16 v[40:43], v[140:143], v[206:209], v[40:43]
	v_mfma_f32_16x16x32_bf16 v[28:31], v[132:135], v[214:217], v[28:31]
	v_mfma_f32_16x16x32_bf16 v[24:27], v[140:143], v[214:217], v[24:27]
	v_mfma_f32_16x16x32_bf16 v[12:15], v[132:135], v[222:225], v[12:15]
	v_mfma_f32_16x16x32_bf16 v[8:11], v[140:143], v[222:225], v[8:11]
	s_setprio 0
	s_setprio 1
	v_mfma_f32_16x16x32_bf16 v[52:55], v[162:165], v[194:197], 0
	v_mfma_f32_16x16x32_bf16 v[48:51], v[170:173], v[194:197], 0
	v_mfma_f32_16x16x32_bf16 v[36:39], v[162:165], v[202:205], 0
	v_mfma_f32_16x16x32_bf16 v[32:35], v[170:173], v[202:205], 0
	v_mfma_f32_16x16x32_bf16 v[20:23], v[162:165], v[210:213], 0
	v_mfma_f32_16x16x32_bf16 v[16:19], v[170:173], v[210:213], 0
	v_mfma_f32_16x16x32_bf16 v[4:7], v[162:165], v[218:221], 0
	v_mfma_f32_16x16x32_bf16 v[0:3], v[170:173], v[218:221], 0
	v_mfma_f32_16x16x32_bf16 v[52:55], v[166:169], v[198:201], v[52:55]
	v_mfma_f32_16x16x32_bf16 v[48:51], v[190:193], v[198:201], v[48:51]
	v_mfma_f32_16x16x32_bf16 v[36:39], v[166:169], v[206:209], v[36:39]
	v_mfma_f32_16x16x32_bf16 v[32:35], v[190:193], v[206:209], v[32:35]
	v_mfma_f32_16x16x32_bf16 v[20:23], v[166:169], v[214:217], v[20:23]
	v_mfma_f32_16x16x32_bf16 v[16:19], v[190:193], v[214:217], v[16:19]
	v_mfma_f32_16x16x32_bf16 v[4:7], v[166:169], v[222:225], v[4:7]
	v_mfma_f32_16x16x32_bf16 v[0:3], v[190:193], v[222:225], v[0:3]
	s_setprio 0
	s_barrier
	s_add_i32 s54, 0, 0x18000
	s_add_i32 s55, 0, 0x1c000
	v_add_u32_e32 v140, s54, v177
	v_add_u32_e32 v189, s55, v177
	ds_read_b128 v[128:131], v140
	ds_read_b128 v[132:135], v140 offset:1024
	ds_read_b128 v[136:139], v140 offset:2048
	ds_read_b128 v[140:143], v140 offset:3072
	ds_read_b128 v[162:165], v189
	ds_read_b128 v[166:169], v189 offset:1024
	ds_read_b128 v[170:173], v189 offset:2048
	ds_read_b128 v[190:193], v189 offset:3072
	s_add_u32 s30, s30, 0x40000
	s_addc_u32 s31, s31, 0
	s_mov_b32 m0, s39
	ds_read_b128 v[194:197], v185 offset:32768
	ds_read_b128 v[198:201], v185 offset:33792
	ds_read_b128 v[202:205], v185 offset:34816
	ds_read_b128 v[206:209], v185 offset:35840
	ds_read_b128 v[210:213], v185 offset:36864
	ds_read_b128 v[214:217], v185 offset:37888
	ds_read_b128 v[218:221], v185 offset:38912
	ds_read_b128 v[222:225], v185 offset:39936
	global_load_lds_dwordx4 v144, s[30:31]
	v_lshl_add_u64 v[234:235], s[30:31], 0, v[148:149]
	s_mov_b32 m0, s40
	s_nop 0
	global_load_lds_dwordx4 v[234:235], off
	s_waitcnt vmcnt(8)
	s_waitcnt lgkmcnt(0)
	s_barrier
	s_setprio 1
	s_waitcnt lgkmcnt(0)
	v_mfma_f32_16x16x32_bf16 v[124:127], v[128:131], v[194:197], v[124:127]
	v_mfma_f32_16x16x32_bf16 v[120:123], v[136:139], v[194:197], v[120:123]
	v_mfma_f32_16x16x32_bf16 v[108:111], v[128:131], v[202:205], v[108:111]
	v_mfma_f32_16x16x32_bf16 v[104:107], v[136:139], v[202:205], v[104:107]
	v_mfma_f32_16x16x32_bf16 v[92:95], v[128:131], v[210:213], v[92:95]
	v_mfma_f32_16x16x32_bf16 v[88:91], v[136:139], v[210:213], v[88:91]
	v_mfma_f32_16x16x32_bf16 v[76:79], v[128:131], v[218:221], v[76:79]
	v_mfma_f32_16x16x32_bf16 v[72:75], v[136:139], v[218:221], v[72:75]
	v_mfma_f32_16x16x32_bf16 v[124:127], v[132:135], v[198:201], v[124:127]
	v_mfma_f32_16x16x32_bf16 v[120:123], v[140:143], v[198:201], v[120:123]
	v_mfma_f32_16x16x32_bf16 v[108:111], v[132:135], v[206:209], v[108:111]
	v_mfma_f32_16x16x32_bf16 v[104:107], v[140:143], v[206:209], v[104:107]
	v_mfma_f32_16x16x32_bf16 v[92:95], v[132:135], v[214:217], v[92:95]
	v_mfma_f32_16x16x32_bf16 v[88:91], v[140:143], v[214:217], v[88:91]
	v_mfma_f32_16x16x32_bf16 v[76:79], v[132:135], v[222:225], v[76:79]
	v_mfma_f32_16x16x32_bf16 v[72:75], v[140:143], v[222:225], v[72:75]
	s_setprio 0
	s_setprio 1
	v_mfma_f32_16x16x32_bf16 v[116:119], v[162:165], v[194:197], v[116:119]
	v_mfma_f32_16x16x32_bf16 v[112:115], v[170:173], v[194:197], v[112:115]
	v_mfma_f32_16x16x32_bf16 v[100:103], v[162:165], v[202:205], v[100:103]
	v_mfma_f32_16x16x32_bf16 v[96:99], v[170:173], v[202:205], v[96:99]
	v_mfma_f32_16x16x32_bf16 v[84:87], v[162:165], v[210:213], v[84:87]
	v_mfma_f32_16x16x32_bf16 v[80:83], v[170:173], v[210:213], v[80:83]
	v_mfma_f32_16x16x32_bf16 v[68:71], v[162:165], v[218:221], v[68:71]
	v_mfma_f32_16x16x32_bf16 v[64:67], v[170:173], v[218:221], v[64:67]
	v_mfma_f32_16x16x32_bf16 v[116:119], v[166:169], v[198:201], v[116:119]
	v_mfma_f32_16x16x32_bf16 v[112:115], v[190:193], v[198:201], v[112:115]
	v_mfma_f32_16x16x32_bf16 v[100:103], v[166:169], v[206:209], v[100:103]
	v_mfma_f32_16x16x32_bf16 v[96:99], v[190:193], v[206:209], v[96:99]
	v_mfma_f32_16x16x32_bf16 v[84:87], v[166:169], v[214:217], v[84:87]
	v_mfma_f32_16x16x32_bf16 v[80:83], v[190:193], v[214:217], v[80:83]
	v_mfma_f32_16x16x32_bf16 v[68:71], v[166:169], v[222:225], v[68:71]
	v_mfma_f32_16x16x32_bf16 v[64:67], v[190:193], v[222:225], v[64:67]
	s_setprio 0
	s_barrier
; #define PG8_STAGE(bufoff, gbase, voff) do { _Pragma("unroll") for (int _i = 0; _i < 2; ++_i) \
;         __builtin_amdgcn_global_load_lds((const unsigned*)((const char*)(gbase) + (voff)[_i]), (PG8_LAS unsigned*)(lds + (bufoff) + ldsw + _i * 8192), 16, 0, 0); } while (0)
; #define PG8_LDA(dst, b, h) do { _Pragma("unroll") for (int m = 0; m < 4; ++m) _Pragma("unroll") for (int k = 0; k < 2; ++k) dst[m][k] = *(const PG8_LAS bf16x8*)(lds + PG8_SA(b, h) + aoff + m * 2048 + k * 1024); } while (0)
; #define PG8_LDB(dst, b, h) do { _Pragma("unroll") for (int n = 0; n < 2; ++n) _Pragma("unroll") for (int k = 0; k < 2; ++k) dst[n][k] = *(const PG8_LAS bf16x8*)(lds + PG8_SB(b, h) + boff + n * 2048 + k * 1024); } while (0)
; #define PG8_MMA(ai, bj, At, Bt) do { __builtin_amdgcn_s_setprio(1); _Pragma("unroll") for (int m = 0; m < 4; ++m) _Pragma("unroll") for (int n = 0; n < 2; ++n) _Pragma("unroll") for (int k = 0; k < 2; ++k) \
;         acc[ai][bj][m][n] = __builtin_amdgcn_mfma_f32_16x16x32_bf16(Bt[n][k], At[m][k], acc[ai][bj][m][n], 0, 0, 0); __builtin_amdgcn_s_setprio(0); } while (0)
; #define PG8_WAIT_V(n) asm volatile("s_waitcnt vmcnt(" #n ")" ::: "memory")
; template <class Epi, class Sched, bool ALIGN_EPI = false, bool SP2 = false>
; __device__ __forceinline__ void gemm_phase(PG8_LAS unsigned char* lds, const Gemm g, const Sched& S, const Epi& E) {
;     ...
;             PG8_LDB(B0, 0, 0); PG8_LDB(B1, 0, 1); PG8_SCHED; PG8_LDA(At, 0, 0); PG8_STAGE(PG8_SA(1, 1), a1 + hstep, voffA);
;             PG8_WAIT_V(8); PG8_WAIT_L(0); PG8_BAR; PG8_MMA(0, 0, At, B0); PG8_MMA(0, 1, At, B1); PG8_BAR; PG8_SCHED;
;             PG8_LDA(At, 0, 1); PG8_STAGE(PG8_SB(0, 0), b2, voffB); PG8_STAGE(PG8_SB(0, 1), b2 + hstep, voffB); PG8_STAGE(PG8_SA(0, 0), a2, voffA);
;             PG8_WAIT_V(8); PG8_WAIT_L(0); PG8_BAR; PG8_MMA(1, 0, At, B0); PG8_MMA(1, 1, At, B1); PG8_BAR; PG8_SCHED;
;             PG8_LDB(B0, 1, 0); PG8_LDB(B1, 1, 1); PG8_SCHED; PG8_LDA(At, 1, 0); PG8_STAGE(PG8_SA(0, 1), a2 + hstep, voffA);
;             PG8_WAIT_V(8); PG8_WAIT_L(0); PG8_BAR; PG8_MMA(0, 0, At, B0); PG8_MMA(0, 1, At, B1); PG8_BAR; PG8_SCHED;
;             PG8_LDA(At, 1, 1); PG8_STAGE(PG8_SB(1, 0), b3, voffB); PG8_STAGE(PG8_SB(1, 1), b3 + hstep, voffB); PG8_STAGE(PG8_SA(1, 0), a3, voffA);
;             PG8_WAIT_V(8); PG8_WAIT_L(0); PG8_BAR; PG8_MMA(1, 0, At, B0); PG8_MMA(1, 1, At, B1); PG8_BAR; PG8_SCHED;
	s_add_i32 s30, s54, s33
	v_lshl_add_u64 v[226:227], v[226:227], 0, s[14:15]
	s_mov_b32 m0, s30
	ds_read_b128 v[194:197], v185 offset:49152
	ds_read_b128 v[198:201], v185 offset:50176
	ds_read_b128 v[202:205], v185 offset:51200
	ds_read_b128 v[206:209], v185 offset:52224
	ds_read_b128 v[210:213], v185 offset:53248
	ds_read_b128 v[214:217], v185 offset:54272
	ds_read_b128 v[218:221], v185 offset:55296
	ds_read_b128 v[222:225], v185 offset:56320
	global_load_lds_dwordx4 v[226:227], off
	s_add_i32 m0, s30, 0x2000
	s_add_u32 s10, s10, 0x40080
	v_lshl_add_u64 v[226:227], v[228:229], 0, s[14:15]
	s_addc_u32 s11, s11, 0
	s_add_i32 s30, s55, s33
	global_load_lds_dwordx4 v[226:227], off
	s_mov_b32 m0, s30
	s_nop 0
	global_load_lds_dwordx4 v146, s[10:11]
	s_add_i32 m0, s30, 0x2000
	s_nop 0
	global_load_lds_dwordx4 v150, s[10:11]
	v_lshl_add_u64 v[226:227], v[230:231], 0, s[14:15]
	s_mov_b32 m0, s45
	s_nop 0
	global_load_lds_dwordx4 v[226:227], off
	v_lshl_add_u64 v[226:227], v[232:233], 0, s[14:15]
	s_mov_b32 m0, s46
	s_nop 0
	global_load_lds_dwordx4 v[226:227], off
	s_waitcnt vmcnt(8)
	s_waitcnt lgkmcnt(0)
	s_barrier
	s_setprio 1
	s_waitcnt lgkmcnt(0)
	v_mfma_f32_16x16x32_bf16 v[60:63], v[128:131], v[194:197], v[60:63]
	v_mfma_f32_16x16x32_bf16 v[56:59], v[136:139], v[194:197], v[56:59]
	v_mfma_f32_16x16x32_bf16 v[44:47], v[128:131], v[202:205], v[44:47]
	v_mfma_f32_16x16x32_bf16 v[40:43], v[136:139], v[202:205], v[40:43]
	v_mfma_f32_16x16x32_bf16 v[28:31], v[128:131], v[210:213], v[28:31]
	v_mfma_f32_16x16x32_bf16 v[24:27], v[136:139], v[210:213], v[24:27]
	v_mfma_f32_16x16x32_bf16 v[12:15], v[128:131], v[218:221], v[12:15]
	v_mfma_f32_16x16x32_bf16 v[8:11], v[136:139], v[218:221], v[8:11]
	v_mfma_f32_16x16x32_bf16 v[60:63], v[132:135], v[198:201], v[60:63]
	v_mfma_f32_16x16x32_bf16 v[56:59], v[140:143], v[198:201], v[56:59]
	v_mfma_f32_16x16x32_bf16 v[44:47], v[132:135], v[206:209], v[44:47]
	v_mfma_f32_16x16x32_bf16 v[40:43], v[140:143], v[206:209], v[40:43]
	v_mfma_f32_16x16x32_bf16 v[28:31], v[132:135], v[214:217], v[28:31]
	v_mfma_f32_16x16x32_bf16 v[24:27], v[140:143], v[214:217], v[24:27]
	v_mfma_f32_16x16x32_bf16 v[12:15], v[132:135], v[222:225], v[12:15]
	v_mfma_f32_16x16x32_bf16 v[8:11], v[140:143], v[222:225], v[8:11]
	s_setprio 0
	s_setprio 1
	v_mfma_f32_16x16x32_bf16 v[52:55], v[162:165], v[194:197], v[52:55]
	v_mfma_f32_16x16x32_bf16 v[48:51], v[170:173], v[194:197], v[48:51]
	v_mfma_f32_16x16x32_bf16 v[36:39], v[162:165], v[202:205], v[36:39]
	v_mfma_f32_16x16x32_bf16 v[32:35], v[170:173], v[202:205], v[32:35]
	v_mfma_f32_16x16x32_bf16 v[20:23], v[162:165], v[210:213], v[20:23]
	v_mfma_f32_16x16x32_bf16 v[16:19], v[170:173], v[210:213], v[16:19]
	v_mfma_f32_16x16x32_bf16 v[4:7], v[162:165], v[218:221], v[4:7]
	v_mfma_f32_16x16x32_bf16 v[0:3], v[170:173], v[218:221], v[0:3]
	v_mfma_f32_16x16x32_bf16 v[52:55], v[166:169], v[198:201], v[52:55]
	v_mfma_f32_16x16x32_bf16 v[48:51], v[190:193], v[198:201], v[48:51]
	v_mfma_f32_16x16x32_bf16 v[36:39], v[166:169], v[206:209], v[36:39]
	v_mfma_f32_16x16x32_bf16 v[32:35], v[190:193], v[206:209], v[32:35]
	v_mfma_f32_16x16x32_bf16 v[20:23], v[166:169], v[214:217], v[20:23]
	v_mfma_f32_16x16x32_bf16 v[16:19], v[190:193], v[214:217], v[16:19]
	v_mfma_f32_16x16x32_bf16 v[4:7], v[166:169], v[222:225], v[4:7]
	v_mfma_f32_16x16x32_bf16 v[0:3], v[190:193], v[222:225], v[0:3]
	s_setprio 0
	s_barrier
	s_add_i32 s53, s53, 2
	s_add_u32 s4, s4, 0x100
	s_addc_u32 s5, s5, 0
	s_add_u32 s34, s34, 0x100
	s_addc_u32 s35, s35, 0
	s_cmp_gt_u32 s53, 13
	s_cbranch_scc0 .LBB0_765
.LBB0_765:
	ds_read_b128 v[128:131], v183
	ds_read_b128 v[132:135], v183 offset:1024
	ds_read_b128 v[136:139], v183 offset:2048
	ds_read_b128 v[140:143], v183 offset:3072
	s_waitcnt lgkmcnt(0)
	ds_read_b128 v[162:165], v184
	ds_read_b128 v[166:169], v184 offset:1024
	ds_read_b128 v[170:173], v184 offset:2048
	ds_read_b128 v[190:193], v184 offset:3072
	s_add_u32 s10, s4, 0xfffc0080
	s_addc_u32 s11, s5, -1
	s_cmp_eq_u32 s53, 12
	s_cselect_b32 s31, s0, s11
	s_cselect_b32 s30, s1, s10
	s_cselect_b32 s11, s21, s35
	s_cselect_b32 s10, s23, s34
	s_add_i32 m0, s29, 0xc000
	ds_read_b128 v[194:197], v185
	ds_read_b128 v[198:201], v185 offset:1024
	ds_read_b128 v[202:205], v185 offset:2048
	ds_read_b128 v[206:209], v185 offset:3072
	ds_read_b128 v[210:213], v185 offset:4096
	ds_read_b128 v[214:217], v185 offset:5120
	ds_read_b128 v[218:221], v185 offset:6144
	ds_read_b128 v[222:225], v185 offset:7168
	global_load_lds_dwordx4 v154, s[4:5]
	s_add_i32 m0, s29, 0xe000
	s_nop 0
	global_load_lds_dwordx4 v156, s[4:5]
	s_waitcnt vmcnt(8)
	s_waitcnt lgkmcnt(0)
	s_barrier
; #define PG8_STAGE(bufoff, gbase, voff) do { _Pragma("unroll") for (int _i = 0; _i < 2; ++_i) \
;         __builtin_amdgcn_global_load_lds((const unsigned*)((const char*)(gbase) + (voff)[_i]), (PG8_LAS unsigned*)(lds + (bufoff) + ldsw + _i * 8192), 16, 0, 0); } while (0)
; #define PG8_LDA(dst, b, h) do { _Pragma("unroll") for (int m = 0; m < 4; ++m) _Pragma("unroll") for (int k = 0; k < 2; ++k) dst[m][k] = *(const PG8_LAS bf16x8*)(lds + PG8_SA(b, h) + aoff + m * 2048 + k * 1024); } while (0)
; #define PG8_MMA(ai, bj, At, Bt) do { __builtin_amdgcn_s_setprio(1); _Pragma("unroll") for (int m = 0; m < 4; ++m) _Pragma("unroll") for (int n = 0; n < 2; ++n) _Pragma("unroll") for (int k = 0; k < 2; ++k) \
;         acc[ai][bj][m][n] = __builtin_amdgcn_mfma_f32_16x16x32_bf16(Bt[n][k], At[m][k], acc[ai][bj][m][n], 0, 0, 0); __builtin_amdgcn_s_setprio(0); } while (0)
; #define PG8_WAIT_V(n) asm volatile("s_waitcnt vmcnt(" #n ")" ::: "memory")
; #define PG8_WAIT_L(n) asm volatile("s_waitcnt lgkmcnt(" #n ")" ::: "memory")
; #define PG8_BAR __builtin_amdgcn_s_barrier()
; #define PG8_SCHED __builtin_amdgcn_sched_barrier(0)
; template <class Epi, class Sched, bool ALIGN_EPI = false, bool SP2 = false>
; __device__ __forceinline__ void gemm_phase(PG8_LAS unsigned char* lds, const Gemm g, const Sched& S, const Epi& E) {
;     ...
;             PG8_WAIT_V(8); PG8_WAIT_L(0); PG8_BAR; PG8_MMA(0, 0, At, B0); PG8_MMA(0, 1, At, B1); PG8_BAR; PG8_SCHED;
;             PG8_LDA(At, 0, 1); PG8_STAGE(PG8_SB(0, 0), b2, voffB); PG8_STAGE(PG8_SB(0, 1), b2 + hstep, voffB); PG8_STAGE(PG8_SA(0, 0), a2, voffA);
;             PG8_WAIT_V(8); PG8_WAIT_L(0); PG8_BAR; PG8_MMA(1, 0, At, B0); PG8_MMA(1, 1, At, B1); PG8_BAR; PG8_SCHED;
	s_setprio 1
	s_waitcnt lgkmcnt(0)
	v_mfma_f32_16x16x32_bf16 v[124:127], v[128:131], v[194:197], v[124:127]
	v_mfma_f32_16x16x32_bf16 v[120:123], v[136:139], v[194:197], v[120:123]
	v_mfma_f32_16x16x32_bf16 v[108:111], v[128:131], v[202:205], v[108:111]
	v_mfma_f32_16x16x32_bf16 v[104:107], v[136:139], v[202:205], v[104:107]
	v_mfma_f32_16x16x32_bf16 v[92:95], v[128:131], v[210:213], v[92:95]
	v_mfma_f32_16x16x32_bf16 v[88:91], v[136:139], v[210:213], v[88:91]
	v_mfma_f32_16x16x32_bf16 v[76:79], v[128:131], v[218:221], v[76:79]
	v_mfma_f32_16x16x32_bf16 v[72:75], v[136:139], v[218:221], v[72:75]
	v_mfma_f32_16x16x32_bf16 v[124:127], v[132:135], v[198:201], v[124:127]
	v_mfma_f32_16x16x32_bf16 v[120:123], v[140:143], v[198:201], v[120:123]
	v_mfma_f32_16x16x32_bf16 v[108:111], v[132:135], v[206:209], v[108:111]
	v_mfma_f32_16x16x32_bf16 v[104:107], v[140:143], v[206:209], v[104:107]
	v_mfma_f32_16x16x32_bf16 v[92:95], v[132:135], v[214:217], v[92:95]
	v_mfma_f32_16x16x32_bf16 v[88:91], v[140:143], v[214:217], v[88:91]
	v_mfma_f32_16x16x32_bf16 v[76:79], v[132:135], v[222:225], v[76:79]
	v_mfma_f32_16x16x32_bf16 v[72:75], v[140:143], v[222:225], v[72:75]
	s_setprio 0
	s_setprio 1
	v_mfma_f32_16x16x32_bf16 v[116:119], v[162:165], v[194:197], v[116:119]
	v_mfma_f32_16x16x32_bf16 v[112:115], v[170:173], v[194:197], v[112:115]
	v_mfma_f32_16x16x32_bf16 v[100:103], v[162:165], v[202:205], v[100:103]
	v_mfma_f32_16x16x32_bf16 v[96:99], v[170:173], v[202:205], v[96:99]
	v_mfma_f32_16x16x32_bf16 v[84:87], v[162:165], v[210:213], v[84:87]
	v_mfma_f32_16x16x32_bf16 v[80:83], v[170:173], v[210:213], v[80:83]
	v_mfma_f32_16x16x32_bf16 v[68:71], v[162:165], v[218:221], v[68:71]
	v_mfma_f32_16x16x32_bf16 v[64:67], v[170:173], v[218:221], v[64:67]
	v_mfma_f32_16x16x32_bf16 v[116:119], v[166:169], v[198:201], v[116:119]
	v_mfma_f32_16x16x32_bf16 v[112:115], v[190:193], v[198:201], v[112:115]
	v_mfma_f32_16x16x32_bf16 v[100:103], v[166:169], v[206:209], v[100:103]
	v_mfma_f32_16x16x32_bf16 v[96:99], v[190:193], v[206:209], v[96:99]
	v_mfma_f32_16x16x32_bf16 v[84:87], v[166:169], v[214:217], v[84:87]
	v_mfma_f32_16x16x32_bf16 v[80:83], v[190:193], v[214:217], v[80:83]
	v_mfma_f32_16x16x32_bf16 v[68:71], v[166:169], v[222:225], v[68:71]
	v_mfma_f32_16x16x32_bf16 v[64:67], v[190:193], v[222:225], v[64:67]
	s_setprio 0
	s_barrier
	s_add_i32 s54, s47, s33
	v_lshl_add_u64 v[226:227], s[10:11], 0, v[146:147]
	s_mov_b32 m0, s54
	ds_read_b128 v[194:197], v185 offset:16384
	ds_read_b128 v[198:201], v185 offset:17408
	ds_read_b128 v[202:205], v185 offset:18432
	ds_read_b128 v[206:209], v185 offset:19456
	ds_read_b128 v[210:213], v185 offset:20480
	ds_read_b128 v[214:217], v185 offset:21504
	ds_read_b128 v[218:221], v185 offset:22528
	ds_read_b128 v[222:225], v185 offset:23552
	global_load_lds_dwordx4 v[226:227], off
	s_add_i32 m0, s54, 0x2000
	s_add_u32 s54, s10, 0x40000
	v_lshl_add_u64 v[228:229], s[10:11], 0, v[150:151]
	s_addc_u32 s55, s11, 0
	s_add_i32 s56, s48, s33
	global_load_lds_dwordx4 v[228:229], off
	s_mov_b32 m0, s56
	v_lshl_add_u64 v[232:233], s[30:31], 0, v[148:149]
	global_load_lds_dwordx4 v146, s[54:55]
	s_add_i32 m0, s56, 0x2000
	s_nop 0
	global_load_lds_dwordx4 v150, s[54:55]
	v_lshl_add_u64 v[230:231], s[30:31], 0, v[144:145]
	s_mov_b32 m0, s29
	s_nop 0
	global_load_lds_dwordx4 v[230:231], off
	s_mov_b32 m0, s38
	s_nop 0
	global_load_lds_dwordx4 v[232:233], off
	s_waitcnt vmcnt(8)
	s_waitcnt lgkmcnt(0)
	s_barrier
	s_setprio 1
	s_waitcnt lgkmcnt(0)
	v_mfma_f32_16x16x32_bf16 v[60:63], v[128:131], v[194:197], v[60:63]
	v_mfma_f32_16x16x32_bf16 v[56:59], v[136:139], v[194:197], v[56:59]
	v_mfma_f32_16x16x32_bf16 v[44:47], v[128:131], v[202:205], v[44:47]
	v_mfma_f32_16x16x32_bf16 v[40:43], v[136:139], v[202:205], v[40:43]
	v_mfma_f32_16x16x32_bf16 v[28:31], v[128:131], v[210:213], v[28:31]
	v_mfma_f32_16x16x32_bf16 v[24:27], v[136:139], v[210:213], v[24:27]
	v_mfma_f32_16x16x32_bf16 v[12:15], v[128:131], v[218:221], v[12:15]
	v_mfma_f32_16x16x32_bf16 v[8:11], v[136:139], v[218:221], v[8:11]
	v_mfma_f32_16x16x32_bf16 v[60:63], v[132:135], v[198:201], v[60:63]
	v_mfma_f32_16x16x32_bf16 v[56:59], v[140:143], v[198:201], v[56:59]
	v_mfma_f32_16x16x32_bf16 v[44:47], v[132:135], v[206:209], v[44:47]
	v_mfma_f32_16x16x32_bf16 v[40:43], v[140:143], v[206:209], v[40:43]
	v_mfma_f32_16x16x32_bf16 v[28:31], v[132:135], v[214:217], v[28:31]
	v_mfma_f32_16x16x32_bf16 v[24:27], v[140:143], v[214:217], v[24:27]
	v_mfma_f32_16x16x32_bf16 v[12:15], v[132:135], v[222:225], v[12:15]
	v_mfma_f32_16x16x32_bf16 v[8:11], v[140:143], v[222:225], v[8:11]
	s_setprio 0
	s_setprio 1
	v_mfma_f32_16x16x32_bf16 v[52:55], v[162:165], v[194:197], v[52:55]
	v_mfma_f32_16x16x32_bf16 v[48:51], v[170:173], v[194:197], v[48:51]
	v_mfma_f32_16x16x32_bf16 v[36:39], v[162:165], v[202:205], v[36:39]
	v_mfma_f32_16x16x32_bf16 v[32:35], v[170:173], v[202:205], v[32:35]
	v_mfma_f32_16x16x32_bf16 v[20:23], v[162:165], v[210:213], v[20:23]
	v_mfma_f32_16x16x32_bf16 v[16:19], v[170:173], v[210:213], v[16:19]
	v_mfma_f32_16x16x32_bf16 v[4:7], v[162:165], v[218:221], v[4:7]
	v_mfma_f32_16x16x32_bf16 v[0:3], v[170:173], v[218:221], v[0:3]
	v_mfma_f32_16x16x32_bf16 v[52:55], v[166:169], v[198:201], v[52:55]
	v_mfma_f32_16x16x32_bf16 v[48:51], v[190:193], v[198:201], v[48:51]
	v_mfma_f32_16x16x32_bf16 v[36:39], v[166:169], v[206:209], v[36:39]
	v_mfma_f32_16x16x32_bf16 v[32:35], v[190:193], v[206:209], v[32:35]
	v_mfma_f32_16x16x32_bf16 v[20:23], v[166:169], v[214:217], v[20:23]
	v_mfma_f32_16x16x32_bf16 v[16:19], v[190:193], v[214:217], v[16:19]
	v_mfma_f32_16x16x32_bf16 v[4:7], v[166:169], v[222:225], v[4:7]
	v_mfma_f32_16x16x32_bf16 v[0:3], v[190:193], v[222:225], v[0:3]
	s_setprio 0
	s_barrier
; #define PG8_STAGE(bufoff, gbase, voff) do { _Pragma("unroll") for (int _i = 0; _i < 2; ++_i) \
;         __builtin_amdgcn_global_load_lds((const unsigned*)((const char*)(gbase) + (voff)[_i]), (PG8_LAS unsigned*)(lds + (bufoff) + ldsw + _i * 8192), 16, 0, 0); } while (0)
; #define PG8_LDA(dst, b, h) do { _Pragma("unroll") for (int m = 0; m < 4; ++m) _Pragma("unroll") for (int k = 0; k < 2; ++k) dst[m][k] = *(const PG8_LAS bf16x8*)(lds + PG8_SA(b, h) + aoff + m * 2048 + k * 1024); } while (0)
; #define PG8_LDB(dst, b, h) do { _Pragma("unroll") for (int n = 0; n < 2; ++n) _Pragma("unroll") for (int k = 0; k < 2; ++k) dst[n][k] = *(const PG8_LAS bf16x8*)(lds + PG8_SB(b, h) + boff + n * 2048 + k * 1024); } while (0)
; #define PG8_MMA(ai, bj, At, Bt) do { __builtin_amdgcn_s_setprio(1); _Pragma("unroll") for (int m = 0; m < 4; ++m) _Pragma("unroll") for (int n = 0; n < 2; ++n) _Pragma("unroll") for (int k = 0; k < 2; ++k) \
;         acc[ai][bj][m][n] = __builtin_amdgcn_mfma_f32_16x16x32_bf16(Bt[n][k], At[m][k], acc[ai][bj][m][n], 0, 0, 0); __builtin_amdgcn_s_setprio(0); } while (0)
; #define PG8_WAIT_V(n) asm volatile("s_waitcnt vmcnt(" #n ")" ::: "memory")
; #define PG8_WAIT_L(n) asm volatile("s_waitcnt lgkmcnt(" #n ")" ::: "memory")
; #define PG8_BAR __builtin_amdgcn_s_barrier()
; #define PG8_SCHED __builtin_amdgcn_sched_barrier(0)
; template <class Epi, class Sched, bool ALIGN_EPI = false, bool SP2 = false>
; __device__ __forceinline__ void gemm_phase(PG8_LAS unsigned char* lds, const Gemm g, const Sched& S, const Epi& E) {
;     ...
;             PG8_LDB(B0, 1, 0); PG8_LDB(B1, 1, 1); PG8_SCHED; PG8_LDA(At, 1, 0); PG8_STAGE(PG8_SA(0, 1), a2 + hstep, voffA);
;             PG8_WAIT_V(8); PG8_WAIT_L(0); PG8_BAR; PG8_MMA(0, 0, At, B0); PG8_MMA(0, 1, At, B1); PG8_BAR; PG8_SCHED;
	s_add_i32 s54, 0, 0x18000
	s_add_i32 s55, 0, 0x1c000
	v_add_u32_e32 v140, s54, v177
	v_add_u32_e32 v189, s55, v177
	ds_read_b128 v[128:131], v140
	ds_read_b128 v[132:135], v140 offset:1024
	ds_read_b128 v[136:139], v140 offset:2048
	ds_read_b128 v[140:143], v140 offset:3072
	ds_read_b128 v[162:165], v189
	ds_read_b128 v[166:169], v189 offset:1024
	ds_read_b128 v[170:173], v189 offset:2048
	ds_read_b128 v[190:193], v189 offset:3072
	s_add_u32 s30, s30, 0x40000
	s_addc_u32 s31, s31, 0
	s_mov_b32 m0, s39
	ds_read_b128 v[194:197], v185 offset:32768
	ds_read_b128 v[198:201], v185 offset:33792
	ds_read_b128 v[202:205], v185 offset:34816
	ds_read_b128 v[206:209], v185 offset:35840
	ds_read_b128 v[210:213], v185 offset:36864
	ds_read_b128 v[214:217], v185 offset:37888
	ds_read_b128 v[218:221], v185 offset:38912
	ds_read_b128 v[222:225], v185 offset:39936
	global_load_lds_dwordx4 v144, s[30:31]
	v_lshl_add_u64 v[234:235], s[30:31], 0, v[148:149]
	s_mov_b32 m0, s40
	s_nop 0
	global_load_lds_dwordx4 v[234:235], off
	s_waitcnt vmcnt(8)
	s_waitcnt lgkmcnt(0)
	s_barrier
	s_setprio 1
	s_waitcnt lgkmcnt(0)
	v_mfma_f32_16x16x32_bf16 v[124:127], v[128:131], v[194:197], v[124:127]
	v_mfma_f32_16x16x32_bf16 v[120:123], v[136:139], v[194:197], v[120:123]
	v_mfma_f32_16x16x32_bf16 v[108:111], v[128:131], v[202:205], v[108:111]
	v_mfma_f32_16x16x32_bf16 v[104:107], v[136:139], v[202:205], v[104:107]
	v_mfma_f32_16x16x32_bf16 v[92:95], v[128:131], v[210:213], v[92:95]
	v_mfma_f32_16x16x32_bf16 v[88:91], v[136:139], v[210:213], v[88:91]
	v_mfma_f32_16x16x32_bf16 v[76:79], v[128:131], v[218:221], v[76:79]
	v_mfma_f32_16x16x32_bf16 v[72:75], v[136:139], v[218:221], v[72:75]
	v_mfma_f32_16x16x32_bf16 v[124:127], v[132:135], v[198:201], v[124:127]
	v_mfma_f32_16x16x32_bf16 v[120:123], v[140:143], v[198:201], v[120:123]
	v_mfma_f32_16x16x32_bf16 v[108:111], v[132:135], v[206:209], v[108:111]
	v_mfma_f32_16x16x32_bf16 v[104:107], v[140:143], v[206:209], v[104:107]
	v_mfma_f32_16x16x32_bf16 v[92:95], v[132:135], v[214:217], v[92:95]
	v_mfma_f32_16x16x32_bf16 v[88:91], v[140:143], v[214:217], v[88:91]
	v_mfma_f32_16x16x32_bf16 v[76:79], v[132:135], v[222:225], v[76:79]
	v_mfma_f32_16x16x32_bf16 v[72:75], v[140:143], v[222:225], v[72:75]
	s_setprio 0
	s_setprio 1
	v_mfma_f32_16x16x32_bf16 v[116:119], v[162:165], v[194:197], v[116:119]
	v_mfma_f32_16x16x32_bf16 v[112:115], v[170:173], v[194:197], v[112:115]
	v_mfma_f32_16x16x32_bf16 v[100:103], v[162:165], v[202:205], v[100:103]
	v_mfma_f32_16x16x32_bf16 v[96:99], v[170:173], v[202:205], v[96:99]
	v_mfma_f32_16x16x32_bf16 v[84:87], v[162:165], v[210:213], v[84:87]
	v_mfma_f32_16x16x32_bf16 v[80:83], v[170:173], v[210:213], v[80:83]
	v_mfma_f32_16x16x32_bf16 v[68:71], v[162:165], v[218:221], v[68:71]
	v_mfma_f32_16x16x32_bf16 v[64:67], v[170:173], v[218:221], v[64:67]
	v_mfma_f32_16x16x32_bf16 v[116:119], v[166:169], v[198:201], v[116:119]
	v_mfma_f32_16x16x32_bf16 v[112:115], v[190:193], v[198:201], v[112:115]
	v_mfma_f32_16x16x32_bf16 v[100:103], v[166:169], v[206:209], v[100:103]
	v_mfma_f32_16x16x32_bf16 v[96:99], v[190:193], v[206:209], v[96:99]
	v_mfma_f32_16x16x32_bf16 v[84:87], v[166:169], v[214:217], v[84:87]
	v_mfma_f32_16x16x32_bf16 v[80:83], v[190:193], v[214:217], v[80:83]
	v_mfma_f32_16x16x32_bf16 v[68:71], v[166:169], v[222:225], v[68:71]
	v_mfma_f32_16x16x32_bf16 v[64:67], v[190:193], v[222:225], v[64:67]
	s_setprio 0
	s_barrier
; #define PG8_STAGE(bufoff, gbase, voff) do { _Pragma("unroll") for (int _i = 0; _i < 2; ++_i) \
;         __builtin_amdgcn_global_load_lds((const unsigned*)((const char*)(gbase) + (voff)[_i]), (PG8_LAS unsigned*)(lds + (bufoff) + ldsw + _i * 8192), 16, 0, 0); } while (0)
; #define PG8_LDA(dst, b, h) do { _Pragma("unroll") for (int m = 0; m < 4; ++m) _Pragma("unroll") for (int k = 0; k < 2; ++k) dst[m][k] = *(const PG8_LAS bf16x8*)(lds + PG8_SA(b, h) + aoff + m * 2048 + k * 1024); } while (0)
; #define PG8_MMA(ai, bj, At, Bt) do { __builtin_amdgcn_s_setprio(1); _Pragma("unroll") for (int m = 0; m < 4; ++m) _Pragma("unroll") for (int n = 0; n < 2; ++n) _Pragma("unroll") for (int k = 0; k < 2; ++k) \
;         acc[ai][bj][m][n] = __builtin_amdgcn_mfma_f32_16x16x32_bf16(Bt[n][k], At[m][k], acc[ai][bj][m][n], 0, 0, 0); __builtin_amdgcn_s_setprio(0); } while (0)
; #define PG8_WAIT_V(n) asm volatile("s_waitcnt vmcnt(" #n ")" ::: "memory")
; #define PG8_WAIT_L(n) asm volatile("s_waitcnt lgkmcnt(" #n ")" ::: "memory")
; #define PG8_BAR __builtin_amdgcn_s_barrier()
; #define PG8_SCHED __builtin_amdgcn_sched_barrier(0)
; template <class Epi, class Sched, bool ALIGN_EPI = false, bool SP2 = false>
; __device__ __forceinline__ void gemm_phase(PG8_LAS unsigned char* lds, const Gemm g, const Sched& S, const Epi& E) {
;     ...
;             PG8_LDA(At, 1, 1); PG8_STAGE(PG8_SB(1, 0), b3, voffB); PG8_STAGE(PG8_SB(1, 1), b3 + hstep, voffB); PG8_STAGE(PG8_SA(1, 0), a3, voffA);
;             PG8_WAIT_V(8); PG8_WAIT_L(0); PG8_BAR; PG8_MMA(1, 0, At, B0); PG8_MMA(1, 1, At, B1); PG8_BAR; PG8_SCHED;
;     ...
;         if constexpr (ALIGN_EPI) { if (wr == 0) PG8_BAR; }
	s_add_i32 s30, s54, s33
	v_lshl_add_u64 v[226:227], v[226:227], 0, s[14:15]
	s_mov_b32 m0, s30
	ds_read_b128 v[194:197], v185 offset:49152
	ds_read_b128 v[198:201], v185 offset:50176
	ds_read_b128 v[202:205], v185 offset:51200
	ds_read_b128 v[206:209], v185 offset:52224
	ds_read_b128 v[210:213], v185 offset:53248
	ds_read_b128 v[214:217], v185 offset:54272
	ds_read_b128 v[218:221], v185 offset:55296
	ds_read_b128 v[222:225], v185 offset:56320
	global_load_lds_dwordx4 v[226:227], off
	s_add_i32 m0, s30, 0x2000
	s_add_u32 s10, s10, 0x40080
	v_lshl_add_u64 v[226:227], v[228:229], 0, s[14:15]
	s_addc_u32 s11, s11, 0
	s_add_i32 s30, s55, s33
	global_load_lds_dwordx4 v[226:227], off
	s_mov_b32 m0, s30
	s_nop 0
	global_load_lds_dwordx4 v146, s[10:11]
	s_add_i32 m0, s30, 0x2000
	s_nop 0
	global_load_lds_dwordx4 v150, s[10:11]
	v_lshl_add_u64 v[226:227], v[230:231], 0, s[14:15]
	s_mov_b32 m0, s45
	s_nop 0
	global_load_lds_dwordx4 v[226:227], off
	v_lshl_add_u64 v[226:227], v[232:233], 0, s[14:15]
	s_mov_b32 m0, s46
	s_nop 0
	global_load_lds_dwordx4 v[226:227], off
	s_waitcnt vmcnt(8)
	s_waitcnt lgkmcnt(0)
	s_barrier
	s_setprio 1
	s_waitcnt lgkmcnt(0)
	v_mfma_f32_16x16x32_bf16 v[60:63], v[128:131], v[194:197], v[60:63]
	v_mfma_f32_16x16x32_bf16 v[56:59], v[136:139], v[194:197], v[56:59]
	v_mfma_f32_16x16x32_bf16 v[44:47], v[128:131], v[202:205], v[44:47]
	v_mfma_f32_16x16x32_bf16 v[40:43], v[136:139], v[202:205], v[40:43]
	v_mfma_f32_16x16x32_bf16 v[28:31], v[128:131], v[210:213], v[28:31]
	v_mfma_f32_16x16x32_bf16 v[24:27], v[136:139], v[210:213], v[24:27]
	v_mfma_f32_16x16x32_bf16 v[12:15], v[128:131], v[218:221], v[12:15]
	v_mfma_f32_16x16x32_bf16 v[8:11], v[136:139], v[218:221], v[8:11]
	v_mfma_f32_16x16x32_bf16 v[60:63], v[132:135], v[198:201], v[60:63]
	v_mfma_f32_16x16x32_bf16 v[56:59], v[140:143], v[198:201], v[56:59]
	v_mfma_f32_16x16x32_bf16 v[44:47], v[132:135], v[206:209], v[44:47]
	v_mfma_f32_16x16x32_bf16 v[40:43], v[140:143], v[206:209], v[40:43]
	v_mfma_f32_16x16x32_bf16 v[28:31], v[132:135], v[214:217], v[28:31]
	v_mfma_f32_16x16x32_bf16 v[24:27], v[140:143], v[214:217], v[24:27]
	v_mfma_f32_16x16x32_bf16 v[12:15], v[132:135], v[222:225], v[12:15]
	v_mfma_f32_16x16x32_bf16 v[8:11], v[140:143], v[222:225], v[8:11]
	s_setprio 0
	s_setprio 1
	v_mfma_f32_16x16x32_bf16 v[52:55], v[162:165], v[194:197], v[52:55]
	v_mfma_f32_16x16x32_bf16 v[48:51], v[170:173], v[194:197], v[48:51]
	v_mfma_f32_16x16x32_bf16 v[36:39], v[162:165], v[202:205], v[36:39]
	v_mfma_f32_16x16x32_bf16 v[32:35], v[170:173], v[202:205], v[32:35]
	v_mfma_f32_16x16x32_bf16 v[20:23], v[162:165], v[210:213], v[20:23]
	v_mfma_f32_16x16x32_bf16 v[16:19], v[170:173], v[210:213], v[16:19]
	v_mfma_f32_16x16x32_bf16 v[4:7], v[162:165], v[218:221], v[4:7]
	v_mfma_f32_16x16x32_bf16 v[0:3], v[170:173], v[218:221], v[0:3]
	v_mfma_f32_16x16x32_bf16 v[52:55], v[166:169], v[198:201], v[52:55]
	v_mfma_f32_16x16x32_bf16 v[48:51], v[190:193], v[198:201], v[48:51]
	v_mfma_f32_16x16x32_bf16 v[36:39], v[166:169], v[206:209], v[36:39]
	v_mfma_f32_16x16x32_bf16 v[32:35], v[190:193], v[206:209], v[32:35]
	v_mfma_f32_16x16x32_bf16 v[20:23], v[166:169], v[214:217], v[20:23]
	v_mfma_f32_16x16x32_bf16 v[16:19], v[190:193], v[214:217], v[16:19]
	v_mfma_f32_16x16x32_bf16 v[4:7], v[166:169], v[222:225], v[4:7]
	v_mfma_f32_16x16x32_bf16 v[0:3], v[190:193], v[222:225], v[0:3]
	s_setprio 0
	s_barrier
	s_add_i32 s53, s53, 2
	s_add_u32 s4, s4, 0x100
	s_addc_u32 s5, s5, 0
	s_add_u32 s34, s34, 0x100
	s_addc_u32 s35, s35, 0
	s_cmp_gt_u32 s53, 13
	s_cbranch_scc0 .LBB0_765
	s_and_b64 vcc, exec, s[16:17]
	s_cbranch_vccz .LBB0_768
	s_barrier

; #define PG8_STAGE(bufoff, gbase, voff) do { _Pragma("unroll") for (int _i = 0; _i < 2; ++_i) \
;         __builtin_amdgcn_global_load_lds((const unsigned*)((const char*)(gbase) + (voff)[_i]), (PG8_LAS unsigned*)(lds + (bufoff) + ldsw + _i * 8192), 16, 0, 0); } while (0)
; #define PG8_LDA(dst, b, h) do { _Pragma("unroll") for (int m = 0; m < 4; ++m) _Pragma("unroll") for (int k = 0; k < 2; ++k) dst[m][k] = *(const PG8_LAS bf16x8*)(lds + PG8_SA(b, h) + aoff + m * 2048 + k * 1024); } while (0)
; #define PG8_LDB(dst, b, h) do { _Pragma("unroll") for (int n = 0; n < 2; ++n) _Pragma("unroll") for (int k = 0; k < 2; ++k) dst[n][k] = *(const PG8_LAS bf16x8*)(lds + PG8_SB(b, h) + boff + n * 2048 + k * 1024); } while (0)
; #define PG8_MMA(ai, bj, At, Bt) do { __builtin_amdgcn_s_setprio(1); _Pragma("unroll") for (int m = 0; m < 4; ++m) _Pragma("unroll") for (int n = 0; n < 2; ++n) _Pragma("unroll") for (int k = 0; k < 2; ++k) \
;         acc[ai][bj][m][n] = __builtin_amdgcn_mfma_f32_16x16x32_bf16(Bt[n][k], At[m][k], acc[ai][bj][m][n], 0, 0, 0); __builtin_amdgcn_s_setprio(0); } while (0)
; #define PG8_WAIT_V(n) asm volatile("s_waitcnt vmcnt(" #n ")" ::: "memory")
; #define PG8_WAIT_L(n) asm volatile("s_waitcnt lgkmcnt(" #n ")" ::: "memory")
; #define PG8_BAR __builtin_amdgcn_s_barrier()
; #define PG8_SCHED __builtin_amdgcn_sched_barrier(0)
; template <class Epi, class Sched, bool ALIGN_EPI = false, bool SP2 = false>
; __device__ __forceinline__ void gemm_phase(PG8_LAS unsigned char* lds, const Gemm g, const Sched& S, const Epi& E) {
;     ...
;             PG8_LDB(B0, 0, 0); PG8_LDB(B1, 0, 1); PG8_SCHED; PG8_LDA(At, 0, 0); PG8_STAGE(PG8_SA(1, 1), a1 + hstep, voffA);
;             PG8_WAIT_V(8); PG8_WAIT_L(0); PG8_BAR; PG8_MMA(0, 0, At, B0); PG8_MMA(0, 1, At, B1); PG8_BAR; PG8_SCHED;
;             PG8_LDA(At, 0, 1); PG8_STAGE(PG8_SB(0, 0), b2, voffB); PG8_STAGE(PG8_SB(0, 1), b2 + hstep, voffB); PG8_STAGE(PG8_SA(0, 0), a2, voffA);
;             PG8_WAIT_V(8); PG8_WAIT_L(0); PG8_BAR; PG8_MMA(1, 0, At, B0); PG8_MMA(1, 1, At, B1); PG8_BAR; PG8_SCHED;
.LBB0_1268:
	v_add_u32_e32 v153, s73, v149
	ds_read_b128 v[144:147], v153
	ds_read_b128 v[154:157], v153 offset:1024
	ds_read_b128 v[158:161], v153 offset:2048
	s_waitcnt lgkmcnt(0)
	ds_read_b128 v[162:165], v153 offset:3072
	v_add_u32_e32 v153, s74, v149
	ds_read_b128 v[166:169], v153
	ds_read_b128 v[170:173], v153 offset:1024
	ds_read_b128 v[174:177], v153 offset:2048
	ds_read_b128 v[180:183], v153 offset:3072
	s_add_u32 s36, s38, 0xfffc0080
	s_addc_u32 s37, s39, -1
	s_cmp_eq_u32 s64, 12
	s_cselect_b32 s45, s27, s37
	s_cselect_b32 s44, s35, s36
	s_cselect_b32 s37, s25, s63
	s_cselect_b32 s36, s61, s62
	s_add_i32 m0, s49, 0xc000
	ds_read_b128 v[184:187], v151
	ds_read_b128 v[188:191], v151 offset:1024
	ds_read_b128 v[192:195], v151 offset:2048
	ds_read_b128 v[196:199], v151 offset:3072
	ds_read_b128 v[200:203], v151 offset:4096
	ds_read_b128 v[204:207], v151 offset:5120
	ds_read_b128 v[208:211], v151 offset:6144
	ds_read_b128 v[212:215], v151 offset:7168
	global_load_lds_dwordx4 v136, s[38:39]
	s_add_i32 m0, s49, 0xe000
	s_nop 0
	global_load_lds_dwordx4 v138, s[38:39]
	s_waitcnt vmcnt(8)
	s_waitcnt lgkmcnt(0)
	s_barrier
	s_setprio 1
	s_waitcnt lgkmcnt(0)
	v_mfma_f32_16x16x32_bf16 v[120:123], v[144:147], v[184:187], v[120:123]
	v_mfma_f32_16x16x32_bf16 v[124:127], v[158:161], v[184:187], v[124:127]
	v_mfma_f32_16x16x32_bf16 v[100:103], v[144:147], v[192:195], v[100:103]
	v_mfma_f32_16x16x32_bf16 v[104:107], v[158:161], v[192:195], v[104:107]
	v_mfma_f32_16x16x32_bf16 v[84:87], v[144:147], v[200:203], v[84:87]
	v_mfma_f32_16x16x32_bf16 v[88:91], v[158:161], v[200:203], v[88:91]
	v_mfma_f32_16x16x32_bf16 v[68:71], v[144:147], v[208:211], v[68:71]
	v_mfma_f32_16x16x32_bf16 v[72:75], v[158:161], v[208:211], v[72:75]
	v_mfma_f32_16x16x32_bf16 v[120:123], v[154:157], v[188:191], v[120:123]
	v_mfma_f32_16x16x32_bf16 v[124:127], v[162:165], v[188:191], v[124:127]
	v_mfma_f32_16x16x32_bf16 v[100:103], v[154:157], v[196:199], v[100:103]
	v_mfma_f32_16x16x32_bf16 v[104:107], v[162:165], v[196:199], v[104:107]
	v_mfma_f32_16x16x32_bf16 v[84:87], v[154:157], v[204:207], v[84:87]
	v_mfma_f32_16x16x32_bf16 v[88:91], v[162:165], v[204:207], v[88:91]
	v_mfma_f32_16x16x32_bf16 v[68:71], v[154:157], v[212:215], v[68:71]
	v_mfma_f32_16x16x32_bf16 v[72:75], v[162:165], v[212:215], v[72:75]
	s_setprio 0
	s_setprio 1
	v_mfma_f32_16x16x32_bf16 v[112:115], v[166:169], v[184:187], v[112:115]
	v_mfma_f32_16x16x32_bf16 v[116:119], v[174:177], v[184:187], v[116:119]
	v_mfma_f32_16x16x32_bf16 v[96:99], v[166:169], v[192:195], v[96:99]
	v_mfma_f32_16x16x32_bf16 v[108:111], v[174:177], v[192:195], v[108:111]
	v_mfma_f32_16x16x32_bf16 v[80:83], v[166:169], v[200:203], v[80:83]
	v_mfma_f32_16x16x32_bf16 v[92:95], v[174:177], v[200:203], v[92:95]
	v_mfma_f32_16x16x32_bf16 v[60:63], v[166:169], v[208:211], v[60:63]
	v_mfma_f32_16x16x32_bf16 v[76:79], v[174:177], v[208:211], v[76:79]
	v_mfma_f32_16x16x32_bf16 v[112:115], v[170:173], v[188:191], v[112:115]
	v_mfma_f32_16x16x32_bf16 v[116:119], v[180:183], v[188:191], v[116:119]
	v_mfma_f32_16x16x32_bf16 v[96:99], v[170:173], v[196:199], v[96:99]
	v_mfma_f32_16x16x32_bf16 v[108:111], v[180:183], v[196:199], v[108:111]
	v_mfma_f32_16x16x32_bf16 v[80:83], v[170:173], v[204:207], v[80:83]
	v_mfma_f32_16x16x32_bf16 v[92:95], v[180:183], v[204:207], v[92:95]
	v_mfma_f32_16x16x32_bf16 v[60:63], v[170:173], v[212:215], v[60:63]
	v_mfma_f32_16x16x32_bf16 v[76:79], v[180:183], v[212:215], v[76:79]
	s_setprio 0
	s_barrier
	s_add_i32 s65, s73, s46
	v_lshl_add_u64 v[216:217], s[36:37], 0, v[130:131]
	s_mov_b32 m0, s65
	ds_read_b128 v[184:187], v151 offset:16384
	ds_read_b128 v[188:191], v151 offset:17408
	ds_read_b128 v[192:195], v151 offset:18432
	ds_read_b128 v[196:199], v151 offset:19456
	ds_read_b128 v[200:203], v151 offset:20480
	ds_read_b128 v[204:207], v151 offset:21504
	ds_read_b128 v[208:211], v151 offset:22528
	ds_read_b128 v[212:215], v151 offset:23552
	global_load_lds_dwordx4 v[216:217], off
	s_add_i32 m0, s65, 0x2000
	s_add_u32 s66, s36, 0x40000
	v_lshl_add_u64 v[218:219], s[36:37], 0, v[134:135]
	s_addc_u32 s67, s37, 0
	s_add_i32 s65, s74, s46
	global_load_lds_dwordx4 v[218:219], off
	s_mov_b32 m0, s65
	v_lshl_add_u64 v[222:223], s[44:45], 0, v[132:133]
	global_load_lds_dwordx4 v130, s[66:67]
	s_add_i32 m0, s65, 0x2000
	s_nop 0
	global_load_lds_dwordx4 v134, s[66:67]
	v_lshl_add_u64 v[220:221], s[44:45], 0, v[128:129]
	s_mov_b32 m0, s49
	s_nop 0
	global_load_lds_dwordx4 v[220:221], off
	s_mov_b32 m0, s50
	s_nop 0
	global_load_lds_dwordx4 v[222:223], off
	s_waitcnt vmcnt(8)
	s_waitcnt lgkmcnt(0)
	s_barrier
; #define PG8_STAGE(bufoff, gbase, voff) do { _Pragma("unroll") for (int _i = 0; _i < 2; ++_i) \
;         __builtin_amdgcn_global_load_lds((const unsigned*)((const char*)(gbase) + (voff)[_i]), (PG8_LAS unsigned*)(lds + (bufoff) + ldsw + _i * 8192), 16, 0, 0); } while (0)
; #define PG8_LDA(dst, b, h) do { _Pragma("unroll") for (int m = 0; m < 4; ++m) _Pragma("unroll") for (int k = 0; k < 2; ++k) dst[m][k] = *(const PG8_LAS bf16x8*)(lds + PG8_SA(b, h) + aoff + m * 2048 + k * 1024); } while (0)
; #define PG8_LDB(dst, b, h) do { _Pragma("unroll") for (int n = 0; n < 2; ++n) _Pragma("unroll") for (int k = 0; k < 2; ++k) dst[n][k] = *(const PG8_LAS bf16x8*)(lds + PG8_SB(b, h) + boff + n * 2048 + k * 1024); } while (0)
; #define PG8_MMA(ai, bj, At, Bt) do { __builtin_amdgcn_s_setprio(1); _Pragma("unroll") for (int m = 0; m < 4; ++m) _Pragma("unroll") for (int n = 0; n < 2; ++n) _Pragma("unroll") for (int k = 0; k < 2; ++k) \
;         acc[ai][bj][m][n] = __builtin_amdgcn_mfma_f32_16x16x32_bf16(Bt[n][k], At[m][k], acc[ai][bj][m][n], 0, 0, 0); __builtin_amdgcn_s_setprio(0); } while (0)
; #define PG8_WAIT_V(n) asm volatile("s_waitcnt vmcnt(" #n ")" ::: "memory")
; #define PG8_WAIT_L(n) asm volatile("s_waitcnt lgkmcnt(" #n ")" ::: "memory")
; #define PG8_BAR __builtin_amdgcn_s_barrier()
; #define PG8_SCHED __builtin_amdgcn_sched_barrier(0)
; template <class Epi, class Sched, bool ALIGN_EPI = false, bool SP2 = false>
; __device__ __forceinline__ void gemm_phase(PG8_LAS unsigned char* lds, const Gemm g, const Sched& S, const Epi& E) {
;     ...
;             PG8_WAIT_V(8); PG8_WAIT_L(0); PG8_BAR; PG8_MMA(1, 0, At, B0); PG8_MMA(1, 1, At, B1); PG8_BAR; PG8_SCHED;
;             PG8_LDB(B0, 1, 0); PG8_LDB(B1, 1, 1); PG8_SCHED; PG8_LDA(At, 1, 0); PG8_STAGE(PG8_SA(0, 1), a2 + hstep, voffA);
;             PG8_WAIT_V(8); PG8_WAIT_L(0); PG8_BAR; PG8_MMA(0, 0, At, B0); PG8_MMA(0, 1, At, B1); PG8_BAR; PG8_SCHED;
	s_setprio 1
	s_waitcnt lgkmcnt(0)
	v_mfma_f32_16x16x32_bf16 v[48:51], v[144:147], v[184:187], v[48:51]
	v_mfma_f32_16x16x32_bf16 v[52:55], v[158:161], v[184:187], v[52:55]
	v_mfma_f32_16x16x32_bf16 v[20:23], v[144:147], v[192:195], v[20:23]
	v_mfma_f32_16x16x32_bf16 v[24:27], v[158:161], v[192:195], v[24:27]
	v_mfma_f32_16x16x32_bf16 v[32:35], v[144:147], v[200:203], v[32:35]
	v_mfma_f32_16x16x32_bf16 v[36:39], v[158:161], v[200:203], v[36:39]
	v_mfma_f32_16x16x32_bf16 v[4:7], v[144:147], v[208:211], v[4:7]
	v_mfma_f32_16x16x32_bf16 v[8:11], v[158:161], v[208:211], v[8:11]
	v_mfma_f32_16x16x32_bf16 v[48:51], v[154:157], v[188:191], v[48:51]
	v_mfma_f32_16x16x32_bf16 v[52:55], v[162:165], v[188:191], v[52:55]
	v_mfma_f32_16x16x32_bf16 v[20:23], v[154:157], v[196:199], v[20:23]
	v_mfma_f32_16x16x32_bf16 v[24:27], v[162:165], v[196:199], v[24:27]
	v_mfma_f32_16x16x32_bf16 v[32:35], v[154:157], v[204:207], v[32:35]
	v_mfma_f32_16x16x32_bf16 v[36:39], v[162:165], v[204:207], v[36:39]
	v_mfma_f32_16x16x32_bf16 v[4:7], v[154:157], v[212:215], v[4:7]
	v_mfma_f32_16x16x32_bf16 v[8:11], v[162:165], v[212:215], v[8:11]
	s_setprio 0
	s_setprio 1
	v_mfma_f32_16x16x32_bf16 v[44:47], v[166:169], v[184:187], v[44:47]
	v_mfma_f32_16x16x32_bf16 v[56:59], v[174:177], v[184:187], v[56:59]
	v_mfma_f32_16x16x32_bf16 v[16:19], v[166:169], v[192:195], v[16:19]
	v_mfma_f32_16x16x32_bf16 v[64:67], v[174:177], v[192:195], v[64:67]
	v_mfma_f32_16x16x32_bf16 v[28:31], v[166:169], v[200:203], v[28:31]
	v_mfma_f32_16x16x32_bf16 v[40:43], v[174:177], v[200:203], v[40:43]
	v_mfma_f32_16x16x32_bf16 v[0:3], v[166:169], v[208:211], v[0:3]
	v_mfma_f32_16x16x32_bf16 v[12:15], v[174:177], v[208:211], v[12:15]
	v_mfma_f32_16x16x32_bf16 v[44:47], v[170:173], v[188:191], v[44:47]
	v_mfma_f32_16x16x32_bf16 v[56:59], v[180:183], v[188:191], v[56:59]
	v_mfma_f32_16x16x32_bf16 v[16:19], v[170:173], v[196:199], v[16:19]
	v_mfma_f32_16x16x32_bf16 v[64:67], v[180:183], v[196:199], v[64:67]
	v_mfma_f32_16x16x32_bf16 v[28:31], v[170:173], v[204:207], v[28:31]
	v_mfma_f32_16x16x32_bf16 v[40:43], v[180:183], v[204:207], v[40:43]
	v_mfma_f32_16x16x32_bf16 v[0:3], v[170:173], v[212:215], v[0:3]
	v_mfma_f32_16x16x32_bf16 v[12:15], v[180:183], v[212:215], v[12:15]
	s_setprio 0
	s_barrier
	s_add_i32 s65, 0, 0x18000
	v_add_u32_e32 v153, s65, v149
	s_add_i32 s66, 0, 0x1c000
	ds_read_b128 v[144:147], v153
	ds_read_b128 v[154:157], v153 offset:1024
	ds_read_b128 v[158:161], v153 offset:2048
	ds_read_b128 v[162:165], v153 offset:3072
	v_add_u32_e32 v153, s66, v149
	ds_read_b128 v[166:169], v153
	ds_read_b128 v[170:173], v153 offset:1024
	ds_read_b128 v[174:177], v153 offset:2048
	ds_read_b128 v[180:183], v153 offset:3072
	s_add_u32 s44, s44, 0x40000
	s_addc_u32 s45, s45, 0
	s_mov_b32 m0, s51
	ds_read_b128 v[184:187], v151 offset:32768
	ds_read_b128 v[188:191], v151 offset:33792
	ds_read_b128 v[192:195], v151 offset:34816
	ds_read_b128 v[196:199], v151 offset:35840
	ds_read_b128 v[200:203], v151 offset:36864
	ds_read_b128 v[204:207], v151 offset:37888
	ds_read_b128 v[208:211], v151 offset:38912
	ds_read_b128 v[212:215], v151 offset:39936
	global_load_lds_dwordx4 v128, s[44:45]
	v_lshl_add_u64 v[224:225], s[44:45], 0, v[132:133]
	s_mov_b32 m0, s69
	s_nop 0
	global_load_lds_dwordx4 v[224:225], off
	s_waitcnt vmcnt(8)
	s_waitcnt lgkmcnt(0)
	s_barrier
	s_setprio 1
	s_waitcnt lgkmcnt(0)
	v_mfma_f32_16x16x32_bf16 v[120:123], v[144:147], v[184:187], v[120:123]
	v_mfma_f32_16x16x32_bf16 v[124:127], v[158:161], v[184:187], v[124:127]
	v_mfma_f32_16x16x32_bf16 v[100:103], v[144:147], v[192:195], v[100:103]
	v_mfma_f32_16x16x32_bf16 v[104:107], v[158:161], v[192:195], v[104:107]
	v_mfma_f32_16x16x32_bf16 v[84:87], v[144:147], v[200:203], v[84:87]
	v_mfma_f32_16x16x32_bf16 v[88:91], v[158:161], v[200:203], v[88:91]
	v_mfma_f32_16x16x32_bf16 v[68:71], v[144:147], v[208:211], v[68:71]
	v_mfma_f32_16x16x32_bf16 v[72:75], v[158:161], v[208:211], v[72:75]
	v_mfma_f32_16x16x32_bf16 v[120:123], v[154:157], v[188:191], v[120:123]
	v_mfma_f32_16x16x32_bf16 v[124:127], v[162:165], v[188:191], v[124:127]
	v_mfma_f32_16x16x32_bf16 v[100:103], v[154:157], v[196:199], v[100:103]
	v_mfma_f32_16x16x32_bf16 v[104:107], v[162:165], v[196:199], v[104:107]
	v_mfma_f32_16x16x32_bf16 v[84:87], v[154:157], v[204:207], v[84:87]
	v_mfma_f32_16x16x32_bf16 v[88:91], v[162:165], v[204:207], v[88:91]
	v_mfma_f32_16x16x32_bf16 v[68:71], v[154:157], v[212:215], v[68:71]
	v_mfma_f32_16x16x32_bf16 v[72:75], v[162:165], v[212:215], v[72:75]
	s_setprio 0
	s_setprio 1
	v_mfma_f32_16x16x32_bf16 v[112:115], v[166:169], v[184:187], v[112:115]
	v_mfma_f32_16x16x32_bf16 v[116:119], v[174:177], v[184:187], v[116:119]
	v_mfma_f32_16x16x32_bf16 v[96:99], v[166:169], v[192:195], v[96:99]
	v_mfma_f32_16x16x32_bf16 v[108:111], v[174:177], v[192:195], v[108:111]
	v_mfma_f32_16x16x32_bf16 v[80:83], v[166:169], v[200:203], v[80:83]
	v_mfma_f32_16x16x32_bf16 v[92:95], v[174:177], v[200:203], v[92:95]
	v_mfma_f32_16x16x32_bf16 v[60:63], v[166:169], v[208:211], v[60:63]
	v_mfma_f32_16x16x32_bf16 v[76:79], v[174:177], v[208:211], v[76:79]
	v_mfma_f32_16x16x32_bf16 v[112:115], v[170:173], v[188:191], v[112:115]
	v_mfma_f32_16x16x32_bf16 v[116:119], v[180:183], v[188:191], v[116:119]
	v_mfma_f32_16x16x32_bf16 v[96:99], v[170:173], v[196:199], v[96:99]
	v_mfma_f32_16x16x32_bf16 v[108:111], v[180:183], v[196:199], v[108:111]
	v_mfma_f32_16x16x32_bf16 v[80:83], v[170:173], v[204:207], v[80:83]
	v_mfma_f32_16x16x32_bf16 v[92:95], v[180:183], v[204:207], v[92:95]
	v_mfma_f32_16x16x32_bf16 v[60:63], v[170:173], v[212:215], v[60:63]
	v_mfma_f32_16x16x32_bf16 v[76:79], v[180:183], v[212:215], v[76:79]
	s_setprio 0
	s_barrier
; #define PG8_STAGE(bufoff, gbase, voff) do { _Pragma("unroll") for (int _i = 0; _i < 2; ++_i) \
;         __builtin_amdgcn_global_load_lds((const unsigned*)((const char*)(gbase) + (voff)[_i]), (PG8_LAS unsigned*)(lds + (bufoff) + ldsw + _i * 8192), 16, 0, 0); } while (0)
; #define PG8_LDA(dst, b, h) do { _Pragma("unroll") for (int m = 0; m < 4; ++m) _Pragma("unroll") for (int k = 0; k < 2; ++k) dst[m][k] = *(const PG8_LAS bf16x8*)(lds + PG8_SA(b, h) + aoff + m * 2048 + k * 1024); } while (0)
; #define PG8_MMA(ai, bj, At, Bt) do { __builtin_amdgcn_s_setprio(1); _Pragma("unroll") for (int m = 0; m < 4; ++m) _Pragma("unroll") for (int n = 0; n < 2; ++n) _Pragma("unroll") for (int k = 0; k < 2; ++k) \
;         acc[ai][bj][m][n] = __builtin_amdgcn_mfma_f32_16x16x32_bf16(Bt[n][k], At[m][k], acc[ai][bj][m][n], 0, 0, 0); __builtin_amdgcn_s_setprio(0); } while (0)
; #define PG8_WAIT_V(n) asm volatile("s_waitcnt vmcnt(" #n ")" ::: "memory")
; #define PG8_WAIT_L(n) asm volatile("s_waitcnt lgkmcnt(" #n ")" ::: "memory")
; #define PG8_BAR __builtin_amdgcn_s_barrier()
; #define PG8_SCHED __builtin_amdgcn_sched_barrier(0)
; template <class Epi, class Sched, bool ALIGN_EPI = false, bool SP2 = false>
; __device__ __forceinline__ void gemm_phase(PG8_LAS unsigned char* lds, const Gemm g, const Sched& S, const Epi& E) {
;     ...
;             PG8_LDA(At, 1, 1); PG8_STAGE(PG8_SB(1, 0), b3, voffB); PG8_STAGE(PG8_SB(1, 1), b3 + hstep, voffB); PG8_STAGE(PG8_SA(1, 0), a3, voffA);
;             PG8_WAIT_V(8); PG8_WAIT_L(0); PG8_BAR; PG8_MMA(1, 0, At, B0); PG8_MMA(1, 1, At, B1); PG8_BAR; PG8_SCHED;
	s_add_i32 s44, s65, s46
	v_lshl_add_u64 v[216:217], v[216:217], 0, s[20:21]
	s_mov_b32 m0, s44
	ds_read_b128 v[184:187], v151 offset:49152
	ds_read_b128 v[188:191], v151 offset:50176
	ds_read_b128 v[192:195], v151 offset:51200
	ds_read_b128 v[196:199], v151 offset:52224
	ds_read_b128 v[200:203], v151 offset:53248
	ds_read_b128 v[204:207], v151 offset:54272
	ds_read_b128 v[208:211], v151 offset:55296
	ds_read_b128 v[212:215], v151 offset:56320
	global_load_lds_dwordx4 v[216:217], off
	s_add_i32 m0, s44, 0x2000
	s_add_u32 s36, s36, 0x40080
	v_lshl_add_u64 v[216:217], v[218:219], 0, s[20:21]
	s_addc_u32 s37, s37, 0
	s_add_i32 s44, s66, s46
	global_load_lds_dwordx4 v[216:217], off
	s_mov_b32 m0, s44
	s_nop 0
	global_load_lds_dwordx4 v130, s[36:37]
	s_add_i32 m0, s44, 0x2000
	s_nop 0
	global_load_lds_dwordx4 v134, s[36:37]
	v_lshl_add_u64 v[216:217], v[220:221], 0, s[20:21]
	s_mov_b32 m0, s71
	s_nop 0
	global_load_lds_dwordx4 v[216:217], off
	v_lshl_add_u64 v[216:217], v[222:223], 0, s[20:21]
	s_mov_b32 m0, s72
	s_nop 0
	global_load_lds_dwordx4 v[216:217], off
	s_waitcnt vmcnt(8)
	s_waitcnt lgkmcnt(0)
	s_barrier
	s_setprio 1
	s_waitcnt lgkmcnt(0)
	v_mfma_f32_16x16x32_bf16 v[48:51], v[144:147], v[184:187], v[48:51]
	v_mfma_f32_16x16x32_bf16 v[52:55], v[158:161], v[184:187], v[52:55]
	v_mfma_f32_16x16x32_bf16 v[20:23], v[144:147], v[192:195], v[20:23]
	v_mfma_f32_16x16x32_bf16 v[24:27], v[158:161], v[192:195], v[24:27]
	v_mfma_f32_16x16x32_bf16 v[32:35], v[144:147], v[200:203], v[32:35]
	v_mfma_f32_16x16x32_bf16 v[36:39], v[158:161], v[200:203], v[36:39]
	v_mfma_f32_16x16x32_bf16 v[4:7], v[144:147], v[208:211], v[4:7]
	v_mfma_f32_16x16x32_bf16 v[8:11], v[158:161], v[208:211], v[8:11]
	v_mfma_f32_16x16x32_bf16 v[48:51], v[154:157], v[188:191], v[48:51]
	v_mfma_f32_16x16x32_bf16 v[52:55], v[162:165], v[188:191], v[52:55]
	v_mfma_f32_16x16x32_bf16 v[20:23], v[154:157], v[196:199], v[20:23]
	v_mfma_f32_16x16x32_bf16 v[24:27], v[162:165], v[196:199], v[24:27]
	v_mfma_f32_16x16x32_bf16 v[32:35], v[154:157], v[204:207], v[32:35]
	v_mfma_f32_16x16x32_bf16 v[36:39], v[162:165], v[204:207], v[36:39]
	v_mfma_f32_16x16x32_bf16 v[4:7], v[154:157], v[212:215], v[4:7]
	v_mfma_f32_16x16x32_bf16 v[8:11], v[162:165], v[212:215], v[8:11]
	s_setprio 0
	s_setprio 1
	v_mfma_f32_16x16x32_bf16 v[44:47], v[166:169], v[184:187], v[44:47]
	v_mfma_f32_16x16x32_bf16 v[56:59], v[174:177], v[184:187], v[56:59]
	v_mfma_f32_16x16x32_bf16 v[16:19], v[166:169], v[192:195], v[16:19]
	v_mfma_f32_16x16x32_bf16 v[64:67], v[174:177], v[192:195], v[64:67]
	v_mfma_f32_16x16x32_bf16 v[28:31], v[166:169], v[200:203], v[28:31]
	v_mfma_f32_16x16x32_bf16 v[40:43], v[174:177], v[200:203], v[40:43]
	v_mfma_f32_16x16x32_bf16 v[0:3], v[166:169], v[208:211], v[0:3]
	v_mfma_f32_16x16x32_bf16 v[12:15], v[174:177], v[208:211], v[12:15]
	v_mfma_f32_16x16x32_bf16 v[44:47], v[170:173], v[188:191], v[44:47]
	v_mfma_f32_16x16x32_bf16 v[56:59], v[180:183], v[188:191], v[56:59]
	v_mfma_f32_16x16x32_bf16 v[16:19], v[170:173], v[196:199], v[16:19]
	v_mfma_f32_16x16x32_bf16 v[64:67], v[180:183], v[196:199], v[64:67]
	v_mfma_f32_16x16x32_bf16 v[28:31], v[170:173], v[204:207], v[28:31]
	v_mfma_f32_16x16x32_bf16 v[40:43], v[180:183], v[204:207], v[40:43]
	v_mfma_f32_16x16x32_bf16 v[0:3], v[170:173], v[212:215], v[0:3]
	v_mfma_f32_16x16x32_bf16 v[12:15], v[180:183], v[212:215], v[12:15]
	s_setprio 0
	s_barrier
	s_add_i32 s64, s64, 2
	s_add_u32 s38, s38, 0x100
	s_addc_u32 s39, s39, 0
	s_add_u32 s62, s62, 0x100
	s_addc_u32 s63, s63, 0
	s_cmp_gt_u32 s64, 13
	s_cbranch_scc0 .LBB0_1268
	s_and_b64 vcc, exec, s[22:23]
	s_cbranch_vccz .LBB0_1271
	s_barrier

; #define PG8_STAGE(bufoff, gbase, voff) do { _Pragma("unroll") for (int _i = 0; _i < 2; ++_i) \
;         __builtin_amdgcn_global_load_lds((const unsigned*)((const char*)(gbase) + (voff)[_i]), (PG8_LAS unsigned*)(lds + (bufoff) + ldsw + _i * 8192), 16, 0, 0); } while (0)
; #define PG8_LDA(dst, b, h) do { _Pragma("unroll") for (int m = 0; m < 4; ++m) _Pragma("unroll") for (int k = 0; k < 2; ++k) dst[m][k] = *(const PG8_LAS bf16x8*)(lds + PG8_SA(b, h) + aoff + m * 2048 + k * 1024); } while (0)
; #define PG8_LDB(dst, b, h) do { _Pragma("unroll") for (int n = 0; n < 2; ++n) _Pragma("unroll") for (int k = 0; k < 2; ++k) dst[n][k] = *(const PG8_LAS bf16x8*)(lds + PG8_SB(b, h) + boff + n * 2048 + k * 1024); } while (0)
; #define PG8_WAIT_V(n) asm volatile("s_waitcnt vmcnt(" #n ")" ::: "memory")
; #define PG8_WAIT_L(n) asm volatile("s_waitcnt lgkmcnt(" #n ")" ::: "memory")
; #define PG8_BAR __builtin_amdgcn_s_barrier()
; #define PG8_SCHED __builtin_amdgcn_sched_barrier(0)
; template <class Epi, class Sched, bool ALIGN_EPI = false, bool SP2 = false>
; __device__ __forceinline__ void gemm_phase(PG8_LAS unsigned char* lds, const Gemm g, const Sched& S, const Epi& E) {
;     ...
;         const bool has_next = S.next(ui + 1, nxt);
;         const char* nA = has_next ? (const char*)g.A + (size_t)nxt.pm * tstep : cA; const char* nB = has_next ? (const char*)g.Bt + (size_t)nxt.pn * tstep : cB;
;         for (int t = 0; t < nt; t += 2) {
;             const bool last = (t == nt - 2);
;             const char* a1 = cA + (size_t)(t + 1) * kstep;
;             const char* a2 = last ? nA : cA + (size_t)(t + 2) * kstep; const char* b2 = last ? nB : cB + (size_t)(t + 2) * kstep;
;             const char* a3 = a2 + kstep; const char* b3 = b2 + kstep;
;             if (last && has_next) S.a_ready(nxt);
;             if constexpr (SP2) {
;             PG8_LDB(B0, 0, 0); PG8_LDB(B1, 0, 1); PG8_SCHED; PG8_LDA(At, 0, 0); PG8_STAGE(PG8_SA(1, 1), a1 + hstep, voffA);
;             PG8_WAIT_V(8); PG8_WAIT_L(0); PG8_BAR; PG8_MMA(0, 0, At, B0); PG8_MMA(0, 1, At, B1); PG8_BAR; PG8_SCHED;
;             PG8_LDA(At, 0, 1); PG8_STAGE(PG8_SB(0, 0), b2, voffB); PG8_STAGE(PG8_SB(0, 1), b2 + hstep, voffB); PG8_STAGE(PG8_SA(0, 0), a2, voffA);
;             PG8_WAIT_V(8); PG8_WAIT_L(0); PG8_BAR; PG8_MMA(1, 0, At, B0); PG8_MMA(1, 1, At, B1); PG8_BAR; PG8_SCHED;
.LBB0_1360:
	s_ashr_i32 s15, s14, 31
	s_lshl_b64 s[16:17], s[14:15], 19
	v_readlane_b32 s18, v237, 35
	v_readlane_b32 s19, v237, 36
	s_add_u32 s16, s18, s16
	s_addc_u32 s17, s19, s17
	s_and_b64 s[18:19], s[0:1], exec
	s_cselect_b32 s15, s17, s23
	s_cselect_b32 s48, s16, s22
	s_ashr_i32 s13, s12, 31
	s_lshl_b64 s[18:19], s[12:13], 19
	s_add_u32 s18, s88, s18
	s_addc_u32 s19, s89, s19
	s_and_b64 s[26:27], s[0:1], exec
	s_cselect_b32 s13, s19, s25
	s_cselect_b32 s49, s18, s24
	s_add_u32 s22, s22, 0x40080
	s_addc_u32 s23, s23, 0
	s_add_u32 s50, s24, 0x100
	s_addc_u32 s51, s25, 0
	s_mov_b32 s52, -2
	ds_read_b128 v[144:147], v154
	ds_read_b128 v[158:161], v154 offset:1024
	ds_read_b128 v[162:165], v154 offset:2048
	ds_read_b128 v[166:169], v154 offset:3072
	ds_read_b128 v[170:173], v155
	ds_read_b128 v[174:177], v155 offset:1024
	ds_read_b128 v[180:183], v155 offset:2048
	ds_read_b128 v[184:187], v155 offset:3072
	s_add_u32 s24, s22, 0xfffc0080
	s_addc_u32 s25, s23, -1
	s_cmp_eq_u32 s52, 12
	s_cselect_b32 s27, s15, s25
	s_cselect_b32 s26, s48, s24
	s_cselect_b32 s25, s13, s51
	s_cselect_b32 s24, s49, s50
	s_add_i32 m0, s21, 0xc000
	ds_read_b128 v[188:191], v156
	ds_read_b128 v[192:195], v156 offset:1024
	ds_read_b128 v[196:199], v156 offset:2048
	ds_read_b128 v[200:203], v156 offset:3072
	ds_read_b128 v[204:207], v156 offset:4096
	ds_read_b128 v[208:211], v156 offset:5120
	ds_read_b128 v[212:215], v156 offset:6144
	ds_read_b128 v[216:219], v156 offset:7168
	global_load_lds_dwordx4 v136, s[22:23]
	s_add_i32 m0, s21, 0xe000
	s_nop 0
	global_load_lds_dwordx4 v138, s[22:23]
	s_waitcnt vmcnt(8)
	s_waitcnt lgkmcnt(0)
	s_barrier
	s_setprio 1
	s_waitcnt lgkmcnt(0)
	v_mfma_f32_16x16x32_bf16 v[124:127], v[144:147], v[188:191], 0
	v_mfma_f32_16x16x32_bf16 v[116:119], v[162:165], v[188:191], 0
	v_mfma_f32_16x16x32_bf16 v[108:111], v[144:147], v[196:199], 0
	v_mfma_f32_16x16x32_bf16 v[100:103], v[162:165], v[196:199], 0
	v_mfma_f32_16x16x32_bf16 v[92:95], v[144:147], v[204:207], 0
	v_mfma_f32_16x16x32_bf16 v[84:87], v[162:165], v[204:207], 0
	v_mfma_f32_16x16x32_bf16 v[76:79], v[144:147], v[212:215], 0
	v_mfma_f32_16x16x32_bf16 v[68:71], v[162:165], v[212:215], 0
	v_mfma_f32_16x16x32_bf16 v[124:127], v[158:161], v[192:195], v[124:127]
	v_mfma_f32_16x16x32_bf16 v[116:119], v[166:169], v[192:195], v[116:119]
	v_mfma_f32_16x16x32_bf16 v[108:111], v[158:161], v[200:203], v[108:111]
	v_mfma_f32_16x16x32_bf16 v[100:103], v[166:169], v[200:203], v[100:103]
	v_mfma_f32_16x16x32_bf16 v[92:95], v[158:161], v[208:211], v[92:95]
	v_mfma_f32_16x16x32_bf16 v[84:87], v[166:169], v[208:211], v[84:87]
	v_mfma_f32_16x16x32_bf16 v[76:79], v[158:161], v[216:219], v[76:79]
	v_mfma_f32_16x16x32_bf16 v[68:71], v[166:169], v[216:219], v[68:71]
	s_setprio 0
	s_setprio 1
	v_mfma_f32_16x16x32_bf16 v[120:123], v[170:173], v[188:191], 0
	v_mfma_f32_16x16x32_bf16 v[112:115], v[180:183], v[188:191], 0
	v_mfma_f32_16x16x32_bf16 v[104:107], v[170:173], v[196:199], 0
	v_mfma_f32_16x16x32_bf16 v[96:99], v[180:183], v[196:199], 0
	v_mfma_f32_16x16x32_bf16 v[88:91], v[170:173], v[204:207], 0
	v_mfma_f32_16x16x32_bf16 v[80:83], v[180:183], v[204:207], 0
	v_mfma_f32_16x16x32_bf16 v[72:75], v[170:173], v[212:215], 0
	v_mfma_f32_16x16x32_bf16 v[64:67], v[180:183], v[212:215], 0
	v_mfma_f32_16x16x32_bf16 v[120:123], v[174:177], v[192:195], v[120:123]
	v_mfma_f32_16x16x32_bf16 v[112:115], v[184:187], v[192:195], v[112:115]
	v_mfma_f32_16x16x32_bf16 v[104:107], v[174:177], v[200:203], v[104:107]
	v_mfma_f32_16x16x32_bf16 v[96:99], v[184:187], v[200:203], v[96:99]
	v_mfma_f32_16x16x32_bf16 v[88:91], v[174:177], v[208:211], v[88:91]
	v_mfma_f32_16x16x32_bf16 v[80:83], v[184:187], v[208:211], v[80:83]
	v_mfma_f32_16x16x32_bf16 v[72:75], v[174:177], v[216:219], v[72:75]
	v_mfma_f32_16x16x32_bf16 v[64:67], v[184:187], v[216:219], v[64:67]
	s_setprio 0
	s_barrier
	s_add_i32 s53, s38, s28
	v_lshl_add_u64 v[148:149], s[24:25], 0, v[132:133]
	s_mov_b32 m0, s53
	ds_read_b128 v[188:191], v156 offset:16384
	ds_read_b128 v[192:195], v156 offset:17408
	ds_read_b128 v[196:199], v156 offset:18432
	ds_read_b128 v[200:203], v156 offset:19456
	ds_read_b128 v[204:207], v156 offset:20480
	ds_read_b128 v[208:211], v156 offset:21504
	ds_read_b128 v[212:215], v156 offset:22528
	ds_read_b128 v[216:219], v156 offset:23552
	global_load_lds_dwordx4 v[148:149], off
	s_add_i32 m0, s53, 0x2000
	s_add_u32 s54, s24, 0x40000
	v_lshl_add_u64 v[220:221], s[24:25], 0, v[128:129]
	s_addc_u32 s55, s25, 0
	s_add_i32 s53, s39, s28
	global_load_lds_dwordx4 v[220:221], off
	s_mov_b32 m0, s53
	v_lshl_add_u64 v[224:225], s[26:27], 0, v[130:131]
	global_load_lds_dwordx4 v132, s[54:55]
	s_add_i32 m0, s53, 0x2000
	s_nop 0
	global_load_lds_dwordx4 v128, s[54:55]
	v_lshl_add_u64 v[222:223], s[26:27], 0, v[134:135]
	s_mov_b32 m0, s21
	s_nop 0
	global_load_lds_dwordx4 v[222:223], off
	s_mov_b32 m0, s29
	s_nop 0
	global_load_lds_dwordx4 v[224:225], off
	s_waitcnt vmcnt(8)
	s_waitcnt lgkmcnt(0)
	s_barrier
; #define PG8_STAGE(bufoff, gbase, voff) do { _Pragma("unroll") for (int _i = 0; _i < 2; ++_i) \
;         __builtin_amdgcn_global_load_lds((const unsigned*)((const char*)(gbase) + (voff)[_i]), (PG8_LAS unsigned*)(lds + (bufoff) + ldsw + _i * 8192), 16, 0, 0); } while (0)
; #define PG8_LDA(dst, b, h) do { _Pragma("unroll") for (int m = 0; m < 4; ++m) _Pragma("unroll") for (int k = 0; k < 2; ++k) dst[m][k] = *(const PG8_LAS bf16x8*)(lds + PG8_SA(b, h) + aoff + m * 2048 + k * 1024); } while (0)
; #define PG8_LDB(dst, b, h) do { _Pragma("unroll") for (int n = 0; n < 2; ++n) _Pragma("unroll") for (int k = 0; k < 2; ++k) dst[n][k] = *(const PG8_LAS bf16x8*)(lds + PG8_SB(b, h) + boff + n * 2048 + k * 1024); } while (0)
; #define PG8_MMA(ai, bj, At, Bt) do { __builtin_amdgcn_s_setprio(1); _Pragma("unroll") for (int m = 0; m < 4; ++m) _Pragma("unroll") for (int n = 0; n < 2; ++n) _Pragma("unroll") for (int k = 0; k < 2; ++k) \
;         acc[ai][bj][m][n] = __builtin_amdgcn_mfma_f32_16x16x32_bf16(Bt[n][k], At[m][k], acc[ai][bj][m][n], 0, 0, 0); __builtin_amdgcn_s_setprio(0); } while (0)
; #define PG8_WAIT_V(n) asm volatile("s_waitcnt vmcnt(" #n ")" ::: "memory")
; #define PG8_WAIT_L(n) asm volatile("s_waitcnt lgkmcnt(" #n ")" ::: "memory")
; #define PG8_BAR __builtin_amdgcn_s_barrier()
; #define PG8_SCHED __builtin_amdgcn_sched_barrier(0)
; template <class Epi, class Sched, bool ALIGN_EPI = false, bool SP2 = false>
; __device__ __forceinline__ void gemm_phase(PG8_LAS unsigned char* lds, const Gemm g, const Sched& S, const Epi& E) {
;     ...
;             PG8_WAIT_V(8); PG8_WAIT_L(0); PG8_BAR; PG8_MMA(1, 0, At, B0); PG8_MMA(1, 1, At, B1); PG8_BAR; PG8_SCHED;
;             PG8_LDB(B0, 1, 0); PG8_LDB(B1, 1, 1); PG8_SCHED; PG8_LDA(At, 1, 0); PG8_STAGE(PG8_SA(0, 1), a2 + hstep, voffA);
;             PG8_WAIT_V(8); PG8_WAIT_L(0); PG8_BAR; PG8_MMA(0, 0, At, B0); PG8_MMA(0, 1, At, B1); PG8_BAR; PG8_SCHED;
	s_setprio 1
	s_waitcnt lgkmcnt(0)
	v_mfma_f32_16x16x32_bf16 v[60:63], v[144:147], v[188:191], 0
	v_mfma_f32_16x16x32_bf16 v[52:55], v[162:165], v[188:191], 0
	v_mfma_f32_16x16x32_bf16 v[44:47], v[144:147], v[196:199], 0
	v_mfma_f32_16x16x32_bf16 v[36:39], v[162:165], v[196:199], 0
	v_mfma_f32_16x16x32_bf16 v[28:31], v[144:147], v[204:207], 0
	v_mfma_f32_16x16x32_bf16 v[20:23], v[162:165], v[204:207], 0
	v_mfma_f32_16x16x32_bf16 v[12:15], v[144:147], v[212:215], 0
	v_mfma_f32_16x16x32_bf16 v[4:7], v[162:165], v[212:215], 0
	v_mfma_f32_16x16x32_bf16 v[60:63], v[158:161], v[192:195], v[60:63]
	v_mfma_f32_16x16x32_bf16 v[52:55], v[166:169], v[192:195], v[52:55]
	v_mfma_f32_16x16x32_bf16 v[44:47], v[158:161], v[200:203], v[44:47]
	v_mfma_f32_16x16x32_bf16 v[36:39], v[166:169], v[200:203], v[36:39]
	v_mfma_f32_16x16x32_bf16 v[28:31], v[158:161], v[208:211], v[28:31]
	v_mfma_f32_16x16x32_bf16 v[20:23], v[166:169], v[208:211], v[20:23]
	v_mfma_f32_16x16x32_bf16 v[12:15], v[158:161], v[216:219], v[12:15]
	v_mfma_f32_16x16x32_bf16 v[4:7], v[166:169], v[216:219], v[4:7]
	s_setprio 0
	s_setprio 1
	v_mfma_f32_16x16x32_bf16 v[56:59], v[170:173], v[188:191], 0
	v_mfma_f32_16x16x32_bf16 v[48:51], v[180:183], v[188:191], 0
	v_mfma_f32_16x16x32_bf16 v[40:43], v[170:173], v[196:199], 0
	v_mfma_f32_16x16x32_bf16 v[32:35], v[180:183], v[196:199], 0
	v_mfma_f32_16x16x32_bf16 v[24:27], v[170:173], v[204:207], 0
	v_mfma_f32_16x16x32_bf16 v[16:19], v[180:183], v[204:207], 0
	v_mfma_f32_16x16x32_bf16 v[8:11], v[170:173], v[212:215], 0
	v_mfma_f32_16x16x32_bf16 v[0:3], v[180:183], v[212:215], 0
	v_mfma_f32_16x16x32_bf16 v[56:59], v[174:177], v[192:195], v[56:59]
	v_mfma_f32_16x16x32_bf16 v[48:51], v[184:187], v[192:195], v[48:51]
	v_mfma_f32_16x16x32_bf16 v[40:43], v[174:177], v[200:203], v[40:43]
	v_mfma_f32_16x16x32_bf16 v[32:35], v[184:187], v[200:203], v[32:35]
	v_mfma_f32_16x16x32_bf16 v[24:27], v[174:177], v[208:211], v[24:27]
	v_mfma_f32_16x16x32_bf16 v[16:19], v[184:187], v[208:211], v[16:19]
	v_mfma_f32_16x16x32_bf16 v[8:11], v[174:177], v[216:219], v[8:11]
	v_mfma_f32_16x16x32_bf16 v[0:3], v[184:187], v[216:219], v[0:3]
	s_setprio 0
	s_barrier
	s_add_i32 s53, 0, 0x18000
	v_add_u32_e32 v157, s53, v151
	s_add_i32 s54, 0, 0x1c000
	ds_read_b128 v[144:147], v157
	ds_read_b128 v[158:161], v157 offset:1024
	ds_read_b128 v[162:165], v157 offset:2048
	ds_read_b128 v[166:169], v157 offset:3072
	v_add_u32_e32 v157, s54, v151
	ds_read_b128 v[170:173], v157
	ds_read_b128 v[174:177], v157 offset:1024
	ds_read_b128 v[180:183], v157 offset:2048
	ds_read_b128 v[184:187], v157 offset:3072
	s_add_u32 s26, s26, 0x40000
	s_addc_u32 s27, s27, 0
	s_mov_b32 m0, s30
	ds_read_b128 v[188:191], v156 offset:32768
	ds_read_b128 v[192:195], v156 offset:33792
	ds_read_b128 v[196:199], v156 offset:34816
	ds_read_b128 v[200:203], v156 offset:35840
	ds_read_b128 v[204:207], v156 offset:36864
	ds_read_b128 v[208:211], v156 offset:37888
	ds_read_b128 v[212:215], v156 offset:38912
	ds_read_b128 v[216:219], v156 offset:39936
	global_load_lds_dwordx4 v134, s[26:27]
	v_lshl_add_u64 v[226:227], s[26:27], 0, v[130:131]
	s_mov_b32 m0, s31
	s_nop 0
	global_load_lds_dwordx4 v[226:227], off
	s_waitcnt vmcnt(8)
	s_waitcnt lgkmcnt(0)
	s_barrier
	s_setprio 1
	s_waitcnt lgkmcnt(0)
	v_mfma_f32_16x16x32_bf16 v[124:127], v[144:147], v[188:191], v[124:127]
	v_mfma_f32_16x16x32_bf16 v[116:119], v[162:165], v[188:191], v[116:119]
	v_mfma_f32_16x16x32_bf16 v[108:111], v[144:147], v[196:199], v[108:111]
	v_mfma_f32_16x16x32_bf16 v[100:103], v[162:165], v[196:199], v[100:103]
	v_mfma_f32_16x16x32_bf16 v[92:95], v[144:147], v[204:207], v[92:95]
	v_mfma_f32_16x16x32_bf16 v[84:87], v[162:165], v[204:207], v[84:87]
	v_mfma_f32_16x16x32_bf16 v[76:79], v[144:147], v[212:215], v[76:79]
	v_mfma_f32_16x16x32_bf16 v[68:71], v[162:165], v[212:215], v[68:71]
	v_mfma_f32_16x16x32_bf16 v[124:127], v[158:161], v[192:195], v[124:127]
	v_mfma_f32_16x16x32_bf16 v[116:119], v[166:169], v[192:195], v[116:119]
	v_mfma_f32_16x16x32_bf16 v[108:111], v[158:161], v[200:203], v[108:111]
	v_mfma_f32_16x16x32_bf16 v[100:103], v[166:169], v[200:203], v[100:103]
	v_mfma_f32_16x16x32_bf16 v[92:95], v[158:161], v[208:211], v[92:95]
	v_mfma_f32_16x16x32_bf16 v[84:87], v[166:169], v[208:211], v[84:87]
	v_mfma_f32_16x16x32_bf16 v[76:79], v[158:161], v[216:219], v[76:79]
	v_mfma_f32_16x16x32_bf16 v[68:71], v[166:169], v[216:219], v[68:71]
	s_setprio 0
	s_setprio 1
	v_mfma_f32_16x16x32_bf16 v[120:123], v[170:173], v[188:191], v[120:123]
	v_mfma_f32_16x16x32_bf16 v[112:115], v[180:183], v[188:191], v[112:115]
	v_mfma_f32_16x16x32_bf16 v[104:107], v[170:173], v[196:199], v[104:107]
	v_mfma_f32_16x16x32_bf16 v[96:99], v[180:183], v[196:199], v[96:99]
	v_mfma_f32_16x16x32_bf16 v[88:91], v[170:173], v[204:207], v[88:91]
	v_mfma_f32_16x16x32_bf16 v[80:83], v[180:183], v[204:207], v[80:83]
	v_mfma_f32_16x16x32_bf16 v[72:75], v[170:173], v[212:215], v[72:75]
	v_mfma_f32_16x16x32_bf16 v[64:67], v[180:183], v[212:215], v[64:67]
	v_mfma_f32_16x16x32_bf16 v[120:123], v[174:177], v[192:195], v[120:123]
	v_mfma_f32_16x16x32_bf16 v[112:115], v[184:187], v[192:195], v[112:115]
	v_mfma_f32_16x16x32_bf16 v[104:107], v[174:177], v[200:203], v[104:107]
	v_mfma_f32_16x16x32_bf16 v[96:99], v[184:187], v[200:203], v[96:99]
	v_mfma_f32_16x16x32_bf16 v[88:91], v[174:177], v[208:211], v[88:91]
	v_mfma_f32_16x16x32_bf16 v[80:83], v[184:187], v[208:211], v[80:83]
	v_mfma_f32_16x16x32_bf16 v[72:75], v[174:177], v[216:219], v[72:75]
	v_mfma_f32_16x16x32_bf16 v[64:67], v[184:187], v[216:219], v[64:67]
	s_setprio 0
	s_barrier
; #define PG8_STAGE(bufoff, gbase, voff) do { _Pragma("unroll") for (int _i = 0; _i < 2; ++_i) \
;         __builtin_amdgcn_global_load_lds((const unsigned*)((const char*)(gbase) + (voff)[_i]), (PG8_LAS unsigned*)(lds + (bufoff) + ldsw + _i * 8192), 16, 0, 0); } while (0)
; #define PG8_LDA(dst, b, h) do { _Pragma("unroll") for (int m = 0; m < 4; ++m) _Pragma("unroll") for (int k = 0; k < 2; ++k) dst[m][k] = *(const PG8_LAS bf16x8*)(lds + PG8_SA(b, h) + aoff + m * 2048 + k * 1024); } while (0)
; #define PG8_LDB(dst, b, h) do { _Pragma("unroll") for (int n = 0; n < 2; ++n) _Pragma("unroll") for (int k = 0; k < 2; ++k) dst[n][k] = *(const PG8_LAS bf16x8*)(lds + PG8_SB(b, h) + boff + n * 2048 + k * 1024); } while (0)
; #define PG8_MMA(ai, bj, At, Bt) do { __builtin_amdgcn_s_setprio(1); _Pragma("unroll") for (int m = 0; m < 4; ++m) _Pragma("unroll") for (int n = 0; n < 2; ++n) _Pragma("unroll") for (int k = 0; k < 2; ++k) \
;         acc[ai][bj][m][n] = __builtin_amdgcn_mfma_f32_16x16x32_bf16(Bt[n][k], At[m][k], acc[ai][bj][m][n], 0, 0, 0); __builtin_amdgcn_s_setprio(0); } while (0)
; #define PG8_WAIT_V(n) asm volatile("s_waitcnt vmcnt(" #n ")" ::: "memory")
; template <class Epi, class Sched, bool ALIGN_EPI = false, bool SP2 = false>
; __device__ __forceinline__ void gemm_phase(PG8_LAS unsigned char* lds, const Gemm g, const Sched& S, const Epi& E) {
;     ...
;             PG8_LDB(B0, 0, 0); PG8_LDB(B1, 0, 1); PG8_SCHED; PG8_LDA(At, 0, 0); PG8_STAGE(PG8_SA(1, 1), a1 + hstep, voffA);
;             PG8_WAIT_V(8); PG8_WAIT_L(0); PG8_BAR; PG8_MMA(0, 0, At, B0); PG8_MMA(0, 1, At, B1); PG8_BAR; PG8_SCHED;
;             PG8_LDA(At, 0, 1); PG8_STAGE(PG8_SB(0, 0), b2, voffB); PG8_STAGE(PG8_SB(0, 1), b2 + hstep, voffB); PG8_STAGE(PG8_SA(0, 0), a2, voffA);
;             PG8_WAIT_V(8); PG8_WAIT_L(0); PG8_BAR; PG8_MMA(1, 0, At, B0); PG8_MMA(1, 1, At, B1); PG8_BAR; PG8_SCHED;
;             PG8_LDB(B0, 1, 0); PG8_LDB(B1, 1, 1); PG8_SCHED; PG8_LDA(At, 1, 0); PG8_STAGE(PG8_SA(0, 1), a2 + hstep, voffA);
;             PG8_WAIT_V(8); PG8_WAIT_L(0); PG8_BAR; PG8_MMA(0, 0, At, B0); PG8_MMA(0, 1, At, B1); PG8_BAR; PG8_SCHED;
;             PG8_LDA(At, 1, 1); PG8_STAGE(PG8_SB(1, 0), b3, voffB); PG8_STAGE(PG8_SB(1, 1), b3 + hstep, voffB); PG8_STAGE(PG8_SA(1, 0), a3, voffA);
;             PG8_WAIT_V(8); PG8_WAIT_L(0); PG8_BAR; PG8_MMA(1, 0, At, B0); PG8_MMA(1, 1, At, B1); PG8_BAR; PG8_SCHED;
	s_add_i32 s26, s53, s28
	v_lshl_add_u64 v[148:149], v[148:149], 0, s[8:9]
	s_mov_b32 m0, s26
	ds_read_b128 v[188:191], v156 offset:49152
	ds_read_b128 v[192:195], v156 offset:50176
	ds_read_b128 v[196:199], v156 offset:51200
	ds_read_b128 v[200:203], v156 offset:52224
	ds_read_b128 v[204:207], v156 offset:53248
	ds_read_b128 v[208:211], v156 offset:54272
	ds_read_b128 v[212:215], v156 offset:55296
	ds_read_b128 v[216:219], v156 offset:56320
	global_load_lds_dwordx4 v[148:149], off
	s_add_i32 m0, s26, 0x2000
	s_add_u32 s24, s24, 0x40080
	v_lshl_add_u64 v[148:149], v[220:221], 0, s[8:9]
	s_addc_u32 s25, s25, 0
	s_add_i32 s26, s54, s28
	global_load_lds_dwordx4 v[148:149], off
	s_mov_b32 m0, s26
	s_nop 0
	global_load_lds_dwordx4 v132, s[24:25]
	s_add_i32 m0, s26, 0x2000
	s_nop 0
	global_load_lds_dwordx4 v128, s[24:25]
	v_lshl_add_u64 v[148:149], v[222:223], 0, s[8:9]
	s_mov_b32 m0, s35
	s_nop 0
	global_load_lds_dwordx4 v[148:149], off
	v_lshl_add_u64 v[148:149], v[224:225], 0, s[8:9]
	s_mov_b32 m0, s36
	s_nop 0
	global_load_lds_dwordx4 v[148:149], off
	s_waitcnt vmcnt(8)
	s_waitcnt lgkmcnt(0)
	s_barrier
	s_setprio 1
	s_waitcnt lgkmcnt(0)
	v_mfma_f32_16x16x32_bf16 v[60:63], v[144:147], v[188:191], v[60:63]
	v_mfma_f32_16x16x32_bf16 v[52:55], v[162:165], v[188:191], v[52:55]
	v_mfma_f32_16x16x32_bf16 v[44:47], v[144:147], v[196:199], v[44:47]
	v_mfma_f32_16x16x32_bf16 v[36:39], v[162:165], v[196:199], v[36:39]
	v_mfma_f32_16x16x32_bf16 v[28:31], v[144:147], v[204:207], v[28:31]
	v_mfma_f32_16x16x32_bf16 v[20:23], v[162:165], v[204:207], v[20:23]
	v_mfma_f32_16x16x32_bf16 v[12:15], v[144:147], v[212:215], v[12:15]
	v_mfma_f32_16x16x32_bf16 v[4:7], v[162:165], v[212:215], v[4:7]
	v_mfma_f32_16x16x32_bf16 v[60:63], v[158:161], v[192:195], v[60:63]
	v_mfma_f32_16x16x32_bf16 v[52:55], v[166:169], v[192:195], v[52:55]
	v_mfma_f32_16x16x32_bf16 v[44:47], v[158:161], v[200:203], v[44:47]
	v_mfma_f32_16x16x32_bf16 v[36:39], v[166:169], v[200:203], v[36:39]
	v_mfma_f32_16x16x32_bf16 v[28:31], v[158:161], v[208:211], v[28:31]
	v_mfma_f32_16x16x32_bf16 v[20:23], v[166:169], v[208:211], v[20:23]
	v_mfma_f32_16x16x32_bf16 v[12:15], v[158:161], v[216:219], v[12:15]
	v_mfma_f32_16x16x32_bf16 v[4:7], v[166:169], v[216:219], v[4:7]
	s_setprio 0
	s_setprio 1
	v_mfma_f32_16x16x32_bf16 v[56:59], v[170:173], v[188:191], v[56:59]
	v_mfma_f32_16x16x32_bf16 v[48:51], v[180:183], v[188:191], v[48:51]
	v_mfma_f32_16x16x32_bf16 v[40:43], v[170:173], v[196:199], v[40:43]
	v_mfma_f32_16x16x32_bf16 v[32:35], v[180:183], v[196:199], v[32:35]
	v_mfma_f32_16x16x32_bf16 v[24:27], v[170:173], v[204:207], v[24:27]
	v_mfma_f32_16x16x32_bf16 v[16:19], v[180:183], v[204:207], v[16:19]
	v_mfma_f32_16x16x32_bf16 v[8:11], v[170:173], v[212:215], v[8:11]
	v_mfma_f32_16x16x32_bf16 v[0:3], v[180:183], v[212:215], v[0:3]
	v_mfma_f32_16x16x32_bf16 v[56:59], v[174:177], v[192:195], v[56:59]
	v_mfma_f32_16x16x32_bf16 v[48:51], v[184:187], v[192:195], v[48:51]
	v_mfma_f32_16x16x32_bf16 v[40:43], v[174:177], v[200:203], v[40:43]
	v_mfma_f32_16x16x32_bf16 v[32:35], v[184:187], v[200:203], v[32:35]
	v_mfma_f32_16x16x32_bf16 v[24:27], v[174:177], v[208:211], v[24:27]
	v_mfma_f32_16x16x32_bf16 v[16:19], v[184:187], v[208:211], v[16:19]
	v_mfma_f32_16x16x32_bf16 v[8:11], v[174:177], v[216:219], v[8:11]
	v_mfma_f32_16x16x32_bf16 v[0:3], v[184:187], v[216:219], v[0:3]
	s_setprio 0
	s_barrier
	s_add_i32 s52, s52, 2
	s_add_u32 s22, s22, 0x100
	s_addc_u32 s23, s23, 0
	s_add_u32 s50, s50, 0x100
	s_addc_u32 s51, s51, 0
	s_cmp_gt_u32 s52, 13
	s_cbranch_scc0 .LBB0_1361
.LBB0_1361:
	ds_read_b128 v[144:147], v154
	ds_read_b128 v[158:161], v154 offset:1024
	ds_read_b128 v[162:165], v154 offset:2048
	ds_read_b128 v[166:169], v154 offset:3072
	ds_read_b128 v[170:173], v155
	ds_read_b128 v[174:177], v155 offset:1024
	ds_read_b128 v[180:183], v155 offset:2048
	ds_read_b128 v[184:187], v155 offset:3072
	s_add_u32 s24, s22, 0xfffc0080
	s_addc_u32 s25, s23, -1
	s_cmp_eq_u32 s52, 12
	s_cselect_b32 s27, s15, s25
	s_cselect_b32 s26, s48, s24
	s_cselect_b32 s25, s13, s51
	s_cselect_b32 s24, s49, s50
	s_add_i32 m0, s21, 0xc000
	ds_read_b128 v[188:191], v156
	ds_read_b128 v[192:195], v156 offset:1024
	ds_read_b128 v[196:199], v156 offset:2048
	ds_read_b128 v[200:203], v156 offset:3072
	ds_read_b128 v[204:207], v156 offset:4096
	ds_read_b128 v[208:211], v156 offset:5120
	ds_read_b128 v[212:215], v156 offset:6144
	ds_read_b128 v[216:219], v156 offset:7168
	global_load_lds_dwordx4 v136, s[22:23]
	s_add_i32 m0, s21, 0xe000
	s_nop 0
	global_load_lds_dwordx4 v138, s[22:23]
	s_waitcnt vmcnt(8)
	s_waitcnt lgkmcnt(0)
	s_barrier
; #define PG8_STAGE(bufoff, gbase, voff) do { _Pragma("unroll") for (int _i = 0; _i < 2; ++_i) \
;         __builtin_amdgcn_global_load_lds((const unsigned*)((const char*)(gbase) + (voff)[_i]), (PG8_LAS unsigned*)(lds + (bufoff) + ldsw + _i * 8192), 16, 0, 0); } while (0)
; #define PG8_LDA(dst, b, h) do { _Pragma("unroll") for (int m = 0; m < 4; ++m) _Pragma("unroll") for (int k = 0; k < 2; ++k) dst[m][k] = *(const PG8_LAS bf16x8*)(lds + PG8_SA(b, h) + aoff + m * 2048 + k * 1024); } while (0)
; #define PG8_MMA(ai, bj, At, Bt) do { __builtin_amdgcn_s_setprio(1); _Pragma("unroll") for (int m = 0; m < 4; ++m) _Pragma("unroll") for (int n = 0; n < 2; ++n) _Pragma("unroll") for (int k = 0; k < 2; ++k) \
;         acc[ai][bj][m][n] = __builtin_amdgcn_mfma_f32_16x16x32_bf16(Bt[n][k], At[m][k], acc[ai][bj][m][n], 0, 0, 0); __builtin_amdgcn_s_setprio(0); } while (0)
; #define PG8_WAIT_V(n) asm volatile("s_waitcnt vmcnt(" #n ")" ::: "memory")
; #define PG8_WAIT_L(n) asm volatile("s_waitcnt lgkmcnt(" #n ")" ::: "memory")
; #define PG8_BAR __builtin_amdgcn_s_barrier()
; #define PG8_SCHED __builtin_amdgcn_sched_barrier(0)
; template <class Epi, class Sched, bool ALIGN_EPI = false, bool SP2 = false>
; __device__ __forceinline__ void gemm_phase(PG8_LAS unsigned char* lds, const Gemm g, const Sched& S, const Epi& E) {
;     ...
;             PG8_WAIT_V(8); PG8_WAIT_L(0); PG8_BAR; PG8_MMA(0, 0, At, B0); PG8_MMA(0, 1, At, B1); PG8_BAR; PG8_SCHED;
;             PG8_LDA(At, 0, 1); PG8_STAGE(PG8_SB(0, 0), b2, voffB); PG8_STAGE(PG8_SB(0, 1), b2 + hstep, voffB); PG8_STAGE(PG8_SA(0, 0), a2, voffA);
;             PG8_WAIT_V(8); PG8_WAIT_L(0); PG8_BAR; PG8_MMA(1, 0, At, B0); PG8_MMA(1, 1, At, B1); PG8_BAR; PG8_SCHED;
	s_setprio 1
	s_waitcnt lgkmcnt(0)
	v_mfma_f32_16x16x32_bf16 v[124:127], v[144:147], v[188:191], v[124:127]
	v_mfma_f32_16x16x32_bf16 v[116:119], v[162:165], v[188:191], v[116:119]
	v_mfma_f32_16x16x32_bf16 v[108:111], v[144:147], v[196:199], v[108:111]
	v_mfma_f32_16x16x32_bf16 v[100:103], v[162:165], v[196:199], v[100:103]
	v_mfma_f32_16x16x32_bf16 v[92:95], v[144:147], v[204:207], v[92:95]
	v_mfma_f32_16x16x32_bf16 v[84:87], v[162:165], v[204:207], v[84:87]
	v_mfma_f32_16x16x32_bf16 v[76:79], v[144:147], v[212:215], v[76:79]
	v_mfma_f32_16x16x32_bf16 v[68:71], v[162:165], v[212:215], v[68:71]
	v_mfma_f32_16x16x32_bf16 v[124:127], v[158:161], v[192:195], v[124:127]
	v_mfma_f32_16x16x32_bf16 v[116:119], v[166:169], v[192:195], v[116:119]
	v_mfma_f32_16x16x32_bf16 v[108:111], v[158:161], v[200:203], v[108:111]
	v_mfma_f32_16x16x32_bf16 v[100:103], v[166:169], v[200:203], v[100:103]
	v_mfma_f32_16x16x32_bf16 v[92:95], v[158:161], v[208:211], v[92:95]
	v_mfma_f32_16x16x32_bf16 v[84:87], v[166:169], v[208:211], v[84:87]
	v_mfma_f32_16x16x32_bf16 v[76:79], v[158:161], v[216:219], v[76:79]
	v_mfma_f32_16x16x32_bf16 v[68:71], v[166:169], v[216:219], v[68:71]
	s_setprio 0
	s_setprio 1
	v_mfma_f32_16x16x32_bf16 v[120:123], v[170:173], v[188:191], v[120:123]
	v_mfma_f32_16x16x32_bf16 v[112:115], v[180:183], v[188:191], v[112:115]
	v_mfma_f32_16x16x32_bf16 v[104:107], v[170:173], v[196:199], v[104:107]
	v_mfma_f32_16x16x32_bf16 v[96:99], v[180:183], v[196:199], v[96:99]
	v_mfma_f32_16x16x32_bf16 v[88:91], v[170:173], v[204:207], v[88:91]
	v_mfma_f32_16x16x32_bf16 v[80:83], v[180:183], v[204:207], v[80:83]
	v_mfma_f32_16x16x32_bf16 v[72:75], v[170:173], v[212:215], v[72:75]
	v_mfma_f32_16x16x32_bf16 v[64:67], v[180:183], v[212:215], v[64:67]
	v_mfma_f32_16x16x32_bf16 v[120:123], v[174:177], v[192:195], v[120:123]
	v_mfma_f32_16x16x32_bf16 v[112:115], v[184:187], v[192:195], v[112:115]
	v_mfma_f32_16x16x32_bf16 v[104:107], v[174:177], v[200:203], v[104:107]
	v_mfma_f32_16x16x32_bf16 v[96:99], v[184:187], v[200:203], v[96:99]
	v_mfma_f32_16x16x32_bf16 v[88:91], v[174:177], v[208:211], v[88:91]
	v_mfma_f32_16x16x32_bf16 v[80:83], v[184:187], v[208:211], v[80:83]
	v_mfma_f32_16x16x32_bf16 v[72:75], v[174:177], v[216:219], v[72:75]
	v_mfma_f32_16x16x32_bf16 v[64:67], v[184:187], v[216:219], v[64:67]
	s_setprio 0
	s_barrier
	s_add_i32 s53, s38, s28
	v_lshl_add_u64 v[148:149], s[24:25], 0, v[132:133]
	s_mov_b32 m0, s53
	ds_read_b128 v[188:191], v156 offset:16384
	ds_read_b128 v[192:195], v156 offset:17408
	ds_read_b128 v[196:199], v156 offset:18432
	ds_read_b128 v[200:203], v156 offset:19456
	ds_read_b128 v[204:207], v156 offset:20480
	ds_read_b128 v[208:211], v156 offset:21504
	ds_read_b128 v[212:215], v156 offset:22528
	ds_read_b128 v[216:219], v156 offset:23552
	global_load_lds_dwordx4 v[148:149], off
	s_add_i32 m0, s53, 0x2000
	s_add_u32 s54, s24, 0x40000
	v_lshl_add_u64 v[220:221], s[24:25], 0, v[128:129]
	s_addc_u32 s55, s25, 0
	s_add_i32 s53, s39, s28
	global_load_lds_dwordx4 v[220:221], off
	s_mov_b32 m0, s53
	v_lshl_add_u64 v[224:225], s[26:27], 0, v[130:131]
	global_load_lds_dwordx4 v132, s[54:55]
	s_add_i32 m0, s53, 0x2000
	s_nop 0
	global_load_lds_dwordx4 v128, s[54:55]
	v_lshl_add_u64 v[222:223], s[26:27], 0, v[134:135]
	s_mov_b32 m0, s21
	s_nop 0
	global_load_lds_dwordx4 v[222:223], off
	s_mov_b32 m0, s29
	s_nop 0
	global_load_lds_dwordx4 v[224:225], off
	s_waitcnt vmcnt(8)
	s_waitcnt lgkmcnt(0)
	s_barrier
	s_setprio 1
	s_waitcnt lgkmcnt(0)
	v_mfma_f32_16x16x32_bf16 v[60:63], v[144:147], v[188:191], v[60:63]
	v_mfma_f32_16x16x32_bf16 v[52:55], v[162:165], v[188:191], v[52:55]
	v_mfma_f32_16x16x32_bf16 v[44:47], v[144:147], v[196:199], v[44:47]
	v_mfma_f32_16x16x32_bf16 v[36:39], v[162:165], v[196:199], v[36:39]
	v_mfma_f32_16x16x32_bf16 v[28:31], v[144:147], v[204:207], v[28:31]
	v_mfma_f32_16x16x32_bf16 v[20:23], v[162:165], v[204:207], v[20:23]
	v_mfma_f32_16x16x32_bf16 v[12:15], v[144:147], v[212:215], v[12:15]
	v_mfma_f32_16x16x32_bf16 v[4:7], v[162:165], v[212:215], v[4:7]
	v_mfma_f32_16x16x32_bf16 v[60:63], v[158:161], v[192:195], v[60:63]
	v_mfma_f32_16x16x32_bf16 v[52:55], v[166:169], v[192:195], v[52:55]
	v_mfma_f32_16x16x32_bf16 v[44:47], v[158:161], v[200:203], v[44:47]
	v_mfma_f32_16x16x32_bf16 v[36:39], v[166:169], v[200:203], v[36:39]
	v_mfma_f32_16x16x32_bf16 v[28:31], v[158:161], v[208:211], v[28:31]
	v_mfma_f32_16x16x32_bf16 v[20:23], v[166:169], v[208:211], v[20:23]
	v_mfma_f32_16x16x32_bf16 v[12:15], v[158:161], v[216:219], v[12:15]
	v_mfma_f32_16x16x32_bf16 v[4:7], v[166:169], v[216:219], v[4:7]
	s_setprio 0
	s_setprio 1
	v_mfma_f32_16x16x32_bf16 v[56:59], v[170:173], v[188:191], v[56:59]
	v_mfma_f32_16x16x32_bf16 v[48:51], v[180:183], v[188:191], v[48:51]
	v_mfma_f32_16x16x32_bf16 v[40:43], v[170:173], v[196:199], v[40:43]
	v_mfma_f32_16x16x32_bf16 v[32:35], v[180:183], v[196:199], v[32:35]
	v_mfma_f32_16x16x32_bf16 v[24:27], v[170:173], v[204:207], v[24:27]
	v_mfma_f32_16x16x32_bf16 v[16:19], v[180:183], v[204:207], v[16:19]
	v_mfma_f32_16x16x32_bf16 v[8:11], v[170:173], v[212:215], v[8:11]
	v_mfma_f32_16x16x32_bf16 v[0:3], v[180:183], v[212:215], v[0:3]
	v_mfma_f32_16x16x32_bf16 v[56:59], v[174:177], v[192:195], v[56:59]
	v_mfma_f32_16x16x32_bf16 v[48:51], v[184:187], v[192:195], v[48:51]
	v_mfma_f32_16x16x32_bf16 v[40:43], v[174:177], v[200:203], v[40:43]
	v_mfma_f32_16x16x32_bf16 v[32:35], v[184:187], v[200:203], v[32:35]
	v_mfma_f32_16x16x32_bf16 v[24:27], v[174:177], v[208:211], v[24:27]
	v_mfma_f32_16x16x32_bf16 v[16:19], v[184:187], v[208:211], v[16:19]
	v_mfma_f32_16x16x32_bf16 v[8:11], v[174:177], v[216:219], v[8:11]
	v_mfma_f32_16x16x32_bf16 v[0:3], v[184:187], v[216:219], v[0:3]
	s_setprio 0
	s_barrier
; #define PG8_STAGE(bufoff, gbase, voff) do { _Pragma("unroll") for (int _i = 0; _i < 2; ++_i) \
;         __builtin_amdgcn_global_load_lds((const unsigned*)((const char*)(gbase) + (voff)[_i]), (PG8_LAS unsigned*)(lds + (bufoff) + ldsw + _i * 8192), 16, 0, 0); } while (0)
; #define PG8_LDA(dst, b, h) do { _Pragma("unroll") for (int m = 0; m < 4; ++m) _Pragma("unroll") for (int k = 0; k < 2; ++k) dst[m][k] = *(const PG8_LAS bf16x8*)(lds + PG8_SA(b, h) + aoff + m * 2048 + k * 1024); } while (0)
; #define PG8_LDB(dst, b, h) do { _Pragma("unroll") for (int n = 0; n < 2; ++n) _Pragma("unroll") for (int k = 0; k < 2; ++k) dst[n][k] = *(const PG8_LAS bf16x8*)(lds + PG8_SB(b, h) + boff + n * 2048 + k * 1024); } while (0)
; #define PG8_MMA(ai, bj, At, Bt) do { __builtin_amdgcn_s_setprio(1); _Pragma("unroll") for (int m = 0; m < 4; ++m) _Pragma("unroll") for (int n = 0; n < 2; ++n) _Pragma("unroll") for (int k = 0; k < 2; ++k) \
;         acc[ai][bj][m][n] = __builtin_amdgcn_mfma_f32_16x16x32_bf16(Bt[n][k], At[m][k], acc[ai][bj][m][n], 0, 0, 0); __builtin_amdgcn_s_setprio(0); } while (0)
; #define PG8_WAIT_V(n) asm volatile("s_waitcnt vmcnt(" #n ")" ::: "memory")
; #define PG8_WAIT_L(n) asm volatile("s_waitcnt lgkmcnt(" #n ")" ::: "memory")
; #define PG8_BAR __builtin_amdgcn_s_barrier()
; #define PG8_SCHED __builtin_amdgcn_sched_barrier(0)
; template <class Epi, class Sched, bool ALIGN_EPI = false, bool SP2 = false>
; __device__ __forceinline__ void gemm_phase(PG8_LAS unsigned char* lds, const Gemm g, const Sched& S, const Epi& E) {
;     ...
;             PG8_LDB(B0, 1, 0); PG8_LDB(B1, 1, 1); PG8_SCHED; PG8_LDA(At, 1, 0); PG8_STAGE(PG8_SA(0, 1), a2 + hstep, voffA);
;             PG8_WAIT_V(8); PG8_WAIT_L(0); PG8_BAR; PG8_MMA(0, 0, At, B0); PG8_MMA(0, 1, At, B1); PG8_BAR; PG8_SCHED;
	s_add_i32 s53, 0, 0x18000
	v_add_u32_e32 v157, s53, v151
	s_add_i32 s54, 0, 0x1c000
	ds_read_b128 v[144:147], v157
	ds_read_b128 v[158:161], v157 offset:1024
	ds_read_b128 v[162:165], v157 offset:2048
	ds_read_b128 v[166:169], v157 offset:3072
	v_add_u32_e32 v157, s54, v151
	ds_read_b128 v[170:173], v157
	ds_read_b128 v[174:177], v157 offset:1024
	ds_read_b128 v[180:183], v157 offset:2048
	ds_read_b128 v[184:187], v157 offset:3072
	s_add_u32 s26, s26, 0x40000
	s_addc_u32 s27, s27, 0
	s_mov_b32 m0, s30
	ds_read_b128 v[188:191], v156 offset:32768
	ds_read_b128 v[192:195], v156 offset:33792
	ds_read_b128 v[196:199], v156 offset:34816
	ds_read_b128 v[200:203], v156 offset:35840
	ds_read_b128 v[204:207], v156 offset:36864
	ds_read_b128 v[208:211], v156 offset:37888
	ds_read_b128 v[212:215], v156 offset:38912
	ds_read_b128 v[216:219], v156 offset:39936
	global_load_lds_dwordx4 v134, s[26:27]
	v_lshl_add_u64 v[226:227], s[26:27], 0, v[130:131]
	s_mov_b32 m0, s31
	s_nop 0
	global_load_lds_dwordx4 v[226:227], off
	s_waitcnt vmcnt(8)
	s_waitcnt lgkmcnt(0)
	s_barrier
	s_setprio 1
	s_waitcnt lgkmcnt(0)
	v_mfma_f32_16x16x32_bf16 v[124:127], v[144:147], v[188:191], v[124:127]
	v_mfma_f32_16x16x32_bf16 v[116:119], v[162:165], v[188:191], v[116:119]
	v_mfma_f32_16x16x32_bf16 v[108:111], v[144:147], v[196:199], v[108:111]
	v_mfma_f32_16x16x32_bf16 v[100:103], v[162:165], v[196:199], v[100:103]
	v_mfma_f32_16x16x32_bf16 v[92:95], v[144:147], v[204:207], v[92:95]
	v_mfma_f32_16x16x32_bf16 v[84:87], v[162:165], v[204:207], v[84:87]
	v_mfma_f32_16x16x32_bf16 v[76:79], v[144:147], v[212:215], v[76:79]
	v_mfma_f32_16x16x32_bf16 v[68:71], v[162:165], v[212:215], v[68:71]
	v_mfma_f32_16x16x32_bf16 v[124:127], v[158:161], v[192:195], v[124:127]
	v_mfma_f32_16x16x32_bf16 v[116:119], v[166:169], v[192:195], v[116:119]
	v_mfma_f32_16x16x32_bf16 v[108:111], v[158:161], v[200:203], v[108:111]
	v_mfma_f32_16x16x32_bf16 v[100:103], v[166:169], v[200:203], v[100:103]
	v_mfma_f32_16x16x32_bf16 v[92:95], v[158:161], v[208:211], v[92:95]
	v_mfma_f32_16x16x32_bf16 v[84:87], v[166:169], v[208:211], v[84:87]
	v_mfma_f32_16x16x32_bf16 v[76:79], v[158:161], v[216:219], v[76:79]
	v_mfma_f32_16x16x32_bf16 v[68:71], v[166:169], v[216:219], v[68:71]
	s_setprio 0
	s_setprio 1
	v_mfma_f32_16x16x32_bf16 v[120:123], v[170:173], v[188:191], v[120:123]
	v_mfma_f32_16x16x32_bf16 v[112:115], v[180:183], v[188:191], v[112:115]
	v_mfma_f32_16x16x32_bf16 v[104:107], v[170:173], v[196:199], v[104:107]
	v_mfma_f32_16x16x32_bf16 v[96:99], v[180:183], v[196:199], v[96:99]
	v_mfma_f32_16x16x32_bf16 v[88:91], v[170:173], v[204:207], v[88:91]
	v_mfma_f32_16x16x32_bf16 v[80:83], v[180:183], v[204:207], v[80:83]
	v_mfma_f32_16x16x32_bf16 v[72:75], v[170:173], v[212:215], v[72:75]
	v_mfma_f32_16x16x32_bf16 v[64:67], v[180:183], v[212:215], v[64:67]
	v_mfma_f32_16x16x32_bf16 v[120:123], v[174:177], v[192:195], v[120:123]
	v_mfma_f32_16x16x32_bf16 v[112:115], v[184:187], v[192:195], v[112:115]
	v_mfma_f32_16x16x32_bf16 v[104:107], v[174:177], v[200:203], v[104:107]
	v_mfma_f32_16x16x32_bf16 v[96:99], v[184:187], v[200:203], v[96:99]
	v_mfma_f32_16x16x32_bf16 v[88:91], v[174:177], v[208:211], v[88:91]
	v_mfma_f32_16x16x32_bf16 v[80:83], v[184:187], v[208:211], v[80:83]
	v_mfma_f32_16x16x32_bf16 v[72:75], v[174:177], v[216:219], v[72:75]
	v_mfma_f32_16x16x32_bf16 v[64:67], v[184:187], v[216:219], v[64:67]
	s_setprio 0
	s_barrier
; #define PG8_STAGE(bufoff, gbase, voff) do { _Pragma("unroll") for (int _i = 0; _i < 2; ++_i) \
;         __builtin_amdgcn_global_load_lds((const unsigned*)((const char*)(gbase) + (voff)[_i]), (PG8_LAS unsigned*)(lds + (bufoff) + ldsw + _i * 8192), 16, 0, 0); } while (0)
; #define PG8_LDA(dst, b, h) do { _Pragma("unroll") for (int m = 0; m < 4; ++m) _Pragma("unroll") for (int k = 0; k < 2; ++k) dst[m][k] = *(const PG8_LAS bf16x8*)(lds + PG8_SA(b, h) + aoff + m * 2048 + k * 1024); } while (0)
; #define PG8_MMA(ai, bj, At, Bt) do { __builtin_amdgcn_s_setprio(1); _Pragma("unroll") for (int m = 0; m < 4; ++m) _Pragma("unroll") for (int n = 0; n < 2; ++n) _Pragma("unroll") for (int k = 0; k < 2; ++k) \
;         acc[ai][bj][m][n] = __builtin_amdgcn_mfma_f32_16x16x32_bf16(Bt[n][k], At[m][k], acc[ai][bj][m][n], 0, 0, 0); __builtin_amdgcn_s_setprio(0); } while (0)
; #define PG8_WAIT_V(n) asm volatile("s_waitcnt vmcnt(" #n ")" ::: "memory")
; #define PG8_WAIT_L(n) asm volatile("s_waitcnt lgkmcnt(" #n ")" ::: "memory")
; #define PG8_BAR __builtin_amdgcn_s_barrier()
; #define PG8_SCHED __builtin_amdgcn_sched_barrier(0)
; template <class Epi, class Sched, bool ALIGN_EPI = false, bool SP2 = false>
; __device__ __forceinline__ void gemm_phase(PG8_LAS unsigned char* lds, const Gemm g, const Sched& S, const Epi& E) {
;     ...
;             PG8_LDA(At, 1, 1); PG8_STAGE(PG8_SB(1, 0), b3, voffB); PG8_STAGE(PG8_SB(1, 1), b3 + hstep, voffB); PG8_STAGE(PG8_SA(1, 0), a3, voffA);
;             PG8_WAIT_V(8); PG8_WAIT_L(0); PG8_BAR; PG8_MMA(1, 0, At, B0); PG8_MMA(1, 1, At, B1); PG8_BAR; PG8_SCHED;
;     ...
;         if constexpr (ALIGN_EPI) { if (wr == 0) PG8_BAR; }
	s_add_i32 s26, s53, s28
	v_lshl_add_u64 v[148:149], v[148:149], 0, s[8:9]
	s_mov_b32 m0, s26
	ds_read_b128 v[188:191], v156 offset:49152
	ds_read_b128 v[192:195], v156 offset:50176
	ds_read_b128 v[196:199], v156 offset:51200
	ds_read_b128 v[200:203], v156 offset:52224
	ds_read_b128 v[204:207], v156 offset:53248
	ds_read_b128 v[208:211], v156 offset:54272
	ds_read_b128 v[212:215], v156 offset:55296
	ds_read_b128 v[216:219], v156 offset:56320
	global_load_lds_dwordx4 v[148:149], off
	s_add_i32 m0, s26, 0x2000
	s_add_u32 s24, s24, 0x40080
	v_lshl_add_u64 v[148:149], v[220:221], 0, s[8:9]
	s_addc_u32 s25, s25, 0
	s_add_i32 s26, s54, s28
	global_load_lds_dwordx4 v[148:149], off
	s_mov_b32 m0, s26
	s_nop 0
	global_load_lds_dwordx4 v132, s[24:25]
	s_add_i32 m0, s26, 0x2000
	s_nop 0
	global_load_lds_dwordx4 v128, s[24:25]
	v_lshl_add_u64 v[148:149], v[222:223], 0, s[8:9]
	s_mov_b32 m0, s35
	s_nop 0
	global_load_lds_dwordx4 v[148:149], off
	v_lshl_add_u64 v[148:149], v[224:225], 0, s[8:9]
	s_mov_b32 m0, s36
	s_nop 0
	global_load_lds_dwordx4 v[148:149], off
	s_waitcnt vmcnt(8)
	s_waitcnt lgkmcnt(0)
	s_barrier
	s_setprio 1
	s_waitcnt lgkmcnt(0)
	v_mfma_f32_16x16x32_bf16 v[60:63], v[144:147], v[188:191], v[60:63]
	v_mfma_f32_16x16x32_bf16 v[52:55], v[162:165], v[188:191], v[52:55]
	v_mfma_f32_16x16x32_bf16 v[44:47], v[144:147], v[196:199], v[44:47]
	v_mfma_f32_16x16x32_bf16 v[36:39], v[162:165], v[196:199], v[36:39]
	v_mfma_f32_16x16x32_bf16 v[28:31], v[144:147], v[204:207], v[28:31]
	v_mfma_f32_16x16x32_bf16 v[20:23], v[162:165], v[204:207], v[20:23]
	v_mfma_f32_16x16x32_bf16 v[12:15], v[144:147], v[212:215], v[12:15]
	v_mfma_f32_16x16x32_bf16 v[4:7], v[162:165], v[212:215], v[4:7]
	v_mfma_f32_16x16x32_bf16 v[60:63], v[158:161], v[192:195], v[60:63]
	v_mfma_f32_16x16x32_bf16 v[52:55], v[166:169], v[192:195], v[52:55]
	v_mfma_f32_16x16x32_bf16 v[44:47], v[158:161], v[200:203], v[44:47]
	v_mfma_f32_16x16x32_bf16 v[36:39], v[166:169], v[200:203], v[36:39]
	v_mfma_f32_16x16x32_bf16 v[28:31], v[158:161], v[208:211], v[28:31]
	v_mfma_f32_16x16x32_bf16 v[20:23], v[166:169], v[208:211], v[20:23]
	v_mfma_f32_16x16x32_bf16 v[12:15], v[158:161], v[216:219], v[12:15]
	v_mfma_f32_16x16x32_bf16 v[4:7], v[166:169], v[216:219], v[4:7]
	s_setprio 0
	s_setprio 1
	v_mfma_f32_16x16x32_bf16 v[56:59], v[170:173], v[188:191], v[56:59]
	v_mfma_f32_16x16x32_bf16 v[48:51], v[180:183], v[188:191], v[48:51]
	v_mfma_f32_16x16x32_bf16 v[40:43], v[170:173], v[196:199], v[40:43]
	v_mfma_f32_16x16x32_bf16 v[32:35], v[180:183], v[196:199], v[32:35]
	v_mfma_f32_16x16x32_bf16 v[24:27], v[170:173], v[204:207], v[24:27]
	v_mfma_f32_16x16x32_bf16 v[16:19], v[180:183], v[204:207], v[16:19]
	v_mfma_f32_16x16x32_bf16 v[8:11], v[170:173], v[212:215], v[8:11]
	v_mfma_f32_16x16x32_bf16 v[0:3], v[180:183], v[212:215], v[0:3]
	v_mfma_f32_16x16x32_bf16 v[56:59], v[174:177], v[192:195], v[56:59]
	v_mfma_f32_16x16x32_bf16 v[48:51], v[184:187], v[192:195], v[48:51]
	v_mfma_f32_16x16x32_bf16 v[40:43], v[174:177], v[200:203], v[40:43]
	v_mfma_f32_16x16x32_bf16 v[32:35], v[184:187], v[200:203], v[32:35]
	v_mfma_f32_16x16x32_bf16 v[24:27], v[174:177], v[208:211], v[24:27]
	v_mfma_f32_16x16x32_bf16 v[16:19], v[184:187], v[208:211], v[16:19]
	v_mfma_f32_16x16x32_bf16 v[8:11], v[174:177], v[216:219], v[8:11]
	v_mfma_f32_16x16x32_bf16 v[0:3], v[184:187], v[216:219], v[0:3]
	s_setprio 0
	s_barrier
	s_add_i32 s52, s52, 2
	s_add_u32 s22, s22, 0x100
	s_addc_u32 s23, s23, 0
	s_add_u32 s50, s50, 0x100
	s_addc_u32 s51, s51, 0
	s_cmp_gt_u32 s52, 13
	s_cbranch_scc0 .LBB0_1361
	s_and_b64 vcc, exec, s[10:11]
	s_cbranch_vccz .LBB0_1364
	s_barrier

; #define PG8_STAGE(bufoff, gbase, voff) do { _Pragma("unroll") for (int _i = 0; _i < 2; ++_i) \
;         __builtin_amdgcn_global_load_lds((const unsigned*)((const char*)(gbase) + (voff)[_i]), (PG8_LAS unsigned*)(lds + (bufoff) + ldsw + _i * 8192), 16, 0, 0); } while (0)
; #define PG8_LDA(dst, b, h) do { _Pragma("unroll") for (int m = 0; m < 4; ++m) _Pragma("unroll") for (int k = 0; k < 2; ++k) dst[m][k] = *(const PG8_LAS bf16x8*)(lds + PG8_SA(b, h) + aoff + m * 2048 + k * 1024); } while (0)
; #define PG8_LDB(dst, b, h) do { _Pragma("unroll") for (int n = 0; n < 2; ++n) _Pragma("unroll") for (int k = 0; k < 2; ++k) dst[n][k] = *(const PG8_LAS bf16x8*)(lds + PG8_SB(b, h) + boff + n * 2048 + k * 1024); } while (0)
; #define PG8_MMA(ai, bj, At, Bt) do { __builtin_amdgcn_s_setprio(1); _Pragma("unroll") for (int m = 0; m < 4; ++m) _Pragma("unroll") for (int n = 0; n < 2; ++n) _Pragma("unroll") for (int k = 0; k < 2; ++k) \
;         acc[ai][bj][m][n] = __builtin_amdgcn_mfma_f32_16x16x32_bf16(Bt[n][k], At[m][k], acc[ai][bj][m][n], 0, 0, 0); __builtin_amdgcn_s_setprio(0); } while (0)
; #define PG8_WAIT_V(n) asm volatile("s_waitcnt vmcnt(" #n ")" ::: "memory")
; #define PG8_WAIT_L(n) asm volatile("s_waitcnt lgkmcnt(" #n ")" ::: "memory")
; #define PG8_BAR __builtin_amdgcn_s_barrier()
; #define PG8_SCHED __builtin_amdgcn_sched_barrier(0)
; template <class Epi, class Sched, bool ALIGN_EPI = false, bool SP2 = false>
; __device__ __forceinline__ void gemm_phase(PG8_LAS unsigned char* lds, const Gemm g, const Sched& S, const Epi& E) {
;     ...
;             PG8_LDB(B0, 0, 0); PG8_LDB(B1, 0, 1); PG8_SCHED; PG8_LDA(At, 0, 0); PG8_STAGE(PG8_SA(1, 1), a1 + hstep, voffA);
;             PG8_WAIT_V(8); PG8_WAIT_L(0); PG8_BAR; PG8_MMA(0, 0, At, B0); PG8_MMA(0, 1, At, B1); PG8_BAR; PG8_SCHED;
;             PG8_LDA(At, 0, 1); PG8_STAGE(PG8_SB(0, 0), b2, voffB); PG8_STAGE(PG8_SB(0, 1), b2 + hstep, voffB); PG8_STAGE(PG8_SA(0, 0), a2, voffA);
;             PG8_WAIT_V(8); PG8_WAIT_L(0); PG8_BAR; PG8_MMA(1, 0, At, B0); PG8_MMA(1, 1, At, B1); PG8_BAR; PG8_SCHED;
.LBB0_1450:
	v_add_u32_e32 v156, s51, v173
	v_add_u32_e32 v176, s52, v173
	ds_read_b128 v[144:147], v156
	ds_read_b128 v[148:151], v156 offset:1024
	ds_read_b128 v[152:155], v156 offset:2048
	ds_read_b128 v[156:159], v156 offset:3072
	ds_read_b128 v[160:163], v176
	ds_read_b128 v[164:167], v176 offset:1024
	ds_read_b128 v[168:171], v176 offset:2048
	ds_read_b128 v[176:179], v176 offset:3072
	s_add_u32 s30, s34, 0xfff50080
	s_addc_u32 s31, s35, -1
	s_cmp_eq_u32 s63, 40
	s_cselect_b32 s37, s5, s31
	s_cselect_b32 s36, s4, s30
	s_cselect_b32 s31, s71, s62
	s_cselect_b32 s30, s70, s61
	s_add_i32 m0, s43, 0xc000
	ds_read_b128 v[180:183], v175
	ds_read_b128 v[184:187], v175 offset:1024
	ds_read_b128 v[188:191], v175 offset:2048
	ds_read_b128 v[192:195], v175 offset:3072
	ds_read_b128 v[196:199], v175 offset:4096
	ds_read_b128 v[200:203], v175 offset:5120
	ds_read_b128 v[204:207], v175 offset:6144
	ds_read_b128 v[208:211], v175 offset:7168
	global_load_lds_dwordx4 v136, s[34:35]
	s_add_i32 m0, s43, 0xe000
	s_nop 0
	global_load_lds_dwordx4 v138, s[34:35]
	s_waitcnt vmcnt(8)
	s_waitcnt lgkmcnt(0)
	s_barrier
	s_setprio 1
	s_waitcnt lgkmcnt(0)
	v_mfma_f32_16x16x32_bf16 v[68:71], v[144:147], v[180:183], v[68:71]
	v_mfma_f32_16x16x32_bf16 v[80:83], v[152:155], v[180:183], v[80:83]
	v_mfma_f32_16x16x32_bf16 v[32:35], v[144:147], v[188:191], v[32:35]
	v_mfma_f32_16x16x32_bf16 v[36:39], v[152:155], v[188:191], v[36:39]
	v_mfma_f32_16x16x32_bf16 v[16:19], v[144:147], v[196:199], v[16:19]
	v_mfma_f32_16x16x32_bf16 v[20:23], v[152:155], v[196:199], v[20:23]
	v_mfma_f32_16x16x32_bf16 v[0:3], v[144:147], v[204:207], v[0:3]
	v_mfma_f32_16x16x32_bf16 v[4:7], v[152:155], v[204:207], v[4:7]
	v_mfma_f32_16x16x32_bf16 v[68:71], v[148:151], v[184:187], v[68:71]
	v_mfma_f32_16x16x32_bf16 v[80:83], v[156:159], v[184:187], v[80:83]
	v_mfma_f32_16x16x32_bf16 v[32:35], v[148:151], v[192:195], v[32:35]
	v_mfma_f32_16x16x32_bf16 v[36:39], v[156:159], v[192:195], v[36:39]
	v_mfma_f32_16x16x32_bf16 v[16:19], v[148:151], v[200:203], v[16:19]
	v_mfma_f32_16x16x32_bf16 v[20:23], v[156:159], v[200:203], v[20:23]
	v_mfma_f32_16x16x32_bf16 v[0:3], v[148:151], v[208:211], v[0:3]
	v_mfma_f32_16x16x32_bf16 v[4:7], v[156:159], v[208:211], v[4:7]
	s_setprio 0
	s_setprio 1
	v_mfma_f32_16x16x32_bf16 v[112:115], v[160:163], v[180:183], v[112:115]
	v_mfma_f32_16x16x32_bf16 v[120:123], v[168:171], v[180:183], v[120:123]
	v_mfma_f32_16x16x32_bf16 v[96:99], v[160:163], v[188:191], v[96:99]
	v_mfma_f32_16x16x32_bf16 v[104:107], v[168:171], v[188:191], v[104:107]
	v_mfma_f32_16x16x32_bf16 v[76:79], v[160:163], v[196:199], v[76:79]
	v_mfma_f32_16x16x32_bf16 v[84:87], v[168:171], v[196:199], v[84:87]
	v_mfma_f32_16x16x32_bf16 v[48:51], v[160:163], v[204:207], v[48:51]
	v_mfma_f32_16x16x32_bf16 v[56:59], v[168:171], v[204:207], v[56:59]
	v_mfma_f32_16x16x32_bf16 v[112:115], v[164:167], v[184:187], v[112:115]
	v_mfma_f32_16x16x32_bf16 v[120:123], v[176:179], v[184:187], v[120:123]
	v_mfma_f32_16x16x32_bf16 v[96:99], v[164:167], v[192:195], v[96:99]
	v_mfma_f32_16x16x32_bf16 v[104:107], v[176:179], v[192:195], v[104:107]
	v_mfma_f32_16x16x32_bf16 v[76:79], v[164:167], v[200:203], v[76:79]
	v_mfma_f32_16x16x32_bf16 v[84:87], v[176:179], v[200:203], v[84:87]
	v_mfma_f32_16x16x32_bf16 v[48:51], v[164:167], v[208:211], v[48:51]
	v_mfma_f32_16x16x32_bf16 v[56:59], v[176:179], v[208:211], v[56:59]
	s_setprio 0
	s_barrier
	s_add_i32 s64, s51, s38
	v_lshl_add_u64 v[212:213], s[30:31], 0, v[130:131]
	s_mov_b32 m0, s64
	ds_read_b128 v[180:183], v175 offset:16384
	ds_read_b128 v[184:187], v175 offset:17408
	ds_read_b128 v[188:191], v175 offset:18432
	ds_read_b128 v[192:195], v175 offset:19456
	ds_read_b128 v[196:199], v175 offset:20480
	ds_read_b128 v[200:203], v175 offset:21504
	ds_read_b128 v[204:207], v175 offset:22528
	ds_read_b128 v[208:211], v175 offset:23552
	global_load_lds_dwordx4 v[212:213], off
	s_add_i32 m0, s64, 0x2000
	s_add_u32 s64, s30, 0xb0000
	v_lshl_add_u64 v[214:215], s[30:31], 0, v[134:135]
	s_addc_u32 s65, s31, 0
	s_add_i32 s66, s52, s38
	global_load_lds_dwordx4 v[214:215], off
	s_mov_b32 m0, s66
	v_lshl_add_u64 v[218:219], s[36:37], 0, v[132:133]
	global_load_lds_dwordx4 v130, s[64:65]
	s_add_i32 m0, s66, 0x2000
	s_nop 0
	global_load_lds_dwordx4 v134, s[64:65]
	v_lshl_add_u64 v[216:217], s[36:37], 0, v[128:129]
	s_mov_b32 m0, s43
	s_nop 0
	global_load_lds_dwordx4 v[216:217], off
	s_mov_b32 m0, s44
	s_nop 0
	global_load_lds_dwordx4 v[218:219], off
	s_waitcnt vmcnt(8)
	s_waitcnt lgkmcnt(0)
	s_barrier
; #define PG8_STAGE(bufoff, gbase, voff) do { _Pragma("unroll") for (int _i = 0; _i < 2; ++_i) \
;         __builtin_amdgcn_global_load_lds((const unsigned*)((const char*)(gbase) + (voff)[_i]), (PG8_LAS unsigned*)(lds + (bufoff) + ldsw + _i * 8192), 16, 0, 0); } while (0)
; #define PG8_LDA(dst, b, h) do { _Pragma("unroll") for (int m = 0; m < 4; ++m) _Pragma("unroll") for (int k = 0; k < 2; ++k) dst[m][k] = *(const PG8_LAS bf16x8*)(lds + PG8_SA(b, h) + aoff + m * 2048 + k * 1024); } while (0)
; #define PG8_LDB(dst, b, h) do { _Pragma("unroll") for (int n = 0; n < 2; ++n) _Pragma("unroll") for (int k = 0; k < 2; ++k) dst[n][k] = *(const PG8_LAS bf16x8*)(lds + PG8_SB(b, h) + boff + n * 2048 + k * 1024); } while (0)
; #define PG8_MMA(ai, bj, At, Bt) do { __builtin_amdgcn_s_setprio(1); _Pragma("unroll") for (int m = 0; m < 4; ++m) _Pragma("unroll") for (int n = 0; n < 2; ++n) _Pragma("unroll") for (int k = 0; k < 2; ++k) \
;         acc[ai][bj][m][n] = __builtin_amdgcn_mfma_f32_16x16x32_bf16(Bt[n][k], At[m][k], acc[ai][bj][m][n], 0, 0, 0); __builtin_amdgcn_s_setprio(0); } while (0)
; #define PG8_WAIT_V(n) asm volatile("s_waitcnt vmcnt(" #n ")" ::: "memory")
; #define PG8_WAIT_L(n) asm volatile("s_waitcnt lgkmcnt(" #n ")" ::: "memory")
; #define PG8_BAR __builtin_amdgcn_s_barrier()
; #define PG8_SCHED __builtin_amdgcn_sched_barrier(0)
; template <class Epi, class Sched, bool ALIGN_EPI = false, bool SP2 = false>
; __device__ __forceinline__ void gemm_phase(PG8_LAS unsigned char* lds, const Gemm g, const Sched& S, const Epi& E) {
;     ...
;             PG8_WAIT_V(8); PG8_WAIT_L(0); PG8_BAR; PG8_MMA(1, 0, At, B0); PG8_MMA(1, 1, At, B1); PG8_BAR; PG8_SCHED;
;             PG8_LDB(B0, 1, 0); PG8_LDB(B1, 1, 1); PG8_SCHED; PG8_LDA(At, 1, 0); PG8_STAGE(PG8_SA(0, 1), a2 + hstep, voffA);
;             PG8_WAIT_V(8); PG8_WAIT_L(0); PG8_BAR; PG8_MMA(0, 0, At, B0); PG8_MMA(0, 1, At, B1); PG8_BAR; PG8_SCHED;
	s_setprio 1
	s_waitcnt lgkmcnt(0)
	v_mfma_f32_16x16x32_bf16 v[52:55], v[144:147], v[180:183], v[52:55]
	v_mfma_f32_16x16x32_bf16 v[60:63], v[152:155], v[180:183], v[60:63]
	v_mfma_f32_16x16x32_bf16 v[40:43], v[144:147], v[188:191], v[40:43]
	v_mfma_f32_16x16x32_bf16 v[44:47], v[152:155], v[188:191], v[44:47]
	v_mfma_f32_16x16x32_bf16 v[24:27], v[144:147], v[196:199], v[24:27]
	v_mfma_f32_16x16x32_bf16 v[28:31], v[152:155], v[196:199], v[28:31]
	v_mfma_f32_16x16x32_bf16 v[8:11], v[144:147], v[204:207], v[8:11]
	v_mfma_f32_16x16x32_bf16 v[12:15], v[152:155], v[204:207], v[12:15]
	v_mfma_f32_16x16x32_bf16 v[52:55], v[148:151], v[184:187], v[52:55]
	v_mfma_f32_16x16x32_bf16 v[60:63], v[156:159], v[184:187], v[60:63]
	v_mfma_f32_16x16x32_bf16 v[40:43], v[148:151], v[192:195], v[40:43]
	v_mfma_f32_16x16x32_bf16 v[44:47], v[156:159], v[192:195], v[44:47]
	v_mfma_f32_16x16x32_bf16 v[24:27], v[148:151], v[200:203], v[24:27]
	v_mfma_f32_16x16x32_bf16 v[28:31], v[156:159], v[200:203], v[28:31]
	v_mfma_f32_16x16x32_bf16 v[8:11], v[148:151], v[208:211], v[8:11]
	v_mfma_f32_16x16x32_bf16 v[12:15], v[156:159], v[208:211], v[12:15]
	s_setprio 0
	s_setprio 1
	v_mfma_f32_16x16x32_bf16 v[116:119], v[160:163], v[180:183], v[116:119]
	v_mfma_f32_16x16x32_bf16 v[124:127], v[168:171], v[180:183], v[124:127]
	v_mfma_f32_16x16x32_bf16 v[100:103], v[160:163], v[188:191], v[100:103]
	v_mfma_f32_16x16x32_bf16 v[108:111], v[168:171], v[188:191], v[108:111]
	v_mfma_f32_16x16x32_bf16 v[88:91], v[160:163], v[196:199], v[88:91]
	v_mfma_f32_16x16x32_bf16 v[92:95], v[168:171], v[196:199], v[92:95]
	v_mfma_f32_16x16x32_bf16 v[64:67], v[160:163], v[204:207], v[64:67]
	v_mfma_f32_16x16x32_bf16 v[72:75], v[168:171], v[204:207], v[72:75]
	v_mfma_f32_16x16x32_bf16 v[116:119], v[164:167], v[184:187], v[116:119]
	v_mfma_f32_16x16x32_bf16 v[124:127], v[176:179], v[184:187], v[124:127]
	v_mfma_f32_16x16x32_bf16 v[100:103], v[164:167], v[192:195], v[100:103]
	v_mfma_f32_16x16x32_bf16 v[108:111], v[176:179], v[192:195], v[108:111]
	v_mfma_f32_16x16x32_bf16 v[88:91], v[164:167], v[200:203], v[88:91]
	v_mfma_f32_16x16x32_bf16 v[92:95], v[176:179], v[200:203], v[92:95]
	v_mfma_f32_16x16x32_bf16 v[64:67], v[164:167], v[208:211], v[64:67]
	v_mfma_f32_16x16x32_bf16 v[72:75], v[176:179], v[208:211], v[72:75]
	s_setprio 0
	s_barrier
	s_add_i32 s64, 0, 0x18000
	s_add_i32 s65, 0, 0x1c000
	v_add_u32_e32 v156, s64, v173
	v_add_u32_e32 v176, s65, v173
	ds_read_b128 v[144:147], v156
	ds_read_b128 v[148:151], v156 offset:1024
	ds_read_b128 v[152:155], v156 offset:2048
	ds_read_b128 v[156:159], v156 offset:3072
	ds_read_b128 v[160:163], v176
	ds_read_b128 v[164:167], v176 offset:1024
	ds_read_b128 v[168:171], v176 offset:2048
	ds_read_b128 v[176:179], v176 offset:3072
	s_add_u32 s36, s36, 0xb0000
	s_addc_u32 s37, s37, 0
	s_mov_b32 m0, s45
	ds_read_b128 v[180:183], v175 offset:32768
	ds_read_b128 v[184:187], v175 offset:33792
	ds_read_b128 v[188:191], v175 offset:34816
	ds_read_b128 v[192:195], v175 offset:35840
	ds_read_b128 v[196:199], v175 offset:36864
	ds_read_b128 v[200:203], v175 offset:37888
	ds_read_b128 v[204:207], v175 offset:38912
	ds_read_b128 v[208:211], v175 offset:39936
	global_load_lds_dwordx4 v128, s[36:37]
	v_lshl_add_u64 v[220:221], s[36:37], 0, v[132:133]
	s_mov_b32 m0, s46
	s_nop 0
	global_load_lds_dwordx4 v[220:221], off
	s_waitcnt vmcnt(8)
	s_waitcnt lgkmcnt(0)
	s_barrier
	s_setprio 1
	s_waitcnt lgkmcnt(0)
	v_mfma_f32_16x16x32_bf16 v[68:71], v[144:147], v[180:183], v[68:71]
	v_mfma_f32_16x16x32_bf16 v[80:83], v[152:155], v[180:183], v[80:83]
	v_mfma_f32_16x16x32_bf16 v[32:35], v[144:147], v[188:191], v[32:35]
	v_mfma_f32_16x16x32_bf16 v[36:39], v[152:155], v[188:191], v[36:39]
	v_mfma_f32_16x16x32_bf16 v[16:19], v[144:147], v[196:199], v[16:19]
	v_mfma_f32_16x16x32_bf16 v[20:23], v[152:155], v[196:199], v[20:23]
	v_mfma_f32_16x16x32_bf16 v[0:3], v[144:147], v[204:207], v[0:3]
	v_mfma_f32_16x16x32_bf16 v[4:7], v[152:155], v[204:207], v[4:7]
	v_mfma_f32_16x16x32_bf16 v[68:71], v[148:151], v[184:187], v[68:71]
	v_mfma_f32_16x16x32_bf16 v[80:83], v[156:159], v[184:187], v[80:83]
	v_mfma_f32_16x16x32_bf16 v[32:35], v[148:151], v[192:195], v[32:35]
	v_mfma_f32_16x16x32_bf16 v[36:39], v[156:159], v[192:195], v[36:39]
	v_mfma_f32_16x16x32_bf16 v[16:19], v[148:151], v[200:203], v[16:19]
	v_mfma_f32_16x16x32_bf16 v[20:23], v[156:159], v[200:203], v[20:23]
	v_mfma_f32_16x16x32_bf16 v[0:3], v[148:151], v[208:211], v[0:3]
	v_mfma_f32_16x16x32_bf16 v[4:7], v[156:159], v[208:211], v[4:7]
	s_setprio 0
	s_setprio 1
	v_mfma_f32_16x16x32_bf16 v[112:115], v[160:163], v[180:183], v[112:115]
	v_mfma_f32_16x16x32_bf16 v[120:123], v[168:171], v[180:183], v[120:123]
	v_mfma_f32_16x16x32_bf16 v[96:99], v[160:163], v[188:191], v[96:99]
	v_mfma_f32_16x16x32_bf16 v[104:107], v[168:171], v[188:191], v[104:107]
	v_mfma_f32_16x16x32_bf16 v[76:79], v[160:163], v[196:199], v[76:79]
	v_mfma_f32_16x16x32_bf16 v[84:87], v[168:171], v[196:199], v[84:87]
	v_mfma_f32_16x16x32_bf16 v[48:51], v[160:163], v[204:207], v[48:51]
	v_mfma_f32_16x16x32_bf16 v[56:59], v[168:171], v[204:207], v[56:59]
	v_mfma_f32_16x16x32_bf16 v[112:115], v[164:167], v[184:187], v[112:115]
	v_mfma_f32_16x16x32_bf16 v[120:123], v[176:179], v[184:187], v[120:123]
	v_mfma_f32_16x16x32_bf16 v[96:99], v[164:167], v[192:195], v[96:99]
	v_mfma_f32_16x16x32_bf16 v[104:107], v[176:179], v[192:195], v[104:107]
	v_mfma_f32_16x16x32_bf16 v[76:79], v[164:167], v[200:203], v[76:79]
	v_mfma_f32_16x16x32_bf16 v[84:87], v[176:179], v[200:203], v[84:87]
	v_mfma_f32_16x16x32_bf16 v[48:51], v[164:167], v[208:211], v[48:51]
	v_mfma_f32_16x16x32_bf16 v[56:59], v[176:179], v[208:211], v[56:59]
	s_setprio 0
	s_barrier
; #define PG8_STAGE(bufoff, gbase, voff) do { _Pragma("unroll") for (int _i = 0; _i < 2; ++_i) \
;         __builtin_amdgcn_global_load_lds((const unsigned*)((const char*)(gbase) + (voff)[_i]), (PG8_LAS unsigned*)(lds + (bufoff) + ldsw + _i * 8192), 16, 0, 0); } while (0)
; #define PG8_LDA(dst, b, h) do { _Pragma("unroll") for (int m = 0; m < 4; ++m) _Pragma("unroll") for (int k = 0; k < 2; ++k) dst[m][k] = *(const PG8_LAS bf16x8*)(lds + PG8_SA(b, h) + aoff + m * 2048 + k * 1024); } while (0)
; #define PG8_MMA(ai, bj, At, Bt) do { __builtin_amdgcn_s_setprio(1); _Pragma("unroll") for (int m = 0; m < 4; ++m) _Pragma("unroll") for (int n = 0; n < 2; ++n) _Pragma("unroll") for (int k = 0; k < 2; ++k) \
;         acc[ai][bj][m][n] = __builtin_amdgcn_mfma_f32_16x16x32_bf16(Bt[n][k], At[m][k], acc[ai][bj][m][n], 0, 0, 0); __builtin_amdgcn_s_setprio(0); } while (0)
; #define PG8_WAIT_V(n) asm volatile("s_waitcnt vmcnt(" #n ")" ::: "memory")
; #define PG8_WAIT_L(n) asm volatile("s_waitcnt lgkmcnt(" #n ")" ::: "memory")
; #define PG8_BAR __builtin_amdgcn_s_barrier()
; #define PG8_SCHED __builtin_amdgcn_sched_barrier(0)
; template <class Epi, class Sched, bool ALIGN_EPI = false, bool SP2 = false>
; __device__ __forceinline__ void gemm_phase(PG8_LAS unsigned char* lds, const Gemm g, const Sched& S, const Epi& E) {
;     ...
;             PG8_LDA(At, 1, 1); PG8_STAGE(PG8_SB(1, 0), b3, voffB); PG8_STAGE(PG8_SB(1, 1), b3 + hstep, voffB); PG8_STAGE(PG8_SA(1, 0), a3, voffA);
;             PG8_WAIT_V(8); PG8_WAIT_L(0); PG8_BAR; PG8_MMA(1, 0, At, B0); PG8_MMA(1, 1, At, B1); PG8_BAR; PG8_SCHED;
	s_add_i32 s36, s64, s38
	v_lshl_add_u64 v[212:213], v[212:213], 0, s[74:75]
	s_mov_b32 m0, s36
	ds_read_b128 v[180:183], v175 offset:49152
	ds_read_b128 v[184:187], v175 offset:50176
	ds_read_b128 v[188:191], v175 offset:51200
	ds_read_b128 v[192:195], v175 offset:52224
	ds_read_b128 v[196:199], v175 offset:53248
	ds_read_b128 v[200:203], v175 offset:54272
	ds_read_b128 v[204:207], v175 offset:55296
	ds_read_b128 v[208:211], v175 offset:56320
	global_load_lds_dwordx4 v[212:213], off
	s_add_i32 m0, s36, 0x2000
	s_add_u32 s30, s30, 0xb0080
	v_lshl_add_u64 v[212:213], v[214:215], 0, s[74:75]
	s_addc_u32 s31, s31, 0
	s_add_i32 s36, s65, s38
	global_load_lds_dwordx4 v[212:213], off
	s_mov_b32 m0, s36
	s_nop 0
	global_load_lds_dwordx4 v130, s[30:31]
	s_add_i32 m0, s36, 0x2000
	s_nop 0
	global_load_lds_dwordx4 v134, s[30:31]
	v_lshl_add_u64 v[212:213], v[216:217], 0, s[74:75]
	s_mov_b32 m0, s48
	s_nop 0
	global_load_lds_dwordx4 v[212:213], off
	v_lshl_add_u64 v[212:213], v[218:219], 0, s[74:75]
	s_mov_b32 m0, s49
	s_nop 0
	global_load_lds_dwordx4 v[212:213], off
	s_waitcnt vmcnt(8)
	s_waitcnt lgkmcnt(0)
	s_barrier
	s_setprio 1
	s_waitcnt lgkmcnt(0)
	v_mfma_f32_16x16x32_bf16 v[52:55], v[144:147], v[180:183], v[52:55]
	v_mfma_f32_16x16x32_bf16 v[60:63], v[152:155], v[180:183], v[60:63]
	v_mfma_f32_16x16x32_bf16 v[40:43], v[144:147], v[188:191], v[40:43]
	v_mfma_f32_16x16x32_bf16 v[44:47], v[152:155], v[188:191], v[44:47]
	v_mfma_f32_16x16x32_bf16 v[24:27], v[144:147], v[196:199], v[24:27]
	v_mfma_f32_16x16x32_bf16 v[28:31], v[152:155], v[196:199], v[28:31]
	v_mfma_f32_16x16x32_bf16 v[8:11], v[144:147], v[204:207], v[8:11]
	v_mfma_f32_16x16x32_bf16 v[12:15], v[152:155], v[204:207], v[12:15]
	v_mfma_f32_16x16x32_bf16 v[52:55], v[148:151], v[184:187], v[52:55]
	v_mfma_f32_16x16x32_bf16 v[60:63], v[156:159], v[184:187], v[60:63]
	v_mfma_f32_16x16x32_bf16 v[40:43], v[148:151], v[192:195], v[40:43]
	v_mfma_f32_16x16x32_bf16 v[44:47], v[156:159], v[192:195], v[44:47]
	v_mfma_f32_16x16x32_bf16 v[24:27], v[148:151], v[200:203], v[24:27]
	v_mfma_f32_16x16x32_bf16 v[28:31], v[156:159], v[200:203], v[28:31]
	v_mfma_f32_16x16x32_bf16 v[8:11], v[148:151], v[208:211], v[8:11]
	v_mfma_f32_16x16x32_bf16 v[12:15], v[156:159], v[208:211], v[12:15]
	s_setprio 0
	s_setprio 1
	v_mfma_f32_16x16x32_bf16 v[116:119], v[160:163], v[180:183], v[116:119]
	v_mfma_f32_16x16x32_bf16 v[124:127], v[168:171], v[180:183], v[124:127]
	v_mfma_f32_16x16x32_bf16 v[100:103], v[160:163], v[188:191], v[100:103]
	v_mfma_f32_16x16x32_bf16 v[108:111], v[168:171], v[188:191], v[108:111]
	v_mfma_f32_16x16x32_bf16 v[88:91], v[160:163], v[196:199], v[88:91]
	v_mfma_f32_16x16x32_bf16 v[92:95], v[168:171], v[196:199], v[92:95]
	v_mfma_f32_16x16x32_bf16 v[64:67], v[160:163], v[204:207], v[64:67]
	v_mfma_f32_16x16x32_bf16 v[72:75], v[168:171], v[204:207], v[72:75]
	v_mfma_f32_16x16x32_bf16 v[116:119], v[164:167], v[184:187], v[116:119]
	v_mfma_f32_16x16x32_bf16 v[124:127], v[176:179], v[184:187], v[124:127]
	v_mfma_f32_16x16x32_bf16 v[100:103], v[164:167], v[192:195], v[100:103]
	v_mfma_f32_16x16x32_bf16 v[108:111], v[176:179], v[192:195], v[108:111]
	v_mfma_f32_16x16x32_bf16 v[88:91], v[164:167], v[200:203], v[88:91]
	v_mfma_f32_16x16x32_bf16 v[92:95], v[176:179], v[200:203], v[92:95]
	v_mfma_f32_16x16x32_bf16 v[64:67], v[164:167], v[208:211], v[64:67]
	v_mfma_f32_16x16x32_bf16 v[72:75], v[176:179], v[208:211], v[72:75]
	s_setprio 0
	s_barrier
	s_add_i32 s63, s63, 2
	s_add_u32 s34, s34, 0x100
	s_addc_u32 s35, s35, 0
	s_add_u32 s61, s61, 0x100
	s_addc_u32 s62, s62, 0
	s_cmp_gt_u32 s63, 41
	s_cbranch_scc0 .LBB0_1450
	s_and_b64 vcc, exec, s[76:77]
	s_cbranch_vccz .LBB0_1453
	s_barrier
